# kernarg ws-pointer reloads via s_load instead of VMEM + drop their vmcnt(0) drains (23 sites: grid barrier entry, hgrn/xattn/scan unit starts)
# speedup vs baseline: 1.0153x; 1.0049x over previous
.LBB0_156:
	s_or_b64 exec, exec, s[10:11]
	s_mov_b64 s[8:9], s[62:63]
	s_barrier
	s_getreg_b32 s5, hwreg(HW_REG_XCC_ID, 0, 4)
	s_waitcnt vmcnt(0)
	v_readlane_b32 s2, v253, 0
	v_readlane_b32 s3, v253, 1
	s_barrier
	s_and_saveexec_b64 s[6:7], s[2:3]
	v_readlane_b32 s2, v253, 3
	s_xor_b64 s[6:7], exec, s[6:7]
	v_readlane_b32 s3, v253, 4
	s_cbranch_execz .LBB0_210
	s_load_dwordx2 s[8:9], s[8:9], 0xc0
	v_readlane_b32 s0, v254, 38
	s_waitcnt expcnt(0) lgkmcnt(0)
	v_mov_b32_e32 v4, s8
	v_mov_b32_e32 v5, s9
	s_and_b32 s5, s5, 15
	v_mov_b32_e32 v0, s0
	ds_read_b32 v2, v0
	v_readlane_b32 s0, v254, 39
	s_waitcnt lgkmcnt(0)
	v_cmp_ne_u32_e32 vcc, 0, v2
	v_mov_b32_e32 v0, s0
	ds_read_b32 v0, v0
	v_readfirstlane_b32 s8, v4
	v_readfirstlane_b32 s9, v5
	s_cbranch_vccnz .LBB0_173
	s_add_u32 s10, s8, 0x2e4c2a00
	s_addc_u32 s11, s9, 0
	s_add_u32 s12, s8, 0x2e4c2c00
	s_addc_u32 s13, s9, 0
	s_add_u32 s14, s8, 0x2e4c2d00
	s_addc_u32 s15, s9, 0
	s_add_u32 s16, s8, 0x2e4c2e00
	s_addc_u32 s17, s9, 0
	s_add_u32 s18, s8, 0x2e4c2f00
	s_addc_u32 s19, s9, 0
	s_add_u32 s20, s8, 0x2e4c3000
	s_addc_u32 s21, s9, 0
	s_add_u32 s22, s8, 0x2e4c3100
	s_addc_u32 s23, s9, 0
	s_add_u32 s24, s8, 0x2e4c3200
	s_addc_u32 s25, s9, 0
	s_add_u32 s26, s8, 0x2e4c3300
	s_addc_u32 s27, s9, 0
	s_add_u32 s28, s8, 0x2e4c3400
	s_addc_u32 s29, s9, 0
	s_add_u32 s30, s8, 0x2e4c3500
	s_addc_u32 s31, s9, 0
	s_add_u32 s34, s8, 0x2e4c3600
	s_addc_u32 s35, s9, 0
	s_add_u32 s36, s8, 0x2e4c3700
	s_addc_u32 s37, s9, 0
	s_add_u32 s38, s8, 0x2e4c3800
	s_addc_u32 s39, s9, 0
	s_add_u32 s40, s8, 0x2e4c3900
	s_addc_u32 s41, s9, 0
	s_add_u32 s42, s8, 0x2e4c3a00
	s_addc_u32 s43, s9, 0
	s_add_u32 s44, s8, 0x2e4c3b00
	s_addc_u32 s45, s9, 0
	s_mov_b32 s52, 1
	s_branch .LBB0_161

.LBB0_210:
	s_or_b64 exec, exec, s[6:7]
	s_mov_b64 s[6:7], s[62:63]
	s_waitcnt lgkmcnt(0)
	s_barrier
	s_load_dwordx2 s[60:61], s[62:63], 0xc0
	s_waitcnt lgkmcnt(0)
	s_load_dwordx2 s[12:13], s[6:7], 0xc0
	s_mov_b64 s[6:7], 0x5300000
	s_bitcmp1_b32 s83, 0
	s_cselect_b32 s96, 0x1880000, 0
	v_readlane_b32 s10, v253, 5
	s_mov_b64 s[8:9], s[62:63]
	v_mov_b32_e32 v20, v208
	v_readlane_b32 s11, v253, 6
	s_and_b64 vcc, exec, s[10:11]
	s_waitcnt lgkmcnt(0)
	v_mov_b32_e32 v0, s12
	v_mov_b32_e32 v1, s13
	v_lshl_add_u64 v[0:1], v[0:1], 0, s[6:7]
	s_mov_b64 s[6:7], s[62:63]
	s_load_dwordx2 s[10:11], s[6:7], 0xc0
	v_readfirstlane_b32 s5, v1
	v_readfirstlane_b32 s24, v0
	s_movk_i32 s6, 0x400
	v_readfirstlane_b32 s25, v20
	s_waitcnt lgkmcnt(0)
	v_mov_b32_e32 v2, s10
	v_mov_b32_e32 v3, s11
	v_lshl_add_u64 v[2:3], v[2:3], 0, s[96:97]
	s_nop 0
	v_readfirstlane_b32 s26, v3
	v_readfirstlane_b32 s27, v2
	s_cbranch_vccz .LBB0_228
	v_lshlrev_b32_e32 v2, 4, v20
	v_add_u32_e32 v3, 0x2000, v2
	v_ashrrev_i32_e32 v4, 31, v3
	v_lshrrev_b32_e32 v4, 22, v4
	v_add_u32_e32 v4, v3, v4
	v_ashrrev_i32_e32 v4, 10, v4
	v_mul_i32_i24_e32 v5, 0x400, v4
	v_sub_u32_e32 v3, v3, v5
	v_lshrrev_b32_e32 v5, 4, v3
	v_bitop3_b32 v3, v5, v3, 32 bitop3:0x6c
	v_ashrrev_i32_e32 v5, 31, v3
	v_lshrrev_b32_e32 v5, 26, v5
	v_add_u32_e32 v5, v3, v5
	v_lshlrev_b32_e32 v7, 3, v4
	v_ashrrev_i32_e32 v6, 6, v5
	v_and_b32_e32 v7, -16, v7
	v_add_u32_e32 v7, v6, v7
	v_and_b32_e32 v6, 3, v6
	s_mov_b32 s0, 0x7fffffe0
	v_lshrrev_b32_e32 v8, 2, v7
	v_lshlrev_b32_e32 v9, 1, v7
	v_lshlrev_b32_e32 v4, 5, v4
	v_and_or_b32 v6, v7, s0, v6
	v_and_b32_e32 v8, 4, v8
	v_and_b32_e32 v9, 24, v9
	v_and_b32_e32 v14, 32, v4
	v_and_b32_e32 v4, 0xc0, v5
	v_or3_b32 v6, v6, v8, v9
	v_sub_u32_e32 v3, v3, v4
	v_mov_b32_e32 v9, 1
	v_ashrrev_i16_sdwa v3, v9, sext(v3) dst_sel:DWORD dst_unused:UNUSED_PAD src0_sel:DWORD src1_sel:BYTE_0
	v_bfe_i32 v15, v3, 0, 16
	v_mul_lo_u32 v6, v6, s6
	v_add_u32_e32 v3, v14, v15
	v_mul_lo_u32 v16, v7, s6
	v_add_lshl_u32 v132, v6, v3, 1
	v_add_lshl_u32 v134, v3, v16, 1
	v_bfe_i32 v3, v20, 27, 1
	v_lshrrev_b32_e32 v3, 22, v3
	v_add_u32_e32 v3, v2, v3
	v_and_b32_e32 v3, 0xfffffc00, v3
	v_sub_u32_e32 v2, v2, v3
	v_ashrrev_i32_e32 v4, 31, v20
	v_lshrrev_b32_e32 v3, 4, v2
	v_lshrrev_b32_e32 v4, 26, v4
	v_bitop3_b32 v3, v3, v2, 32 bitop3:0x6c
	v_ashrrev_i32_e32 v2, 31, v2
	v_add_u32_e32 v4, v20, v4
	v_lshrrev_b32_e32 v2, 26, v2
	v_ashrrev_i32_e32 v4, 6, v4
	v_add_u32_e32 v2, v3, v2
	v_lshlrev_b32_e32 v5, 3, v4
	v_ashrrev_i32_e32 v2, 6, v2
	v_and_b32_e32 v5, -16, v5
	s_ashr_i32 s7, s6, 31
	v_add_u32_e32 v5, v2, v5
	v_and_b32_e32 v6, 3, v2
	s_lshl_b64 s[14:15], s[6:7], 9
	v_and_or_b32 v6, v5, s0, v6
	v_readlane_b32 s0, v253, 42
	s_mul_i32 s10, s14, s0
	v_readlane_b32 s0, v253, 41
	v_readlane_b32 s20, v253, 43
	s_mul_hi_u32 s11, s14, s0
	v_readlane_b32 s21, v253, 44
	v_mul_i32_i24_e32 v2, 64, v2
	s_add_i32 s16, s11, s10
	s_lshr_b64 s[10:11], s[6:7], 23
	s_mul_i32 s17, s14, s21
	s_mul_hi_u32 s18, s14, s20
	global_load_dwordx2 v[0:1], v167, s[8:9] offset:192
	s_ashr_i32 s8, s25, 6
	v_lshrrev_b32_e32 v7, 2, v5
	v_lshlrev_b32_e32 v8, 1, v5
	v_sub_u32_e32 v2, v3, v2
	s_mul_i32 s11, s10, s0
	s_add_i32 s17, s18, s17
	s_mul_i32 s10, s10, s20
	s_ashr_i32 s9, s25, 8
	s_lshl_b64 s[12:13], s[6:7], 8
	s_lshl_b32 s28, s8, 10
	v_and_b32_e32 v7, 4, v7
	v_and_b32_e32 v8, 24, v8
	v_lshlrev_b32_e32 v4, 5, v4
	v_ashrrev_i16_sdwa v2, v9, sext(v2) dst_sel:DWORD dst_unused:UNUSED_PAD src0_sel:DWORD src1_sel:BYTE_0
	s_add_i32 s16, s16, s11
	s_add_i32 s17, s17, s10
	s_mul_i32 s10, s14, s20
	v_or3_b32 v6, v6, v7, v8
	v_and_b32_e32 v17, 32, v4
	v_bfe_i32 v18, v2, 0, 16
	s_add_u32 s18, s27, s10
	v_mul_lo_u32 v6, v6, s6
	v_add_u32_e32 v2, v17, v18
	s_addc_u32 s19, s26, s17
	s_add_i32 s29, s28, 0
	v_add_lshl_u32 v166, v6, v2, 1
	s_add_i32 m0, s29, 0x10000
	s_mul_i32 s11, s14, s0
	global_load_lds_dwordx4 v166, s[18:19]
	s_add_i32 m0, s29, 0x12000
	v_mul_lo_u32 v19, v5, s6
	s_add_u32 s20, s24, s11
	v_add_lshl_u32 v136, v2, v19, 1
	global_load_lds_dwordx4 v132, s[18:19]
	s_addc_u32 s21, s5, s16
	s_mov_b32 m0, s29
	s_add_i32 s30, s29, 0x2000
	global_load_lds_dwordx4 v136, s[20:21]
	s_mov_b32 m0, s30
	s_add_u32 s10, s18, s12
	global_load_lds_dwordx4 v134, s[20:21]
	s_addc_u32 s11, s19, s13
	s_add_i32 m0, s29, 0x14000
	v_mov_b32_e32 v133, v167
	global_load_lds_dwordx4 v166, s[10:11]
	s_add_i32 m0, s29, 0x16000
	v_lshl_add_u64 v[10:11], s[10:11], 0, v[166:167]
	v_lshl_add_u64 v[12:13], s[10:11], 0, v[132:133]
	global_load_lds_dwordx4 v132, s[10:11]
	s_add_u32 s10, s20, s12
	s_addc_u32 s11, s21, s13
	s_add_i32 s31, s29, 0x4000
	s_mov_b32 m0, s31
	s_add_i32 s34, s29, 0x6000
	global_load_lds_dwordx4 v136, s[10:11]
	s_mov_b32 m0, s34
	v_mov_b32_e32 v137, v167
	global_load_lds_dwordx4 v134, s[10:11]
	v_mov_b32_e32 v135, v167
	v_lshl_add_u64 v[2:3], s[18:19], 0, v[166:167]
	v_lshl_add_u64 v[4:5], s[18:19], 0, v[132:133]
	v_lshl_add_u64 v[6:7], s[20:21], 0, v[136:137]
	v_lshl_add_u64 v[8:9], s[20:21], 0, v[134:135]
	s_cmp_lg_u32 s9, 1
	s_cbranch_scc1 .LBB0_213
	s_barrier

.LBB0_233:
	s_mov_b64 s[8:9], s[62:63]
	s_getreg_b32 s5, hwreg(HW_REG_XCC_ID, 0, 4)
	s_waitcnt vmcnt(0)
	v_readlane_b32 s2, v253, 0
	v_readlane_b32 s3, v253, 1
	s_waitcnt vmcnt(0) lgkmcnt(0)
	s_barrier
	s_and_saveexec_b64 s[6:7], s[2:3]
	s_cbranch_execz .LBB0_286
	s_load_dwordx2 s[8:9], s[8:9], 0xc0
	v_readlane_b32 s0, v254, 38
	s_waitcnt expcnt(0) lgkmcnt(0)
	v_mov_b32_e32 v4, s8
	v_mov_b32_e32 v5, s9
	s_and_b32 s5, s5, 15
	v_mov_b32_e32 v0, s0
	ds_read_b32 v2, v0
	v_readlane_b32 s0, v254, 39
	s_waitcnt lgkmcnt(0)
	v_cmp_ne_u32_e32 vcc, 0, v2
	v_mov_b32_e32 v0, s0
	ds_read_b32 v0, v0
	v_readfirstlane_b32 s8, v4
	v_readfirstlane_b32 s9, v5
	s_cbranch_vccnz .LBB0_250
	s_add_u32 s10, s8, 0x2e4c2a00
	s_addc_u32 s11, s9, 0
	s_add_u32 s12, s8, 0x2e4c2c00
	s_addc_u32 s13, s9, 0
	s_add_u32 s14, s8, 0x2e4c2d00
	s_addc_u32 s15, s9, 0
	s_add_u32 s16, s8, 0x2e4c2e00
	s_addc_u32 s17, s9, 0
	s_add_u32 s18, s8, 0x2e4c2f00
	s_addc_u32 s19, s9, 0
	s_add_u32 s20, s8, 0x2e4c3000
	s_addc_u32 s21, s9, 0
	s_add_u32 s22, s8, 0x2e4c3100
	s_addc_u32 s23, s9, 0
	s_add_u32 s24, s8, 0x2e4c3200
	s_addc_u32 s25, s9, 0
	s_add_u32 s26, s8, 0x2e4c3300
	s_addc_u32 s27, s9, 0
	s_add_u32 s28, s8, 0x2e4c3400
	s_addc_u32 s29, s9, 0
	s_add_u32 s30, s8, 0x2e4c3500
	s_addc_u32 s31, s9, 0
	s_add_u32 s34, s8, 0x2e4c3600
	s_addc_u32 s35, s9, 0
	s_add_u32 s36, s8, 0x2e4c3700
	s_addc_u32 s37, s9, 0
	s_add_u32 s38, s8, 0x2e4c3800
	s_addc_u32 s39, s9, 0
	s_add_u32 s40, s8, 0x2e4c3900
	s_addc_u32 s41, s9, 0
	s_add_u32 s42, s8, 0x2e4c3a00
	s_addc_u32 s43, s9, 0
	s_add_u32 s44, s8, 0x2e4c3b00
	s_addc_u32 s45, s9, 0
	s_mov_b32 s52, 1
	s_branch .LBB0_238

.LBB0_305:
	s_mov_b64 s[6:7], s[62:63]
	s_load_dwordx2 s[14:15], s[6:7], 0xc0
	s_lshl_b32 s96, s37, 1
	v_mov_b32_e32 v4, v208
	s_mov_b64 s[8:9], 0x4b00000
	s_ashr_i32 s6, s5, 5
	v_lshlrev_b32_e32 v5, 4, v4
	s_lshl_b32 s7, s6, 8
	v_and_b32_e32 v166, 0x70, v5
	v_ashrrev_i32_e32 v5, 3, v4
	v_add_u32_e32 v6, s7, v5
	v_ashrrev_i32_e32 v7, 31, v6
	v_lshlrev_b64 v[6:7], 12, v[6:7]
	v_add_u32_e32 v10, 0, v166
	v_mad_u64_u32 v[12:13], s[10:11], v5, s94, v[10:11]
	v_add_u32_e32 v11, 0x200, v4
	v_ashrrev_i32_e32 v5, 3, v11
	v_add_u32_e32 v14, 0x400, v4
	v_and_b32_e32 v88, 31, v4
	s_lshl_b32 s6, s6, 11
	v_bfe_u32 v37, v4, 5, 1
	v_mov_b32_e32 v38, s92
	v_lshl_add_u32 v89, v37, 4, 0
	s_waitcnt lgkmcnt(0)
	v_mov_b32_e32 v64, s14
	v_mov_b32_e32 v65, s15
	v_lshl_add_u64 v[0:1], v[64:65], 0, s[96:97]
	v_lshl_add_u64 v[0:1], v[0:1], 0, s[8:9]
	s_lshl_b32 s8, s5, 3
	s_and_b32 s8, s8, 0xc0
	s_lshl_b32 s96, s8, 1
	v_lshl_add_u64 v[2:3], v[0:1], 0, s[96:97]
	v_lshl_add_u64 v[2:3], v[2:3], 0, v[166:167]
	v_lshl_add_u64 v[6:7], v[2:3], 0, v[6:7]
	s_mov_b32 s9, 0
	s_mov_b64 s[10:11], 0x40000
	v_mov_b32_e32 v3, v12
	global_load_dwordx4 v[24:27], v[6:7], off
	v_lshl_add_u64 v[6:7], v[6:7], 0, s[10:11]
	global_load_dwordx4 v[28:31], v[6:7], off
	v_lshl_add_u64 v[6:7], v[6:7], 0, s[10:11]
	global_load_dwordx4 v[32:35], v[6:7], off
	v_lshl_add_u64 v[6:7], v[6:7], 0, s[10:11]
	global_load_dwordx4 v[40:43], v[6:7], off
	v_add_u32_e32 v12, 0x600, v4
	v_ashrrev_i32_e32 v5, 5, v4
	s_waitcnt vmcnt(0)
	ds_write_b128 v3, v[24:27]
	ds_write_b128 v3, v[28:31] offset:9216
	ds_write_b128 v3, v[32:35] offset:18432
	ds_write_b128 v3, v[40:43] offset:27648
	v_add_u32_e32 v2, s7, v5
	v_ashrrev_i32_e32 v3, 31, v2
	v_lshlrev_b64 v[2:3], 12, v[2:3]
	v_lshl_add_u64 v[2:3], v[0:1], 0, v[2:3]
	v_lshlrev_b32_e32 v6, 2, v4
	v_lshl_add_u64 v[2:3], v[2:3], 0, s[96:97]
	v_and_b32_e32 v166, 0x7c, v6
	v_lshl_add_u64 v[2:3], v[2:3], 0, v[166:167]
	v_ashrrev_i32_e32 v7, 5, v11
	global_load_dword v6, v[2:3], off offset:512
	v_add_u32_e32 v2, s7, v7
	v_ashrrev_i32_e32 v3, 31, v2
	v_lshlrev_b64 v[2:3], 12, v[2:3]
	v_lshl_add_u64 v[2:3], v[0:1], 0, v[2:3]
	v_lshl_add_u64 v[2:3], v[2:3], 0, s[96:97]
	v_lshl_add_u64 v[2:3], v[2:3], 0, v[166:167]
	v_ashrrev_i32_e32 v9, 5, v14
	global_load_dword v8, v[2:3], off offset:512
	v_add_u32_e32 v2, s7, v9
	v_ashrrev_i32_e32 v3, 31, v2
	v_lshlrev_b64 v[2:3], 12, v[2:3]
	v_lshl_add_u64 v[2:3], v[0:1], 0, v[2:3]
	v_lshl_add_u64 v[2:3], v[2:3], 0, s[96:97]
	v_lshl_add_u64 v[2:3], v[2:3], 0, v[166:167]
	v_ashrrev_i32_e32 v11, 5, v12
	global_load_dword v10, v[2:3], off offset:512
	v_add_u32_e32 v2, s7, v11
	v_ashrrev_i32_e32 v3, 31, v2
	v_lshlrev_b64 v[2:3], 12, v[2:3]
	v_lshl_add_u64 v[2:3], v[0:1], 0, v[2:3]
	v_lshl_add_u64 v[2:3], v[2:3], 0, s[96:97]
	v_lshl_add_u64 v[2:3], v[2:3], 0, v[166:167]
	global_load_dword v12, v[2:3], off offset:512
	v_add_u32_e32 v2, 0x800, v4
	v_ashrrev_i32_e32 v13, 5, v2
	v_add_u32_e32 v2, s7, v13
	v_ashrrev_i32_e32 v3, 31, v2
	v_lshlrev_b64 v[2:3], 12, v[2:3]
	v_lshl_add_u64 v[2:3], v[0:1], 0, v[2:3]
	v_lshl_add_u64 v[2:3], v[2:3], 0, s[96:97]
	v_lshl_add_u64 v[2:3], v[2:3], 0, v[166:167]
	global_load_dword v14, v[2:3], off offset:512
	v_add_u32_e32 v2, 0xa00, v4
	v_ashrrev_i32_e32 v15, 5, v2
	v_add_u32_e32 v2, s7, v15
	v_ashrrev_i32_e32 v3, 31, v2
	v_lshlrev_b64 v[2:3], 12, v[2:3]
	v_lshl_add_u64 v[2:3], v[0:1], 0, v[2:3]
	v_lshl_add_u64 v[2:3], v[2:3], 0, s[96:97]
	v_lshl_add_u64 v[2:3], v[2:3], 0, v[166:167]
	global_load_dword v16, v[2:3], off offset:512
	v_add_u32_e32 v2, 0xc00, v4
	v_ashrrev_i32_e32 v17, 5, v2
	v_add_u32_e32 v2, s7, v17
	v_ashrrev_i32_e32 v3, 31, v2
	v_lshlrev_b64 v[2:3], 12, v[2:3]
	v_lshl_add_u64 v[2:3], v[0:1], 0, v[2:3]
	v_lshl_add_u64 v[2:3], v[2:3], 0, s[96:97]
	v_lshl_add_u64 v[2:3], v[2:3], 0, v[166:167]
	global_load_dword v18, v[2:3], off offset:512
	v_add_u32_e32 v2, 0xe00, v4
	v_ashrrev_i32_e32 v19, 5, v2
	v_add_u32_e32 v2, s7, v19
	v_ashrrev_i32_e32 v3, 31, v2
	v_lshlrev_b64 v[2:3], 12, v[2:3]
	v_lshl_add_u64 v[2:3], v[0:1], 0, v[2:3]
	v_lshl_add_u64 v[2:3], v[2:3], 0, s[96:97]
	v_lshl_add_u64 v[2:3], v[2:3], 0, v[166:167]
	global_load_dword v20, v[2:3], off offset:512
	v_add_u32_e32 v2, 0x1000, v4
	v_ashrrev_i32_e32 v21, 5, v2
	v_add_u32_e32 v2, s7, v21
	v_ashrrev_i32_e32 v3, 31, v2
	v_lshlrev_b64 v[2:3], 12, v[2:3]
	v_lshl_add_u64 v[2:3], v[0:1], 0, v[2:3]
	v_lshl_add_u64 v[2:3], v[2:3], 0, s[96:97]
	v_lshl_add_u64 v[2:3], v[2:3], 0, v[166:167]
	global_load_dword v22, v[2:3], off offset:512
	v_add_u32_e32 v2, 0x1200, v4
	v_ashrrev_i32_e32 v23, 5, v2
	v_add_u32_e32 v2, s7, v23
	v_ashrrev_i32_e32 v3, 31, v2
	v_lshlrev_b64 v[2:3], 12, v[2:3]
	v_lshl_add_u64 v[2:3], v[0:1], 0, v[2:3]
	v_lshl_add_u64 v[2:3], v[2:3], 0, s[96:97]
	v_lshl_add_u64 v[2:3], v[2:3], 0, v[166:167]
	global_load_dword v24, v[2:3], off offset:512
	v_add_u32_e32 v2, 0x1400, v4
	v_ashrrev_i32_e32 v25, 5, v2
	v_add_u32_e32 v2, s7, v25
	v_ashrrev_i32_e32 v3, 31, v2
	v_lshlrev_b64 v[2:3], 12, v[2:3]
	v_lshl_add_u64 v[2:3], v[0:1], 0, v[2:3]
	v_lshl_add_u64 v[2:3], v[2:3], 0, s[96:97]
	v_lshl_add_u64 v[2:3], v[2:3], 0, v[166:167]
	global_load_dword v26, v[2:3], off offset:512
	v_add_u32_e32 v2, 0x1600, v4
	v_ashrrev_i32_e32 v27, 5, v2
	v_add_u32_e32 v2, s7, v27
	v_ashrrev_i32_e32 v3, 31, v2
	v_lshlrev_b64 v[2:3], 12, v[2:3]
	v_lshl_add_u64 v[2:3], v[0:1], 0, v[2:3]
	v_lshl_add_u64 v[2:3], v[2:3], 0, s[96:97]
	v_lshl_add_u64 v[2:3], v[2:3], 0, v[166:167]
	global_load_dword v28, v[2:3], off offset:512
	v_add_u32_e32 v2, 0x1800, v4
	v_ashrrev_i32_e32 v29, 5, v2
	v_add_u32_e32 v2, s7, v29
	v_ashrrev_i32_e32 v3, 31, v2
	v_lshlrev_b64 v[2:3], 12, v[2:3]
	v_lshl_add_u64 v[2:3], v[0:1], 0, v[2:3]
	v_lshl_add_u64 v[2:3], v[2:3], 0, s[96:97]
	v_lshl_add_u64 v[2:3], v[2:3], 0, v[166:167]
	global_load_dword v30, v[2:3], off offset:512
	v_add_u32_e32 v2, 0x1a00, v4
	v_ashrrev_i32_e32 v31, 5, v2
	v_add_u32_e32 v2, s7, v31
	v_ashrrev_i32_e32 v3, 31, v2
	v_lshlrev_b64 v[2:3], 12, v[2:3]
	v_lshl_add_u64 v[2:3], v[0:1], 0, v[2:3]
	v_lshl_add_u64 v[2:3], v[2:3], 0, s[96:97]
	v_lshl_add_u64 v[2:3], v[2:3], 0, v[166:167]
	global_load_dword v32, v[2:3], off offset:512
	v_add_u32_e32 v2, 0x1c00, v4
	v_ashrrev_i32_e32 v33, 5, v2
	v_add_u32_e32 v2, s7, v33
	v_ashrrev_i32_e32 v3, 31, v2
	v_lshlrev_b64 v[2:3], 12, v[2:3]
	v_lshl_add_u64 v[2:3], v[0:1], 0, v[2:3]
	v_lshl_add_u64 v[2:3], v[2:3], 0, s[96:97]
	v_lshl_add_u64 v[2:3], v[2:3], 0, v[166:167]
	global_load_dword v34, v[2:3], off offset:512
	v_add_u32_e32 v2, 0x1e00, v4
	v_ashrrev_i32_e32 v35, 5, v2
	v_add_u32_e32 v2, s7, v35
	v_ashrrev_i32_e32 v3, 31, v2
	v_lshlrev_b64 v[2:3], 12, v[2:3]
	v_lshl_add_u64 v[0:1], v[0:1], 0, v[2:3]
	v_lshl_add_u64 v[0:1], v[0:1], 0, s[96:97]
	v_lshl_add_u64 v[0:1], v[0:1], 0, v[166:167]
	global_load_dword v36, v[0:1], off offset:512
	v_lshl_add_u32 v0, v88, 2, s92
	v_mad_u64_u32 v[2:3], s[10:11], v5, s93, v[0:1]
	s_waitcnt vmcnt(15)
	ds_write_b32 v2, v6
	v_mad_u64_u32 v[2:3], s[10:11], v7, s93, v[0:1]
	s_waitcnt vmcnt(14)
	ds_write_b32 v2, v8
	v_mad_u64_u32 v[2:3], s[10:11], v9, s93, v[0:1]
	s_waitcnt vmcnt(13)
	ds_write_b32 v2, v10
	v_mad_u64_u32 v[2:3], s[10:11], v11, s93, v[0:1]
	s_waitcnt vmcnt(12)
	ds_write_b32 v2, v12
	v_mad_u64_u32 v[2:3], s[10:11], v13, s93, v[0:1]
	s_waitcnt vmcnt(11)
	ds_write_b32 v2, v14
	v_mad_u64_u32 v[2:3], s[10:11], v15, s93, v[0:1]
	s_waitcnt vmcnt(10)
	ds_write_b32 v2, v16
	v_mad_u64_u32 v[2:3], s[10:11], v17, s93, v[0:1]
	s_waitcnt vmcnt(9)
	ds_write_b32 v2, v18
	v_mad_u64_u32 v[2:3], s[10:11], v19, s93, v[0:1]
	s_waitcnt vmcnt(8)
	ds_write_b32 v2, v20
	v_mad_u64_u32 v[2:3], s[10:11], v21, s93, v[0:1]
	s_waitcnt vmcnt(7)
	ds_write_b32 v2, v22
	v_mad_u64_u32 v[2:3], s[10:11], v23, s93, v[0:1]
	s_waitcnt vmcnt(6)
	ds_write_b32 v2, v24
	v_mad_u64_u32 v[2:3], s[10:11], v25, s93, v[0:1]
	s_lshl_b32 s7, s5, 8
	s_waitcnt vmcnt(5)
	ds_write_b32 v2, v26
	v_mad_u64_u32 v[2:3], s[10:11], v27, s93, v[0:1]
	s_and_b32 s7, s7, 0x700
	s_or_b32 s6, s6, s7
	v_lshlrev_b32_e32 v16, 2, v37
	v_mov_b32_e32 v17, 0xff800000
	s_waitcnt vmcnt(4)
	ds_write_b32 v2, v28
	v_mad_u64_u32 v[2:3], s[10:11], v29, s93, v[0:1]
	s_waitcnt vmcnt(3)
	ds_write_b32 v2, v30
	v_mad_u64_u32 v[2:3], s[10:11], v31, s93, v[0:1]
	s_waitcnt vmcnt(2)
	ds_write_b32 v2, v32
	v_mad_u64_u32 v[2:3], s[10:11], v33, s93, v[0:1]
	v_mad_u64_u32 v[0:1], s[10:11], v35, s93, v[0:1]
	v_or_b32_e32 v1, s6, v88
	s_waitcnt vmcnt(1)
	ds_write_b32 v2, v34
	v_and_or_b32 v2, s5, 24, v37
	v_lshlrev_b32_e32 v2, 4, v2
	s_waitcnt vmcnt(0)
	ds_write_b32 v0, v36
	v_ashrrev_i32_e32 v0, 1, v4
	v_and_b32_e32 v0, 0xffffffe0, v0
	v_add_u32_e32 v86, v1, v0
	v_ashrrev_i32_e32 v87, 31, v86
	v_alignbit_b32 v0, v87, v86, 8
	v_mad_u64_u32 v[0:1], s[6:7], v0, s77, v[64:65]
	v_lshlrev_b32_e32 v3, 9, v86
	v_mad_u32_u24 v1, v87, s77, v1
	v_and_b32_e32 v166, 0x1fe00, v3
	v_lshl_add_u64 v[0:1], v[0:1], 0, v[166:167]
	s_mov_b64 s[6:7], 0x74c2800
	v_mov_b32_e32 v3, v167
	v_lshl_add_u64 v[0:1], v[0:1], 0, s[6:7]
	v_lshl_add_u64 v[2:3], v[0:1], 0, v[2:3]
	s_mov_b64 s[6:7], 0x360000
	v_lshl_add_u64 v[6:7], v[2:3], 0, s[6:7]
	s_mov_b32 s6, 0x360000
	v_add_co_u32_e32 v2, vcc, s6, v2
	s_mov_b64 s[6:7], 0x380000
	s_nop 0
	v_addc_co_u32_e32 v3, vcc, 0, v3, vcc
	global_load_dwordx4 v[48:51], v[2:3], off
	global_load_dwordx4 v[52:55], v[6:7], off offset:32
	global_load_dwordx4 v[56:59], v[6:7], off offset:64
	global_load_dwordx4 v[60:63], v[6:7], off offset:96
	v_or_b32_e32 v2, s8, v16
	v_lshlrev_b32_e32 v166, 1, v2
	v_lshl_add_u64 v[0:1], v[0:1], 0, v[166:167]
	v_lshl_add_u64 v[2:3], v[0:1], 0, s[6:7]
	s_mov_b32 s6, 0x380000
	v_add_co_u32_e32 v0, vcc, s6, v0
	s_mov_b64 s[6:7], -1
	s_nop 0
	v_addc_co_u32_e32 v1, vcc, 0, v1, vcc
	global_load_dwordx2 v[84:85], v[0:1], off
	global_load_dwordx2 v[78:79], v[2:3], off offset:16
	global_load_dwordx2 v[76:77], v[2:3], off offset:32
	global_load_dwordx2 v[74:75], v[2:3], off offset:48
	global_load_dwordx2 v[72:73], v[2:3], off offset:64
	global_load_dwordx2 v[70:71], v[2:3], off offset:80
	global_load_dwordx2 v[68:69], v[2:3], off offset:96
	global_load_dwordx2 v[66:67], v[2:3], off offset:112
	v_and_b32_e32 v0, 0xff, v4
	v_ashrrev_i32_e32 v2, 4, v4
	v_and_b32_e32 v3, -16, v2
	v_mad_u32_u24 v4, v0, s93, v38
	v_lshl_add_u32 v7, v3, 2, v4
	s_waitcnt lgkmcnt(0)
	s_barrier
	v_lshlrev_b32_e32 v5, 1, v0
	ds_read2_b32 v[0:1], v7 offset1:1
	v_add_u32_e32 v6, 0, v5
	v_mul_lo_u32 v3, v3, s69
	v_add_u32_e32 v8, v6, v3
	v_add3_u32 v3, 0, v3, v5
	s_waitcnt lgkmcnt(0)
	ds_write_b16 v8, v0 offset:36864
	ds_write_b16_d16_hi v3, v0 offset:37384
	ds_write_b16 v3, v1 offset:37904
	ds_write_b16_d16_hi v3, v1 offset:38424
	ds_read2_b32 v[0:1], v7 offset0:2 offset1:3
	s_waitcnt lgkmcnt(0)
	ds_write_b16 v3, v0 offset:38944
	ds_write_b16_d16_hi v3, v0 offset:39464
	ds_write_b16 v3, v1 offset:39984
	ds_write_b16_d16_hi v3, v1 offset:40504
	ds_read2_b32 v[0:1], v7 offset0:4 offset1:5
	s_waitcnt lgkmcnt(0)
	ds_write_b16 v3, v0 offset:41024
	ds_write_b16_d16_hi v3, v0 offset:41544
	ds_write_b16 v3, v1 offset:42064
	ds_write_b16_d16_hi v3, v1 offset:42584
	ds_read2_b32 v[0:1], v7 offset0:6 offset1:7
	s_waitcnt lgkmcnt(0)
	ds_write_b16 v3, v0 offset:43104
	ds_write_b16_d16_hi v3, v0 offset:43624
	ds_write_b16 v3, v1 offset:44144
	ds_write_b16_d16_hi v3, v1 offset:44664
	ds_read2_b32 v[0:1], v7 offset0:8 offset1:9
	s_waitcnt lgkmcnt(0)
	ds_write_b16 v3, v0 offset:45184
	ds_write_b16_d16_hi v3, v0 offset:45704
	ds_write_b16 v3, v1 offset:46224
	ds_write_b16_d16_hi v3, v1 offset:46744
	ds_read2_b32 v[0:1], v7 offset0:10 offset1:11
	s_waitcnt lgkmcnt(0)
	ds_write_b16 v3, v0 offset:47264
	ds_write_b16_d16_hi v3, v0 offset:47784
	ds_write_b16 v3, v1 offset:48304
	ds_write_b16_d16_hi v3, v1 offset:48824
	ds_read2_b32 v[0:1], v7 offset0:12 offset1:13
	s_waitcnt lgkmcnt(0)
	ds_write_b16 v3, v0 offset:49344
	ds_write_b16_d16_hi v3, v0 offset:49864
	ds_write_b16 v3, v1 offset:50384
	ds_write_b16_d16_hi v3, v1 offset:50904
	ds_read_b32 v0, v7 offset:56
	s_waitcnt lgkmcnt(0)
	ds_write_b16 v3, v0 offset:51424
	ds_write_b16_d16_hi v3, v0 offset:51944
	v_or_b32_e32 v0, 15, v2
	v_lshl_add_u32 v1, v0, 2, v4
	ds_read_b32 v1, v1
	v_mul_lo_u32 v0, v0, s69
	v_add_u32_e32 v2, v6, v0
	v_add3_u32 v0, 0, v0, v5
	s_waitcnt lgkmcnt(0)
	ds_write_b16 v2, v1 offset:36864
	ds_write_b16_d16_hi v0, v1 offset:37384
	s_waitcnt lgkmcnt(0)
	s_barrier

.LBB0_326:
	v_readlane_b32 s0, v253, 36
	s_or_b32 s41, s37, s0
	v_readlane_b32 s0, v253, 37
	s_or_b32 s40, s37, s0
	v_readlane_b32 s0, v253, 38
	s_or_b32 s39, s37, s0
	v_readlane_b32 s0, v253, 39
	s_or_b32 s38, s37, s0
	s_and_b64 vcc, exec, s[6:7]
	s_cbranch_vccz .LBB0_849
	s_mov_b64 s[6:7], s[62:63]
	s_load_dwordx2 s[6:7], s[6:7], 0xc0
	v_mov_b32_e32 v4, v208
	s_mov_b64 s[10:11], 0x74c2800
	v_lshlrev_b32_e32 v2, 1, v4
	v_and_b32_e32 v5, 0x7e, v2
	v_or_b32_e32 v166, s41, v5
	v_readlane_b32 s0, v253, 16
	v_readlane_b32 s2, v254, 4
	v_readlane_b32 s3, v254, 5
	v_readlane_b32 s16, v253, 58
	v_readlane_b32 s17, v253, 59
	s_mov_b32 s5, s60
	v_readlane_b32 s22, v253, 57
	s_mov_b32 s23, s64
	s_waitcnt lgkmcnt(0)
	v_mov_b32_e32 v0, s6
	v_mov_b32_e32 v1, s7
	v_lshl_add_u64 v[2:3], v[0:1], 0, s[10:11]
	v_lshl_add_u64 v[0:1], v[166:167], 2, v[0:1]
	v_add_co_u32_e32 v0, vcc, 0x7380000, v0
	s_nop 1
	v_addc_co_u32_e32 v1, vcc, 0, v1, vcc
	global_load_dwordx2 v[34:35], v[0:1], off
	v_ashrrev_i32_e32 v0, 3, v4
	v_and_b32_e32 v0, -8, v0
	v_add_u32_e32 v4, s0, v0
	v_ashrrev_i32_e32 v8, 31, v4
	v_alignbit_b32 v6, v8, v4, 8
	v_mad_u64_u32 v[0:1], s[6:7], v6, 49, s[2:3]
	v_readlane_b32 s2, v254, 6
	v_readlane_b32 s3, v254, 7
	v_mad_u32_u24 v1, v8, 49, v1
	v_readlane_b32 s0, v253, 18
	v_mad_u64_u32 v[6:7], s[6:7], v6, 49, s[2:3]
	s_nop 0
	v_or_b32_e32 v5, s0, v5
	v_lshlrev_b64 v[0:1], 17, v[0:1]
	v_mad_u32_u24 v7, v8, 49, v7
	v_lshl_add_u64 v[0:1], v[2:3], 0, v[0:1]
	v_lshlrev_b32_e32 v166, 1, v5
	v_lshlrev_b32_e32 v4, 9, v4
	v_lshlrev_b64 v[6:7], 17, v[6:7]
	v_lshl_add_u64 v[0:1], v[0:1], 0, v[166:167]
	v_and_b32_e32 v4, 0x1f000, v4
	v_mov_b32_e32 v5, v167
	v_lshl_add_u64 v[2:3], v[2:3], 0, v[6:7]
	v_lshl_add_u64 v[0:1], v[0:1], 0, v[4:5]
	v_lshl_add_u64 v[2:3], v[2:3], 0, v[166:167]
	s_mov_b64 s[6:7], s[62:63]
	v_lshl_add_u64 v[2:3], v[2:3], 0, v[4:5]
	global_load_dword v69, v[0:1], off
	global_load_dword v68, v[2:3], off
	global_load_dword v67, v[0:1], off offset:512
	global_load_dword v64, v[2:3], off offset:512
	global_load_dword v66, v[0:1], off offset:1024
	global_load_dword v65, v[2:3], off offset:1024
	global_load_dword v63, v[0:1], off offset:1536
	global_load_dword v60, v[2:3], off offset:1536
	global_load_dword v62, v[0:1], off offset:2048
	global_load_dword v61, v[2:3], off offset:2048
	global_load_dword v59, v[0:1], off offset:2560
	global_load_dword v56, v[2:3], off offset:2560
	global_load_dword v58, v[0:1], off offset:3072
	global_load_dword v57, v[2:3], off offset:3072
	global_load_dword v55, v[0:1], off offset:3584
	global_load_dword v54, v[2:3], off offset:3584
	s_load_dwordx2 s[6:7], s[6:7], 0xc0
	v_mov_b32_e32 v4, v208
	s_mov_b32 s0, 0x7380000
	v_lshlrev_b32_e32 v2, 1, v4
	v_and_b32_e32 v5, 0x7e, v2
	v_or_b32_e32 v166, s40, v5
	v_readlane_b32 s2, v254, 8
	v_readlane_b32 s3, v254, 9
	s_waitcnt lgkmcnt(0)
	v_mov_b32_e32 v0, s6
	v_mov_b32_e32 v1, s7
	v_lshl_add_u64 v[2:3], v[0:1], 0, s[10:11]
	v_lshl_add_u64 v[0:1], v[166:167], 2, v[0:1]
	v_add_co_u32_e32 v0, vcc, s0, v0
	v_readlane_b32 s0, v253, 19
	s_nop 0
	v_addc_co_u32_e32 v1, vcc, 0, v1, vcc
	global_load_dwordx2 v[32:33], v[0:1], off
	v_ashrrev_i32_e32 v0, 3, v4
	v_and_b32_e32 v0, -8, v0
	v_add_u32_e32 v4, s0, v0
	v_ashrrev_i32_e32 v8, 31, v4
	v_alignbit_b32 v6, v8, v4, 8
	v_mad_u64_u32 v[0:1], s[6:7], v6, 49, s[2:3]
	v_readlane_b32 s2, v254, 10
	v_readlane_b32 s3, v254, 11
	v_mad_u32_u24 v1, v8, 49, v1
	v_readlane_b32 s0, v253, 20
	v_mad_u64_u32 v[6:7], s[6:7], v6, 49, s[2:3]
	s_nop 0
	v_or_b32_e32 v5, s0, v5
	v_lshlrev_b64 v[0:1], 17, v[0:1]
	v_mad_u32_u24 v7, v8, 49, v7
	v_lshl_add_u64 v[0:1], v[2:3], 0, v[0:1]
	v_lshlrev_b32_e32 v166, 1, v5
	v_lshlrev_b32_e32 v4, 9, v4
	v_lshlrev_b64 v[6:7], 17, v[6:7]
	v_lshl_add_u64 v[0:1], v[0:1], 0, v[166:167]
	v_and_b32_e32 v4, 0x1f000, v4
	v_mov_b32_e32 v5, v167
	v_lshl_add_u64 v[2:3], v[2:3], 0, v[6:7]
	v_lshl_add_u64 v[0:1], v[0:1], 0, v[4:5]
	v_lshl_add_u64 v[2:3], v[2:3], 0, v[166:167]
	v_lshl_add_u64 v[2:3], v[2:3], 0, v[4:5]
	global_load_dword v53, v[0:1], off
	global_load_dword v52, v[2:3], off
	global_load_dword v51, v[0:1], off offset:512
	global_load_dword v48, v[2:3], off offset:512
	global_load_dword v50, v[0:1], off offset:1024
	global_load_dword v49, v[2:3], off offset:1024
	global_load_dword v47, v[0:1], off offset:1536
	global_load_dword v44, v[2:3], off offset:1536
	global_load_dword v46, v[0:1], off offset:2048
	global_load_dword v45, v[2:3], off offset:2048
	global_load_dword v43, v[0:1], off offset:2560
	global_load_dword v39, v[2:3], off offset:2560
	global_load_dword v42, v[0:1], off offset:3072
	global_load_dword v41, v[2:3], off offset:3072
	global_load_dword v40, v[0:1], off offset:3584
	global_load_dword v38, v[2:3], off offset:3584
	s_waitcnt vmcnt(17)
	v_readlane_b32 s6, v253, 62
	s_and_b64 vcc, exec, s[8:9]
	v_readlane_b32 s7, v253, 63
	s_cbranch_vccz .LBB0_1001

.LBB0_458:
	s_or_b64 exec, exec, s[6:7]
	v_lshlrev_b32_e32 v0, 5, v7
	v_readlane_b32 s0, v254, 44
	v_ashrrev_i32_e32 v1, 2, v70
	v_and_b32_e32 v68, 31, v70
	v_and_b32_e32 v66, 0x60, v0
	v_mov_b32_e32 v0, s0
	v_and_b32_e32 v67, 0xffffffc0, v1
	v_mul_u32_u24_e32 v2, 0x48, v68
	v_lshrrev_b32_e32 v3, 1, v70
	v_mad_u32_u24 v0, v66, s94, v0
	v_mul_lo_u32 v1, v67, s94
	v_lshlrev_b32_e32 v2, 1, v2
	v_and_b32_e32 v3, 16, v3
	v_add3_u32 v34, v0, v2, v3
	v_add3_u32 v0, s2, v1, v3
	v_or_b32_e32 v1, 32, v6
	s_waitcnt lgkmcnt(0)
	s_barrier
	v_add_u32_e32 v35, v0, v2
	v_mad_u32_u24 v69, v1, s94, v0
	ds_read_b128 v[0:3], v34
	ds_read_b128 v[54:57], v34 offset:32
	ds_read_b128 v[4:7], v35
	ds_read_b128 v[58:61], v35 offset:32
	s_waitcnt lgkmcnt(1)
	v_mfma_f32_32x32x16_bf16 v[16:31], v[0:3], v[4:7], 0
	ds_read_b128 v[4:7], v69
	ds_read_b128 v[62:65], v69 offset:32
	v_readlane_b32 s2, v253, 21
	v_readlane_b32 s3, v253, 22
	s_mov_b32 s0, 0x264c2000
	s_mov_b64 s[6:7], s[62:63]
	s_waitcnt lgkmcnt(1)
	v_mfma_f32_32x32x16_bf16 v[0:15], v[0:3], v[4:7], 0
	v_mfma_f32_32x32x16_bf16 v[16:31], v[54:57], v[58:61], v[16:31]
	s_waitcnt lgkmcnt(0)
	v_mfma_f32_32x32x16_bf16 v[0:15], v[54:57], v[62:65], v[0:15]
	ds_read_b128 v[54:57], v34 offset:64
	ds_read_b128 v[58:61], v35 offset:64
	ds_read_b128 v[62:65], v69 offset:64
	s_waitcnt lgkmcnt(1)
	v_mfma_f32_32x32x16_bf16 v[16:31], v[54:57], v[58:61], v[16:31]
	s_waitcnt lgkmcnt(0)
	v_mfma_f32_32x32x16_bf16 v[0:15], v[54:57], v[62:65], v[0:15]
	ds_read_b128 v[54:57], v34 offset:96
	ds_read_b128 v[58:61], v35 offset:96
	ds_read_b128 v[62:65], v69 offset:96
	s_waitcnt vmcnt(0)
	v_lshl_add_u64 v[34:35], v[36:37], 0, s[2:3]
	v_or_b32_e32 v36, v67, v68
	v_lshrrev_b32_e32 v37, 3, v70
	v_lshlrev_b32_e32 v36, 7, v36
	s_mov_b64 s[2:3], 0x264c2800
	v_mov_b32_e32 v70, v208
	s_waitcnt lgkmcnt(1)
	v_mfma_f32_32x32x16_bf16 v[16:31], v[54:57], v[58:61], v[16:31]
	s_waitcnt lgkmcnt(0)
	v_mfma_f32_32x32x16_bf16 v[0:15], v[54:57], v[62:65], v[0:15]
	v_and_or_b32 v54, v37, 4, v66
	v_ashrrev_i32_e32 v37, 31, v36
	v_lshl_add_u64 v[34:35], v[36:37], 1, v[34:35]
	v_lshlrev_b32_e32 v166, 1, v54
	s_nop 5
	v_cvt_pk_bf16_f32 v16, v16, v17
	v_cvt_pk_bf16_f32 v17, v18, v19
	v_lshl_add_u64 v[18:19], v[34:35], 0, v[166:167]
	v_lshl_add_u64 v[36:37], v[18:19], 0, s[2:3]
	v_add_co_u32_e32 v18, vcc, s0, v18
	s_mov_b64 s[2:3], 0x264c4800
	s_nop 0
	v_addc_co_u32_e32 v19, vcc, 0, v19, vcc
	global_store_dwordx2 v[18:19], v[16:17], off offset:2048
	v_cvt_pk_bf16_f32 v16, v20, v21
	v_cvt_pk_bf16_f32 v17, v22, v23
	global_store_dwordx2 v[36:37], v[16:17], off offset:16
	v_cvt_pk_bf16_f32 v16, v24, v25
	v_cvt_pk_bf16_f32 v17, v26, v27
	global_store_dwordx2 v[36:37], v[16:17], off offset:32
	v_cvt_pk_bf16_f32 v16, v28, v29
	v_cvt_pk_bf16_f32 v17, v30, v31
	global_store_dwordx2 v[36:37], v[16:17], off offset:48
	v_lshl_add_u64 v[16:17], v[34:35], 0, s[2:3]
	v_cvt_pk_bf16_f32 v0, v0, v1
	v_cvt_pk_bf16_f32 v1, v2, v3
	v_lshl_add_u64 v[2:3], v[16:17], 0, v[166:167]
	global_store_dwordx2 v[2:3], v[0:1], off
	v_or_b32_e32 v2, 16, v166
	v_mov_b32_e32 v3, v167
	v_cvt_pk_bf16_f32 v0, v4, v5
	v_cvt_pk_bf16_f32 v1, v6, v7
	v_lshl_add_u64 v[2:3], v[16:17], 0, v[2:3]
	global_store_dwordx2 v[2:3], v[0:1], off
	v_or_b32_e32 v2, 32, v166
	v_mov_b32_e32 v3, v167
	v_cvt_pk_bf16_f32 v0, v8, v9
	v_cvt_pk_bf16_f32 v1, v10, v11
	v_lshl_add_u64 v[2:3], v[16:17], 0, v[2:3]
	v_or_b32_e32 v166, 48, v166
	global_store_dwordx2 v[2:3], v[0:1], off
	v_cvt_pk_bf16_f32 v0, v12, v13
	v_cvt_pk_bf16_f32 v1, v14, v15
	v_lshl_add_u64 v[2:3], v[16:17], 0, v[166:167]
	global_store_dwordx2 v[2:3], v[0:1], off
	s_barrier
	s_load_dwordx2 s[6:7], s[6:7], 0xc0
	v_mov_b32_e32 v4, v208
	s_mov_b64 s[2:3], 0x74c2800
	v_lshlrev_b32_e32 v2, 1, v4
	v_and_b32_e32 v5, 0x7e, v2
	v_or_b32_e32 v166, s39, v5
	s_mov_b32 s0, 0x7380000
	s_waitcnt lgkmcnt(0)
	v_mov_b32_e32 v0, s6
	v_mov_b32_e32 v1, s7
	v_lshl_add_u64 v[2:3], v[0:1], 0, s[2:3]
	v_lshl_add_u64 v[0:1], v[166:167], 2, v[0:1]
	v_add_co_u32_e32 v0, vcc, s0, v0
	v_readlane_b32 s0, v253, 23
	s_nop 0
	v_addc_co_u32_e32 v1, vcc, 0, v1, vcc
	global_load_dwordx2 v[34:35], v[0:1], off
	v_ashrrev_i32_e32 v0, 3, v4
	v_and_b32_e32 v0, -8, v0
	v_add_u32_e32 v4, s0, v0
	v_ashrrev_i32_e32 v8, 31, v4
	v_readlane_b32 s2, v254, 12
	v_alignbit_b32 v6, v8, v4, 8
	v_readlane_b32 s3, v254, 13
	v_readlane_b32 s0, v253, 24
	v_lshlrev_b32_e32 v4, 9, v4
	v_mad_u64_u32 v[0:1], s[6:7], v6, 49, s[2:3]
	v_readlane_b32 s2, v254, 14
	v_readlane_b32 s3, v254, 15
	v_mad_u32_u24 v1, v8, 49, v1
	v_or_b32_e32 v5, s0, v5
	v_mad_u64_u32 v[6:7], s[6:7], v6, 49, s[2:3]
	v_lshlrev_b64 v[0:1], 17, v[0:1]
	v_mad_u32_u24 v7, v8, 49, v7
	v_lshl_add_u64 v[0:1], v[2:3], 0, v[0:1]
	v_lshlrev_b32_e32 v166, 1, v5
	v_lshlrev_b64 v[6:7], 17, v[6:7]
	v_lshl_add_u64 v[0:1], v[0:1], 0, v[166:167]
	v_and_b32_e32 v4, 0x1f000, v4
	v_mov_b32_e32 v5, v167
	v_lshl_add_u64 v[2:3], v[2:3], 0, v[6:7]
	v_lshl_add_u64 v[0:1], v[0:1], 0, v[4:5]
	v_lshl_add_u64 v[2:3], v[2:3], 0, v[166:167]
	v_lshl_add_u64 v[2:3], v[2:3], 0, v[4:5]
	global_load_dword v69, v[0:1], off
	global_load_dword v68, v[2:3], off
	global_load_dword v67, v[0:1], off offset:512
	global_load_dword v64, v[2:3], off offset:512
	global_load_dword v66, v[0:1], off offset:1024
	global_load_dword v65, v[2:3], off offset:1024
	global_load_dword v63, v[0:1], off offset:1536
	global_load_dword v60, v[2:3], off offset:1536
	global_load_dword v62, v[0:1], off offset:2048
	global_load_dword v61, v[2:3], off offset:2048
	global_load_dword v59, v[0:1], off offset:2560
	global_load_dword v55, v[2:3], off offset:2560
	global_load_dword v58, v[0:1], off offset:3072
	global_load_dword v57, v[2:3], off offset:3072
	global_load_dword v56, v[0:1], off offset:3584
	global_load_dword v54, v[2:3], off offset:3584
	v_lshlrev_b32_e32 v1, 16, v53
	v_and_b32_e32 v5, 0xffff0000, v53
	v_mul_f32_e32 v8, 0xbfb8aa3b, v1
	v_mul_f32_e32 v9, 0xbfb8aa3b, v5
	v_exp_f32_e32 v8, v8
	v_exp_f32_e32 v9, v9
	s_mov_b64 s[6:7], s[62:63]
	v_add_f32_e32 v8, 1.0, v8
	v_add_f32_e32 v9, 1.0, v9
	v_rcp_f32_e32 v8, v8
	v_rcp_f32_e32 v9, v9
	global_load_dwordx2 v[36:37], v167, s[6:7] offset:192
	s_movk_i32 s2, 0x408
	v_and_b32_e32 v6, 63, v70
	v_ashrrev_i32_e32 v7, 6, v70
	v_lshlrev_b32_e32 v0, 1, v6
	v_pk_add_f32 v[2:3], v[32:33], 1.0 op_sel_hi:[1,0] neg_lo:[1,0] neg_hi:[1,0]
	v_mad_u64_u32 v[10:11], s[6:7], v7, s2, v[0:1]
	v_mul_f32_e32 v1, 0x3fb8aa3b, v1
	v_fma_f32 v8, v2, v8, v32
	v_fma_f32 v9, v3, v9, v33
	v_exp_f32_e32 v1, v1
	v_log_f32_e32 v8, v8
	v_log_f32_e32 v9, v9
	v_lshl_add_u32 v10, v10, 2, 0
	v_add_f32_e32 v1, 1.0, v1
	v_readlane_b32 s0, v254, 42
	ds_write_b64 v10, v[8:9]
	v_rcp_f32_e32 v8, v1
	v_mul_f32_e32 v1, 0x3fb8aa3b, v5
	v_exp_f32_e32 v1, v1
	v_lshl_add_u32 v4, v6, 2, s0
	s_movk_i32 s2, 0x820
	v_and_b32_e32 v11, 0xffff0000, v51
	v_add_f32_e32 v1, 1.0, v1
	v_rcp_f32_e32 v9, v1
	s_movk_i32 s3, 0x900
	v_cmp_lt_u32_e64 s[12:13], 15, v6
	v_pk_mul_f32 v[8:9], v[2:3], v[8:9]
	ds_write_b64 v10, v[8:9] offset:33024
	v_lshlrev_b32_e32 v10, 16, v51
	v_mul_f32_e32 v1, 0xbfb8aa3b, v10
	v_exp_f32_e32 v1, v1
	v_mad_u64_u32 v[8:9], s[6:7], v7, s2, v[4:5]
	v_lshl_or_b32 v5, v7, 3, 1
	v_add_f32_e32 v1, 1.0, v1
	v_rcp_f32_e32 v1, v1
	s_movk_i32 s2, 0x81
	ds_write_b32 v8, v52
	v_fma_f32 v1, v2, v1, v32
	v_mad_u64_u32 v[8:9], s[6:7], v5, s2, v[0:1]
	v_log_f32_e32 v12, v1
	v_lshl_add_u32 v1, v8, 2, 0
	v_mul_f32_e32 v8, 0xbfb8aa3b, v11
	v_exp_f32_e32 v8, v8
	v_mul_f32_e32 v9, 0x3fb8aa3b, v11
	v_exp_f32_e32 v9, v9
	s_movk_i32 s2, 0x104
	v_add_f32_e32 v8, 1.0, v8
	v_rcp_f32_e32 v8, v8
	v_add_f32_e32 v9, 1.0, v9
	v_rcp_f32_e32 v9, v9
	v_mad_u64_u32 v[4:5], s[6:7], v5, s2, v[4:5]
	v_fma_f32 v8, v3, v8, v33
	v_log_f32_e32 v8, v8
	v_lshlrev_b32_e32 v5, 16, v50
	s_movk_i32 s2, 0x204
	ds_write2_b32 v1, v12, v8 offset1:1
	v_mul_f32_e32 v8, 0x3fb8aa3b, v10
	v_exp_f32_e32 v8, v8
	v_add_u32_e32 v10, 0x8100, v1
	v_add_f32_e32 v8, 1.0, v8
	v_rcp_f32_e32 v8, v8
	s_nop 0
	v_pk_mul_f32 v[8:9], v[2:3], v[8:9]
	ds_write2_b32 v10, v8, v9 offset1:1
	v_and_b32_e32 v10, 0xffff0000, v50
	v_mul_f32_e32 v8, 0xbfb8aa3b, v5
	v_mul_f32_e32 v9, 0xbfb8aa3b, v10
	v_exp_f32_e32 v8, v8
	v_exp_f32_e32 v9, v9
	v_mul_f32_e32 v5, 0x3fb8aa3b, v5
	v_exp_f32_e32 v5, v5
	v_add_f32_e32 v8, 1.0, v8
	v_add_f32_e32 v9, 1.0, v9
	v_rcp_f32_e32 v8, v8
	v_rcp_f32_e32 v9, v9
	v_add_f32_e32 v5, 1.0, v5
	v_fma_f32 v8, v2, v8, v32
	v_fma_f32 v9, v3, v9, v33
	v_log_f32_e32 v8, v8
	v_log_f32_e32 v9, v9
	ds_write_b64 v1, v[8:9] offset:516
	v_rcp_f32_e32 v8, v5
	v_mul_f32_e32 v5, 0x3fb8aa3b, v10
	v_exp_f32_e32 v5, v5
	v_add_u32_e32 v10, 0x408, v1
	v_add_f32_e32 v5, 1.0, v5
	v_rcp_f32_e32 v9, v5
	v_lshlrev_b32_e32 v5, 16, v47
	v_pk_mul_f32 v[8:9], v[2:3], v[8:9]
	ds_write_b64 v1, v[8:9] offset:33540
	ds_write2_b32 v4, v48, v49 offset1:65
	v_and_b32_e32 v9, 0xffff0000, v47
	v_mul_f32_e32 v8, 0xbfb8aa3b, v5
	v_mul_f32_e32 v11, 0xbfb8aa3b, v9
	v_exp_f32_e32 v8, v8
	v_exp_f32_e32 v11, v11
	v_mul_f32_e32 v5, 0x3fb8aa3b, v5
	v_mul_f32_e32 v9, 0x3fb8aa3b, v9
	v_add_f32_e32 v8, 1.0, v8
	v_add_f32_e32 v11, 1.0, v11
	v_rcp_f32_e32 v8, v8
	v_rcp_f32_e32 v11, v11
	v_exp_f32_e32 v5, v5
	v_exp_f32_e32 v9, v9
	v_fma_f32 v8, v2, v8, v32
	v_fma_f32 v11, v3, v11, v33
	v_log_f32_e32 v8, v8
	v_log_f32_e32 v11, v11
	v_add_f32_e32 v5, 1.0, v5
	v_add_f32_e32 v9, 1.0, v9
	v_rcp_f32_e32 v9, v9
	ds_write2_b32 v10, v8, v11 offset1:1
	v_rcp_f32_e32 v8, v5
	v_add_u32_e32 v5, 0x8508, v1
	v_and_b32_e32 v10, 0xffff0000, v46
	v_pk_mul_f32 v[8:9], v[2:3], v[8:9]
	ds_write2_b32 v5, v8, v9 offset1:1
	v_lshlrev_b32_e32 v5, 16, v46
	v_mul_f32_e32 v8, 0xbfb8aa3b, v5
	v_mul_f32_e32 v9, 0xbfb8aa3b, v10
	v_exp_f32_e32 v8, v8
	v_exp_f32_e32 v9, v9
	v_mul_f32_e32 v5, 0x3fb8aa3b, v5
	v_exp_f32_e32 v5, v5
	v_add_f32_e32 v8, 1.0, v8
	v_add_f32_e32 v9, 1.0, v9
	v_rcp_f32_e32 v8, v8
	v_rcp_f32_e32 v9, v9
	v_add_f32_e32 v5, 1.0, v5
	v_fma_f32 v8, v2, v8, v32
	v_fma_f32 v9, v3, v9, v33
	v_log_f32_e32 v8, v8
	v_log_f32_e32 v9, v9
	ds_write_b64 v1, v[8:9] offset:1548
	v_rcp_f32_e32 v8, v5
	v_mul_f32_e32 v5, 0x3fb8aa3b, v10
	v_exp_f32_e32 v5, v5
	v_add_u32_e32 v10, 0x810, v1
	v_add_f32_e32 v5, 1.0, v5
	v_rcp_f32_e32 v9, v5
	v_lshlrev_b32_e32 v5, 16, v43
	v_pk_mul_f32 v[8:9], v[2:3], v[8:9]
	ds_write_b64 v1, v[8:9] offset:34572
	ds_write2_b32 v4, v44, v45 offset0:130 offset1:195
	v_and_b32_e32 v9, 0xffff0000, v43
	v_mul_f32_e32 v8, 0xbfb8aa3b, v5
	v_mul_f32_e32 v11, 0xbfb8aa3b, v9
	v_exp_f32_e32 v8, v8
	v_exp_f32_e32 v11, v11
	v_mul_f32_e32 v5, 0x3fb8aa3b, v5
	v_mul_f32_e32 v9, 0x3fb8aa3b, v9
	v_add_f32_e32 v8, 1.0, v8
	v_add_f32_e32 v11, 1.0, v11
	v_rcp_f32_e32 v8, v8
	v_rcp_f32_e32 v11, v11
	v_exp_f32_e32 v5, v5
	v_exp_f32_e32 v9, v9
	v_fma_f32 v8, v2, v8, v32
	v_fma_f32 v11, v3, v11, v33
	v_log_f32_e32 v8, v8
	v_log_f32_e32 v11, v11
	v_add_f32_e32 v5, 1.0, v5
	v_add_f32_e32 v9, 1.0, v9
	v_rcp_f32_e32 v9, v9
	ds_write2_b32 v10, v8, v11 offset1:1
	v_rcp_f32_e32 v8, v5
	v_add_u32_e32 v5, 0x8910, v1
	v_and_b32_e32 v10, 0xffff0000, v42
	v_pk_mul_f32 v[8:9], v[2:3], v[8:9]
	ds_write2_b32 v5, v8, v9 offset1:1
	v_lshlrev_b32_e32 v5, 16, v42
	v_mul_f32_e32 v8, 0xbfb8aa3b, v5
	v_mul_f32_e32 v9, 0xbfb8aa3b, v10
	v_exp_f32_e32 v8, v8
	v_exp_f32_e32 v9, v9
	v_mul_f32_e32 v5, 0x3fb8aa3b, v5
	v_exp_f32_e32 v5, v5
	v_add_f32_e32 v8, 1.0, v8
	v_add_f32_e32 v9, 1.0, v9
	v_rcp_f32_e32 v8, v8
	v_rcp_f32_e32 v9, v9
	v_add_f32_e32 v5, 1.0, v5
	v_fma_f32 v8, v2, v8, v32
	v_fma_f32 v9, v3, v9, v33
	v_log_f32_e32 v8, v8
	v_log_f32_e32 v9, v9
	ds_write_b64 v1, v[8:9] offset:2580
	v_rcp_f32_e32 v8, v5
	v_mul_f32_e32 v5, 0x3fb8aa3b, v10
	v_exp_f32_e32 v5, v5
	v_add_u32_e32 v10, 0xc18, v1
	v_add_f32_e32 v5, 1.0, v5
	v_rcp_f32_e32 v9, v5
	v_add_u32_e32 v5, 0x400, v4
	ds_write2_b32 v5, v39, v41 offset0:4 offset1:69
	v_lshlrev_b32_e32 v5, 16, v40
	v_pk_mul_f32 v[8:9], v[2:3], v[8:9]
	ds_write_b64 v1, v[8:9] offset:35604
	v_and_b32_e32 v9, 0xffff0000, v40
	v_mul_f32_e32 v8, 0xbfb8aa3b, v5
	v_mul_f32_e32 v11, 0xbfb8aa3b, v9
	v_exp_f32_e32 v8, v8
	v_exp_f32_e32 v11, v11
	v_mul_f32_e32 v5, 0x3fb8aa3b, v5
	v_exp_f32_e32 v5, v5
	v_add_f32_e32 v8, 1.0, v8
	v_add_f32_e32 v11, 1.0, v11
	v_rcp_f32_e32 v8, v8
	v_rcp_f32_e32 v11, v11
	v_add_f32_e32 v5, 1.0, v5
	v_add_u32_e32 v1, 0x8d18, v1
	v_fma_f32 v8, v2, v8, v32
	v_fmac_f32_e32 v33, v3, v11
	v_log_f32_e32 v8, v8
	v_log_f32_e32 v11, v33
	ds_write2_b32 v10, v8, v11 offset1:1
	v_rcp_f32_e32 v8, v5
	v_mul_f32_e32 v5, 0x3fb8aa3b, v9
	v_exp_f32_e32 v5, v5
	s_nop 0
	v_add_f32_e32 v5, 1.0, v5
	v_rcp_f32_e32 v9, v5
	s_nop 0
	v_pk_mul_f32 v[2:3], v[2:3], v[8:9]
	ds_write2_b32 v1, v2, v3 offset1:1
	ds_write_b32 v4, v38 offset:1560
	v_and_b32_e32 v1, 0x7f, v70
	v_ashrrev_i32_e32 v3, 3, v70
	v_and_b32_e32 v4, 0x3ffffff0, v3
	v_lshl_add_u32 v2, v1, 2, 0
	v_mad_u64_u32 v[4:5], s[6:7], v4, s2, v[2:3]
	s_waitcnt lgkmcnt(0)
	s_barrier
	ds_read2_b32 v[8:9], v4 offset1:129
	v_or_b32_e32 v3, 15, v3
	v_mad_u64_u32 v[2:3], s[6:7], v3, s2, v[2:3]
	v_readlane_b32 s2, v254, 43
	s_waitcnt lgkmcnt(0)
	v_add_f32_e32 v1, 0, v8
	v_add_f32_e32 v5, v1, v9
	ds_write2_b32 v4, v1, v5 offset1:129
	v_add_u32_e32 v1, 0x400, v4
	ds_read2_b32 v[8:9], v1 offset0:2 offset1:131
	s_waitcnt lgkmcnt(0)
	v_add_f32_e32 v5, v5, v8
	v_add_f32_e32 v10, v5, v9
	ds_write2_b32 v1, v5, v10 offset0:2 offset1:131
	v_add_u32_e32 v1, 0x800, v4
	ds_read2_b32 v[8:9], v1 offset0:4 offset1:133
	s_waitcnt lgkmcnt(0)
	v_add_f32_e32 v5, v10, v8
	v_add_f32_e32 v10, v5, v9
	ds_write2_b32 v1, v5, v10 offset0:4 offset1:133
	v_add_u32_e32 v1, 0xc00, v4
	ds_read2_b32 v[8:9], v1 offset0:6 offset1:135
	s_waitcnt lgkmcnt(0)
	v_add_f32_e32 v5, v10, v8
	v_add_f32_e32 v10, v5, v9
	ds_write2_b32 v1, v5, v10 offset0:6 offset1:135
	v_add_u32_e32 v1, 0x1000, v4
	ds_read2_b32 v[8:9], v1 offset0:8 offset1:137
	s_waitcnt lgkmcnt(0)
	v_add_f32_e32 v5, v10, v8
	v_add_f32_e32 v10, v5, v9
	ds_write2_b32 v1, v5, v10 offset0:8 offset1:137
	v_add_u32_e32 v1, 0x1400, v4
	ds_read2_b32 v[8:9], v1 offset0:10 offset1:139
	s_waitcnt lgkmcnt(0)
	v_add_f32_e32 v5, v10, v8
	v_add_f32_e32 v10, v5, v9
	ds_write2_b32 v1, v5, v10 offset0:10 offset1:139
	v_add_u32_e32 v1, 0x1800, v4
	ds_read2_b32 v[8:9], v1 offset0:12 offset1:141
	s_waitcnt lgkmcnt(0)
	v_add_f32_e32 v5, v10, v8
	v_add_f32_e32 v8, v5, v9
	ds_write2_b32 v1, v5, v8 offset0:12 offset1:141
	ds_read_b32 v1, v4 offset:7224
	s_waitcnt lgkmcnt(0)
	v_add_f32_e32 v1, v8, v1
	ds_write_b32 v4, v1 offset:7224
	ds_read_b32 v3, v2
	v_lshl_add_u32 v4, v70, 2, s51
	s_waitcnt lgkmcnt(0)
	v_add_f32_e32 v1, v1, v3
	ds_write_b32 v2, v1
	ds_write_b32 v4, v1
	v_ashrrev_i32_e32 v1, 31, v70
	v_lshrrev_b32_e32 v1, 26, v1
	v_add_u32_e32 v1, v70, v1
	v_ashrrev_i32_e32 v1, 6, v1
	v_mul_u32_u24_e32 v2, 0x41, v6
	v_lshlrev_b32_e32 v5, 5, v1
	v_lshlrev_b32_e32 v8, 2, v2
	v_add3_u32 v2, s0, v5, v8
	ds_read2_b32 v[2:3], v2 offset1:1
	v_mul_lo_u32 v9, v1, s3
	v_add3_u32 v10, s2, v9, v0
	v_lshl_or_b32 v1, v1, 3, 1
	s_movk_i32 s3, 0x120
	s_waitcnt lgkmcnt(0)
	ds_write_b16 v10, v2
	v_add_u32_e32 v10, s2, v0
	v_add_u32_e32 v9, v10, v9
	v_mul_lo_u32 v1, v1, s3
	ds_write_b16_d16_hi v9, v2 offset:144
	v_add3_u32 v2, s2, v1, v0
	v_add_u32_e32 v9, v10, v1
	ds_write_b16 v2, v3
	ds_write_b16_d16_hi v9, v3 offset:144
	v_add3_u32 v3, s0, v8, v5
	ds_read2_b32 v[0:1], v3 offset0:2 offset1:3
	s_waitcnt lgkmcnt(0)
	ds_write_b16 v2, v0 offset:288
	ds_write_b16_d16_hi v9, v0 offset:432
	ds_write_b16 v2, v1 offset:576
	ds_write_b16_d16_hi v9, v1 offset:720
	ds_read2_b32 v[0:1], v3 offset0:4 offset1:5
	s_waitcnt lgkmcnt(0)
	ds_write_b16 v2, v0 offset:864
	ds_write_b16_d16_hi v9, v0 offset:1008
	ds_write_b16 v2, v1 offset:1152
	ds_write_b16_d16_hi v9, v1 offset:1296
	ds_read2_b32 v[0:1], v3 offset0:6 offset1:7
	s_waitcnt lgkmcnt(0)
	ds_write_b16 v2, v0 offset:1440
	ds_write_b16_d16_hi v9, v0 offset:1584
	ds_write_b16 v2, v1 offset:1728
	ds_write_b16_d16_hi v9, v1 offset:1872
	v_bfe_u32 v0, v70, 4, 2
	v_lshl_add_u32 v5, v7, 2, s51
	s_waitcnt lgkmcnt(0)
	s_barrier
	v_cmp_ne_u32_e64 s[10:11], 1, v0
	v_cmp_eq_u32_e32 vcc, 2, v0
	ds_read2st64_b32 v[0:1], v5 offset0:2 offset1:4
	ds_read_b32 v3, v5 offset:1536
	s_and_saveexec_b64 s[6:7], s[12:13]
	s_xor_b64 s[6:7], exec, s[6:7]
	s_cbranch_execz .LBB0_464
	s_and_saveexec_b64 s[14:15], s[10:11]
	s_xor_b64 s[14:15], exec, s[14:15]
	s_cbranch_execz .LBB0_461
	s_waitcnt lgkmcnt(0)
	v_add_f32_e32 v0, v1, v3
	v_cndmask_b32_e32 v2, v3, v0, vcc

.LBB0_588:
	s_or_b64 exec, exec, s[6:7]
	v_lshlrev_b32_e32 v0, 5, v7
	v_readlane_b32 s0, v254, 44
	v_ashrrev_i32_e32 v1, 2, v70
	v_and_b32_e32 v52, 31, v70
	v_and_b32_e32 v50, 0x60, v0
	v_mov_b32_e32 v0, s0
	v_and_b32_e32 v51, 0xffffffc0, v1
	v_mul_u32_u24_e32 v2, 0x48, v52
	v_lshrrev_b32_e32 v3, 1, v70
	v_mad_u32_u24 v0, v50, s94, v0
	v_mul_lo_u32 v1, v51, s94
	v_lshlrev_b32_e32 v2, 1, v2
	v_and_b32_e32 v3, 16, v3
	v_add3_u32 v32, v0, v2, v3
	v_add3_u32 v0, s2, v1, v3
	v_or_b32_e32 v1, 32, v6
	s_waitcnt lgkmcnt(0)
	s_barrier
	v_add_u32_e32 v33, v0, v2
	v_mad_u32_u24 v53, v1, s94, v0
	ds_read_b128 v[0:3], v32
	ds_read_b128 v[38:41], v32 offset:32
	ds_read_b128 v[4:7], v33
	ds_read_b128 v[42:45], v33 offset:32
	s_waitcnt lgkmcnt(1)
	v_mfma_f32_32x32x16_bf16 v[16:31], v[0:3], v[4:7], 0
	ds_read_b128 v[4:7], v53
	ds_read_b128 v[46:49], v53 offset:32
	v_readlane_b32 s2, v253, 26
	v_readlane_b32 s3, v253, 27
	s_mov_b32 s0, 0x264c2000
	s_mov_b64 s[6:7], s[62:63]
	s_waitcnt lgkmcnt(1)
	v_mfma_f32_32x32x16_bf16 v[0:15], v[0:3], v[4:7], 0
	v_mfma_f32_32x32x16_bf16 v[16:31], v[38:41], v[42:45], v[16:31]
	s_waitcnt lgkmcnt(0)
	v_mfma_f32_32x32x16_bf16 v[0:15], v[38:41], v[46:49], v[0:15]
	ds_read_b128 v[38:41], v32 offset:64
	ds_read_b128 v[42:45], v33 offset:64
	ds_read_b128 v[46:49], v53 offset:64
	s_waitcnt lgkmcnt(1)
	v_mfma_f32_32x32x16_bf16 v[16:31], v[38:41], v[42:45], v[16:31]
	s_waitcnt lgkmcnt(0)
	v_mfma_f32_32x32x16_bf16 v[0:15], v[38:41], v[46:49], v[0:15]
	ds_read_b128 v[38:41], v32 offset:96
	ds_read_b128 v[42:45], v33 offset:96
	ds_read_b128 v[46:49], v53 offset:96
	s_waitcnt vmcnt(0)
	v_lshl_add_u64 v[32:33], v[36:37], 0, s[2:3]
	v_or_b32_e32 v36, v51, v52
	v_lshrrev_b32_e32 v37, 3, v70
	v_lshlrev_b32_e32 v36, 7, v36
	s_mov_b64 s[2:3], 0x264c2800
	v_mov_b32_e32 v70, v208
	s_waitcnt lgkmcnt(1)
	v_mfma_f32_32x32x16_bf16 v[16:31], v[38:41], v[42:45], v[16:31]
	s_waitcnt lgkmcnt(0)
	v_mfma_f32_32x32x16_bf16 v[0:15], v[38:41], v[46:49], v[0:15]
	v_and_or_b32 v38, v37, 4, v50
	v_ashrrev_i32_e32 v37, 31, v36
	v_lshl_add_u64 v[32:33], v[36:37], 1, v[32:33]
	v_lshlrev_b32_e32 v166, 1, v38
	s_nop 5
	v_cvt_pk_bf16_f32 v16, v16, v17
	v_cvt_pk_bf16_f32 v17, v18, v19
	v_lshl_add_u64 v[18:19], v[32:33], 0, v[166:167]
	v_lshl_add_u64 v[36:37], v[18:19], 0, s[2:3]
	v_add_co_u32_e32 v18, vcc, s0, v18
	s_mov_b64 s[2:3], 0x264c4800
	s_nop 0
	v_addc_co_u32_e32 v19, vcc, 0, v19, vcc
	global_store_dwordx2 v[18:19], v[16:17], off offset:2048
	v_cvt_pk_bf16_f32 v16, v20, v21
	v_cvt_pk_bf16_f32 v17, v22, v23
	global_store_dwordx2 v[36:37], v[16:17], off offset:16
	v_cvt_pk_bf16_f32 v16, v24, v25
	v_cvt_pk_bf16_f32 v17, v26, v27
	global_store_dwordx2 v[36:37], v[16:17], off offset:32
	v_cvt_pk_bf16_f32 v16, v28, v29
	v_cvt_pk_bf16_f32 v17, v30, v31
	global_store_dwordx2 v[36:37], v[16:17], off offset:48
	v_lshl_add_u64 v[16:17], v[32:33], 0, s[2:3]
	v_cvt_pk_bf16_f32 v0, v0, v1
	v_cvt_pk_bf16_f32 v1, v2, v3
	v_lshl_add_u64 v[2:3], v[16:17], 0, v[166:167]
	global_store_dwordx2 v[2:3], v[0:1], off
	v_or_b32_e32 v2, 16, v166
	v_mov_b32_e32 v3, v167
	v_cvt_pk_bf16_f32 v0, v4, v5
	v_cvt_pk_bf16_f32 v1, v6, v7
	v_lshl_add_u64 v[2:3], v[16:17], 0, v[2:3]
	global_store_dwordx2 v[2:3], v[0:1], off
	v_or_b32_e32 v2, 32, v166
	v_mov_b32_e32 v3, v167
	v_cvt_pk_bf16_f32 v0, v8, v9
	v_cvt_pk_bf16_f32 v1, v10, v11
	v_lshl_add_u64 v[2:3], v[16:17], 0, v[2:3]
	v_or_b32_e32 v166, 48, v166
	global_store_dwordx2 v[2:3], v[0:1], off
	v_cvt_pk_bf16_f32 v0, v12, v13
	v_cvt_pk_bf16_f32 v1, v14, v15
	v_lshl_add_u64 v[2:3], v[16:17], 0, v[166:167]
	global_store_dwordx2 v[2:3], v[0:1], off
	s_barrier
	s_load_dwordx2 s[6:7], s[6:7], 0xc0
	v_mov_b32_e32 v4, v208
	s_mov_b64 s[2:3], 0x74c2800
	v_lshlrev_b32_e32 v2, 1, v4
	v_and_b32_e32 v5, 0x7e, v2
	v_or_b32_e32 v166, s38, v5
	s_mov_b32 s0, 0x7380000
	s_waitcnt lgkmcnt(0)
	v_mov_b32_e32 v0, s6
	v_mov_b32_e32 v1, s7
	v_lshl_add_u64 v[2:3], v[0:1], 0, s[2:3]
	v_lshl_add_u64 v[0:1], v[166:167], 2, v[0:1]
	v_add_co_u32_e32 v0, vcc, s0, v0
	v_readlane_b32 s0, v253, 28
	s_nop 0
	v_addc_co_u32_e32 v1, vcc, 0, v1, vcc
	global_load_dwordx2 v[32:33], v[0:1], off
	v_ashrrev_i32_e32 v0, 3, v4
	v_and_b32_e32 v0, -8, v0
	v_add_u32_e32 v4, s0, v0
	v_ashrrev_i32_e32 v8, 31, v4
	v_readlane_b32 s2, v254, 16
	v_alignbit_b32 v6, v8, v4, 8
	v_readlane_b32 s3, v254, 17
	v_readlane_b32 s0, v253, 29
	v_lshlrev_b32_e32 v4, 9, v4
	v_mad_u64_u32 v[0:1], s[6:7], v6, 49, s[2:3]
	v_readlane_b32 s2, v254, 18
	v_readlane_b32 s3, v254, 19
	v_mad_u32_u24 v1, v8, 49, v1
	v_or_b32_e32 v5, s0, v5
	v_mad_u64_u32 v[6:7], s[6:7], v6, 49, s[2:3]
	v_lshlrev_b64 v[0:1], 17, v[0:1]
	v_mad_u32_u24 v7, v8, 49, v7
	v_lshl_add_u64 v[0:1], v[2:3], 0, v[0:1]
	v_lshlrev_b32_e32 v166, 1, v5
	v_lshlrev_b64 v[6:7], 17, v[6:7]
	v_lshl_add_u64 v[0:1], v[0:1], 0, v[166:167]
	v_and_b32_e32 v4, 0x1f000, v4
	v_mov_b32_e32 v5, v167
	v_lshl_add_u64 v[2:3], v[2:3], 0, v[6:7]
	v_lshl_add_u64 v[0:1], v[0:1], 0, v[4:5]
	v_lshl_add_u64 v[2:3], v[2:3], 0, v[166:167]
	v_lshl_add_u64 v[2:3], v[2:3], 0, v[4:5]
	global_load_dword v53, v[0:1], off
	global_load_dword v52, v[2:3], off
	global_load_dword v51, v[0:1], off offset:512
	global_load_dword v48, v[2:3], off offset:512
	global_load_dword v50, v[0:1], off offset:1024
	global_load_dword v49, v[2:3], off offset:1024
	global_load_dword v47, v[0:1], off offset:1536
	global_load_dword v44, v[2:3], off offset:1536
	global_load_dword v46, v[0:1], off offset:2048
	global_load_dword v45, v[2:3], off offset:2048
	global_load_dword v43, v[0:1], off offset:2560
	global_load_dword v39, v[2:3], off offset:2560
	global_load_dword v42, v[0:1], off offset:3072
	global_load_dword v41, v[2:3], off offset:3072
	global_load_dword v40, v[0:1], off offset:3584
	global_load_dword v38, v[2:3], off offset:3584
	v_lshlrev_b32_e32 v1, 16, v69
	v_and_b32_e32 v5, 0xffff0000, v69
	v_mul_f32_e32 v8, 0xbfb8aa3b, v1
	v_mul_f32_e32 v9, 0xbfb8aa3b, v5
	v_exp_f32_e32 v8, v8
	v_exp_f32_e32 v9, v9
	s_mov_b64 s[6:7], s[62:63]
	v_add_f32_e32 v8, 1.0, v8
	v_add_f32_e32 v9, 1.0, v9
	v_rcp_f32_e32 v8, v8
	v_rcp_f32_e32 v9, v9
	global_load_dwordx2 v[36:37], v167, s[6:7] offset:192
	s_movk_i32 s2, 0x408
	v_and_b32_e32 v6, 63, v70
	v_ashrrev_i32_e32 v7, 6, v70
	v_lshlrev_b32_e32 v0, 1, v6
	v_pk_add_f32 v[2:3], v[34:35], 1.0 op_sel_hi:[1,0] neg_lo:[1,0] neg_hi:[1,0]
	v_mad_u64_u32 v[10:11], s[6:7], v7, s2, v[0:1]
	v_mul_f32_e32 v1, 0x3fb8aa3b, v1
	v_fma_f32 v8, v2, v8, v34
	v_fma_f32 v9, v3, v9, v35
	v_exp_f32_e32 v1, v1
	v_log_f32_e32 v8, v8
	v_log_f32_e32 v9, v9
	v_lshl_add_u32 v10, v10, 2, 0
	v_add_f32_e32 v1, 1.0, v1
	v_readlane_b32 s0, v254, 42
	ds_write_b64 v10, v[8:9]
	v_rcp_f32_e32 v8, v1
	v_mul_f32_e32 v1, 0x3fb8aa3b, v5
	v_exp_f32_e32 v1, v1
	v_lshl_add_u32 v4, v6, 2, s0
	s_movk_i32 s2, 0x820
	v_and_b32_e32 v11, 0xffff0000, v67
	v_add_f32_e32 v1, 1.0, v1
	v_rcp_f32_e32 v9, v1
	s_movk_i32 s3, 0x900
	v_cmp_lt_u32_e64 s[12:13], 15, v6
	v_pk_mul_f32 v[8:9], v[2:3], v[8:9]
	ds_write_b64 v10, v[8:9] offset:33024
	v_lshlrev_b32_e32 v10, 16, v67
	v_mul_f32_e32 v1, 0xbfb8aa3b, v10
	v_exp_f32_e32 v1, v1
	v_mad_u64_u32 v[8:9], s[6:7], v7, s2, v[4:5]
	v_lshl_or_b32 v5, v7, 3, 1
	v_add_f32_e32 v1, 1.0, v1
	v_rcp_f32_e32 v1, v1
	s_movk_i32 s2, 0x81
	ds_write_b32 v8, v68
	v_fma_f32 v1, v2, v1, v34
	v_mad_u64_u32 v[8:9], s[6:7], v5, s2, v[0:1]
	v_log_f32_e32 v12, v1
	v_lshl_add_u32 v1, v8, 2, 0
	v_mul_f32_e32 v8, 0xbfb8aa3b, v11
	v_exp_f32_e32 v8, v8
	v_mul_f32_e32 v9, 0x3fb8aa3b, v11
	v_exp_f32_e32 v9, v9
	s_movk_i32 s2, 0x104
	v_add_f32_e32 v8, 1.0, v8
	v_rcp_f32_e32 v8, v8
	v_add_f32_e32 v9, 1.0, v9
	v_rcp_f32_e32 v9, v9
	v_mad_u64_u32 v[4:5], s[6:7], v5, s2, v[4:5]
	v_fma_f32 v8, v3, v8, v35
	v_log_f32_e32 v8, v8
	v_lshlrev_b32_e32 v5, 16, v66
	s_movk_i32 s2, 0x204
	ds_write2_b32 v1, v12, v8 offset1:1
	v_mul_f32_e32 v8, 0x3fb8aa3b, v10
	v_exp_f32_e32 v8, v8
	v_add_u32_e32 v10, 0x8100, v1
	v_add_f32_e32 v8, 1.0, v8
	v_rcp_f32_e32 v8, v8
	s_nop 0
	v_pk_mul_f32 v[8:9], v[2:3], v[8:9]
	ds_write2_b32 v10, v8, v9 offset1:1
	v_and_b32_e32 v10, 0xffff0000, v66
	v_mul_f32_e32 v8, 0xbfb8aa3b, v5
	v_mul_f32_e32 v9, 0xbfb8aa3b, v10
	v_exp_f32_e32 v8, v8
	v_exp_f32_e32 v9, v9
	v_mul_f32_e32 v5, 0x3fb8aa3b, v5
	v_exp_f32_e32 v5, v5
	v_add_f32_e32 v8, 1.0, v8
	v_add_f32_e32 v9, 1.0, v9
	v_rcp_f32_e32 v8, v8
	v_rcp_f32_e32 v9, v9
	v_add_f32_e32 v5, 1.0, v5
	v_fma_f32 v8, v2, v8, v34
	v_fma_f32 v9, v3, v9, v35
	v_log_f32_e32 v8, v8
	v_log_f32_e32 v9, v9
	ds_write_b64 v1, v[8:9] offset:516
	v_rcp_f32_e32 v8, v5
	v_mul_f32_e32 v5, 0x3fb8aa3b, v10
	v_exp_f32_e32 v5, v5
	v_add_u32_e32 v10, 0x408, v1
	v_add_f32_e32 v5, 1.0, v5
	v_rcp_f32_e32 v9, v5
	v_lshlrev_b32_e32 v5, 16, v63
	v_pk_mul_f32 v[8:9], v[2:3], v[8:9]
	ds_write_b64 v1, v[8:9] offset:33540
	ds_write2_b32 v4, v64, v65 offset1:65
	v_and_b32_e32 v9, 0xffff0000, v63
	v_mul_f32_e32 v8, 0xbfb8aa3b, v5
	v_mul_f32_e32 v11, 0xbfb8aa3b, v9
	v_exp_f32_e32 v8, v8
	v_exp_f32_e32 v11, v11
	v_mul_f32_e32 v5, 0x3fb8aa3b, v5
	v_mul_f32_e32 v9, 0x3fb8aa3b, v9
	v_add_f32_e32 v8, 1.0, v8
	v_add_f32_e32 v11, 1.0, v11
	v_rcp_f32_e32 v8, v8
	v_rcp_f32_e32 v11, v11
	v_exp_f32_e32 v5, v5
	v_exp_f32_e32 v9, v9
	v_fma_f32 v8, v2, v8, v34
	v_fma_f32 v11, v3, v11, v35
	v_log_f32_e32 v8, v8
	v_log_f32_e32 v11, v11
	v_add_f32_e32 v5, 1.0, v5
	v_add_f32_e32 v9, 1.0, v9
	v_rcp_f32_e32 v9, v9
	ds_write2_b32 v10, v8, v11 offset1:1
	v_rcp_f32_e32 v8, v5
	v_add_u32_e32 v5, 0x8508, v1
	v_and_b32_e32 v10, 0xffff0000, v62
	v_pk_mul_f32 v[8:9], v[2:3], v[8:9]
	ds_write2_b32 v5, v8, v9 offset1:1
	v_lshlrev_b32_e32 v5, 16, v62
	v_mul_f32_e32 v8, 0xbfb8aa3b, v5
	v_mul_f32_e32 v9, 0xbfb8aa3b, v10
	v_exp_f32_e32 v8, v8
	v_exp_f32_e32 v9, v9
	v_mul_f32_e32 v5, 0x3fb8aa3b, v5
	v_exp_f32_e32 v5, v5
	v_add_f32_e32 v8, 1.0, v8
	v_add_f32_e32 v9, 1.0, v9
	v_rcp_f32_e32 v8, v8
	v_rcp_f32_e32 v9, v9
	v_add_f32_e32 v5, 1.0, v5
	v_fma_f32 v8, v2, v8, v34
	v_fma_f32 v9, v3, v9, v35
	v_log_f32_e32 v8, v8
	v_log_f32_e32 v9, v9
	ds_write_b64 v1, v[8:9] offset:1548
	v_rcp_f32_e32 v8, v5
	v_mul_f32_e32 v5, 0x3fb8aa3b, v10
	v_exp_f32_e32 v5, v5
	v_add_u32_e32 v10, 0x810, v1
	v_add_f32_e32 v5, 1.0, v5
	v_rcp_f32_e32 v9, v5
	v_lshlrev_b32_e32 v5, 16, v59
	v_pk_mul_f32 v[8:9], v[2:3], v[8:9]
	ds_write_b64 v1, v[8:9] offset:34572
	ds_write2_b32 v4, v60, v61 offset0:130 offset1:195
	v_and_b32_e32 v9, 0xffff0000, v59
	v_mul_f32_e32 v8, 0xbfb8aa3b, v5
	v_mul_f32_e32 v11, 0xbfb8aa3b, v9
	v_exp_f32_e32 v8, v8
	v_exp_f32_e32 v11, v11
	v_mul_f32_e32 v5, 0x3fb8aa3b, v5
	v_mul_f32_e32 v9, 0x3fb8aa3b, v9
	v_add_f32_e32 v8, 1.0, v8
	v_add_f32_e32 v11, 1.0, v11
	v_rcp_f32_e32 v8, v8
	v_rcp_f32_e32 v11, v11
	v_exp_f32_e32 v5, v5
	v_exp_f32_e32 v9, v9
	v_fma_f32 v8, v2, v8, v34
	v_fma_f32 v11, v3, v11, v35
	v_log_f32_e32 v8, v8
	v_log_f32_e32 v11, v11
	v_add_f32_e32 v5, 1.0, v5
	v_add_f32_e32 v9, 1.0, v9
	v_rcp_f32_e32 v9, v9
	ds_write2_b32 v10, v8, v11 offset1:1
	v_rcp_f32_e32 v8, v5
	v_add_u32_e32 v5, 0x8910, v1
	v_and_b32_e32 v10, 0xffff0000, v58
	v_pk_mul_f32 v[8:9], v[2:3], v[8:9]
	ds_write2_b32 v5, v8, v9 offset1:1
	v_lshlrev_b32_e32 v5, 16, v58
	v_mul_f32_e32 v8, 0xbfb8aa3b, v5
	v_mul_f32_e32 v9, 0xbfb8aa3b, v10
	v_exp_f32_e32 v8, v8
	v_exp_f32_e32 v9, v9
	v_mul_f32_e32 v5, 0x3fb8aa3b, v5
	v_exp_f32_e32 v5, v5
	v_add_f32_e32 v8, 1.0, v8
	v_add_f32_e32 v9, 1.0, v9
	v_rcp_f32_e32 v8, v8
	v_rcp_f32_e32 v9, v9
	v_add_f32_e32 v5, 1.0, v5
	v_fma_f32 v8, v2, v8, v34
	v_fma_f32 v9, v3, v9, v35
	v_log_f32_e32 v8, v8
	v_log_f32_e32 v9, v9
	ds_write_b64 v1, v[8:9] offset:2580
	v_rcp_f32_e32 v8, v5
	v_mul_f32_e32 v5, 0x3fb8aa3b, v10
	v_exp_f32_e32 v5, v5
	v_add_u32_e32 v10, 0xc18, v1
	v_add_f32_e32 v5, 1.0, v5
	v_rcp_f32_e32 v9, v5
	v_add_u32_e32 v5, 0x400, v4
	ds_write2_b32 v5, v55, v57 offset0:4 offset1:69
	v_lshlrev_b32_e32 v5, 16, v56
	v_pk_mul_f32 v[8:9], v[2:3], v[8:9]
	ds_write_b64 v1, v[8:9] offset:35604
	v_and_b32_e32 v9, 0xffff0000, v56
	v_mul_f32_e32 v8, 0xbfb8aa3b, v5
	v_mul_f32_e32 v11, 0xbfb8aa3b, v9
	v_exp_f32_e32 v8, v8
	v_exp_f32_e32 v11, v11
	v_mul_f32_e32 v5, 0x3fb8aa3b, v5
	v_exp_f32_e32 v5, v5
	v_add_f32_e32 v8, 1.0, v8
	v_add_f32_e32 v11, 1.0, v11
	v_rcp_f32_e32 v8, v8
	v_rcp_f32_e32 v11, v11
	v_add_f32_e32 v5, 1.0, v5
	v_add_u32_e32 v1, 0x8d18, v1
	v_fma_f32 v8, v2, v8, v34
	v_fmac_f32_e32 v35, v3, v11
	v_log_f32_e32 v8, v8
	v_log_f32_e32 v11, v35
	ds_write2_b32 v10, v8, v11 offset1:1
	v_rcp_f32_e32 v8, v5
	v_mul_f32_e32 v5, 0x3fb8aa3b, v9
	v_exp_f32_e32 v5, v5
	s_nop 0
	v_add_f32_e32 v5, 1.0, v5
	v_rcp_f32_e32 v9, v5
	s_nop 0
	v_pk_mul_f32 v[2:3], v[2:3], v[8:9]
	ds_write2_b32 v1, v2, v3 offset1:1
	ds_write_b32 v4, v54 offset:1560
	v_and_b32_e32 v1, 0x7f, v70
	v_ashrrev_i32_e32 v3, 3, v70
	v_and_b32_e32 v4, 0x3ffffff0, v3
	v_lshl_add_u32 v2, v1, 2, 0
	v_mad_u64_u32 v[4:5], s[6:7], v4, s2, v[2:3]
	s_waitcnt lgkmcnt(0)
	s_barrier
	ds_read2_b32 v[8:9], v4 offset1:129
	v_or_b32_e32 v3, 15, v3
	v_mad_u64_u32 v[2:3], s[6:7], v3, s2, v[2:3]
	v_readlane_b32 s2, v254, 43
	s_waitcnt lgkmcnt(0)
	v_add_f32_e32 v1, 0, v8
	v_add_f32_e32 v5, v1, v9
	ds_write2_b32 v4, v1, v5 offset1:129
	v_add_u32_e32 v1, 0x400, v4
	ds_read2_b32 v[8:9], v1 offset0:2 offset1:131
	s_waitcnt lgkmcnt(0)
	v_add_f32_e32 v5, v5, v8
	v_add_f32_e32 v10, v5, v9
	ds_write2_b32 v1, v5, v10 offset0:2 offset1:131
	v_add_u32_e32 v1, 0x800, v4
	ds_read2_b32 v[8:9], v1 offset0:4 offset1:133
	s_waitcnt lgkmcnt(0)
	v_add_f32_e32 v5, v10, v8
	v_add_f32_e32 v10, v5, v9
	ds_write2_b32 v1, v5, v10 offset0:4 offset1:133
	v_add_u32_e32 v1, 0xc00, v4
	ds_read2_b32 v[8:9], v1 offset0:6 offset1:135
	s_waitcnt lgkmcnt(0)
	v_add_f32_e32 v5, v10, v8
	v_add_f32_e32 v10, v5, v9
	ds_write2_b32 v1, v5, v10 offset0:6 offset1:135
	v_add_u32_e32 v1, 0x1000, v4
	ds_read2_b32 v[8:9], v1 offset0:8 offset1:137
	s_waitcnt lgkmcnt(0)
	v_add_f32_e32 v5, v10, v8
	v_add_f32_e32 v10, v5, v9
	ds_write2_b32 v1, v5, v10 offset0:8 offset1:137
	v_add_u32_e32 v1, 0x1400, v4
	ds_read2_b32 v[8:9], v1 offset0:10 offset1:139
	s_waitcnt lgkmcnt(0)
	v_add_f32_e32 v5, v10, v8
	v_add_f32_e32 v10, v5, v9
	ds_write2_b32 v1, v5, v10 offset0:10 offset1:139
	v_add_u32_e32 v1, 0x1800, v4
	ds_read2_b32 v[8:9], v1 offset0:12 offset1:141
	s_waitcnt lgkmcnt(0)
	v_add_f32_e32 v5, v10, v8
	v_add_f32_e32 v8, v5, v9
	ds_write2_b32 v1, v5, v8 offset0:12 offset1:141
	ds_read_b32 v1, v4 offset:7224
	s_waitcnt lgkmcnt(0)
	v_add_f32_e32 v1, v8, v1
	ds_write_b32 v4, v1 offset:7224
	ds_read_b32 v3, v2
	v_lshl_add_u32 v4, v70, 2, s51
	s_waitcnt lgkmcnt(0)
	v_add_f32_e32 v1, v1, v3
	ds_write_b32 v2, v1
	ds_write_b32 v4, v1
	v_ashrrev_i32_e32 v1, 31, v70
	v_lshrrev_b32_e32 v1, 26, v1
	v_add_u32_e32 v1, v70, v1
	v_ashrrev_i32_e32 v1, 6, v1
	v_mul_u32_u24_e32 v2, 0x41, v6
	v_lshlrev_b32_e32 v5, 5, v1
	v_lshlrev_b32_e32 v8, 2, v2
	v_add3_u32 v2, s0, v5, v8
	ds_read2_b32 v[2:3], v2 offset1:1
	v_mul_lo_u32 v9, v1, s3
	v_add3_u32 v10, s2, v9, v0
	v_lshl_or_b32 v1, v1, 3, 1
	s_movk_i32 s3, 0x120
	s_waitcnt lgkmcnt(0)
	ds_write_b16 v10, v2
	v_add_u32_e32 v10, s2, v0
	v_add_u32_e32 v9, v10, v9
	v_mul_lo_u32 v1, v1, s3
	ds_write_b16_d16_hi v9, v2 offset:144
	v_add3_u32 v2, s2, v1, v0
	v_add_u32_e32 v9, v10, v1
	ds_write_b16 v2, v3
	ds_write_b16_d16_hi v9, v3 offset:144
	v_add3_u32 v3, s0, v8, v5
	ds_read2_b32 v[0:1], v3 offset0:2 offset1:3
	s_waitcnt lgkmcnt(0)
	ds_write_b16 v2, v0 offset:288
	ds_write_b16_d16_hi v9, v0 offset:432
	ds_write_b16 v2, v1 offset:576
	ds_write_b16_d16_hi v9, v1 offset:720
	ds_read2_b32 v[0:1], v3 offset0:4 offset1:5
	s_waitcnt lgkmcnt(0)
	ds_write_b16 v2, v0 offset:864
	ds_write_b16_d16_hi v9, v0 offset:1008
	ds_write_b16 v2, v1 offset:1152
	ds_write_b16_d16_hi v9, v1 offset:1296
	ds_read2_b32 v[0:1], v3 offset0:6 offset1:7
	s_waitcnt lgkmcnt(0)
	ds_write_b16 v2, v0 offset:1440
	ds_write_b16_d16_hi v9, v0 offset:1584
	ds_write_b16 v2, v1 offset:1728
	ds_write_b16_d16_hi v9, v1 offset:1872
	v_bfe_u32 v0, v70, 4, 2
	v_lshl_add_u32 v5, v7, 2, s51
	s_waitcnt lgkmcnt(0)
	s_barrier
	v_cmp_ne_u32_e64 s[10:11], 1, v0
	v_cmp_eq_u32_e32 vcc, 2, v0
	ds_read2st64_b32 v[0:1], v5 offset0:2 offset1:4
	ds_read_b32 v3, v5 offset:1536
	s_and_saveexec_b64 s[6:7], s[12:13]
	s_xor_b64 s[6:7], exec, s[6:7]
	s_cbranch_execz .LBB0_594
	s_and_saveexec_b64 s[14:15], s[10:11]
	s_xor_b64 s[14:15], exec, s[14:15]
	s_cbranch_execz .LBB0_591
	s_waitcnt lgkmcnt(0)
	v_add_f32_e32 v0, v1, v3
	v_cndmask_b32_e32 v2, v3, v0, vcc

.LBB0_849:
	s_mov_b64 s[10:11], s[62:63]
	s_getreg_b32 s5, hwreg(HW_REG_XCC_ID, 0, 4)
	s_waitcnt vmcnt(0)
	v_readlane_b32 s2, v253, 0
	v_readlane_b32 s3, v253, 1
	s_barrier
	s_and_saveexec_b64 s[6:7], s[2:3]
	v_readlane_b32 s75, v254, 49
	s_movk_i32 s69, 0x189
	v_readlane_b32 s70, v254, 53
	v_readlane_b32 s71, v254, 54
	v_readlane_b32 s73, v254, 56
	v_readlane_b32 s74, v254, 57
	s_movk_i32 s0, 0x4000
	s_mov_b32 s2, 0x10000
	s_mov_b32 s3, 0x18000
	s_cbranch_execz .LBB0_1067
	s_load_dwordx2 s[10:11], s[10:11], 0xc0
	v_readlane_b32 s2, v254, 38
	s_waitcnt expcnt(0) lgkmcnt(0)
	v_mov_b32_e32 v4, s10
	v_mov_b32_e32 v5, s11
	s_and_b32 s5, s5, 15
	v_mov_b32_e32 v0, s2
	ds_read_b32 v2, v0
	v_readlane_b32 s2, v254, 39
	s_waitcnt lgkmcnt(0)
	v_cmp_ne_u32_e32 vcc, 0, v2
	v_mov_b32_e32 v0, s2
	ds_read_b32 v0, v0
	v_readfirstlane_b32 s10, v4
	v_readfirstlane_b32 s11, v5
	s_cbranch_vccnz .LBB0_1031
	s_add_u32 s12, s10, 0x2e4c2a00
	s_addc_u32 s13, s11, 0
	s_add_u32 s14, s10, 0x2e4c2c00
	s_addc_u32 s15, s11, 0
	s_add_u32 s16, s10, 0x2e4c2d00
	s_addc_u32 s17, s11, 0
	s_add_u32 s18, s10, 0x2e4c2e00
	s_addc_u32 s19, s11, 0
	s_add_u32 s20, s10, 0x2e4c2f00
	s_addc_u32 s21, s11, 0
	s_add_u32 s22, s10, 0x2e4c3000
	s_addc_u32 s23, s11, 0
	s_add_u32 s24, s10, 0x2e4c3100
	s_addc_u32 s25, s11, 0
	s_add_u32 s26, s10, 0x2e4c3200
	s_addc_u32 s27, s11, 0
	s_add_u32 s28, s10, 0x2e4c3300
	s_addc_u32 s29, s11, 0
	s_add_u32 s30, s10, 0x2e4c3400
	s_addc_u32 s31, s11, 0
	s_add_u32 s34, s10, 0x2e4c3500
	s_addc_u32 s35, s11, 0
	s_mov_b32 s2, s36
	s_add_u32 s36, s10, 0x2e4c3600
	s_addc_u32 s37, s11, 0
	s_mov_b32 s96, s38
	s_add_u32 s38, s10, 0x2e4c3700
	s_mov_b32 s54, s76
	s_mov_b32 s76, s59
	s_mov_b32 s59, s72
	s_mov_b32 s72, s85
	s_mov_b32 s85, s79
	s_mov_b32 s82, s78
	s_mov_b64 s[78:79], s[8:9]
	s_mov_b32 s8, s61
	s_mov_b32 s61, s60
	s_mov_b32 s60, s39
	s_addc_u32 s39, s11, 0
	s_mov_b32 s9, s40
	s_add_u32 s40, s10, 0x2e4c3800
	s_mov_b32 s69, s70
	s_mov_b32 s70, s74
	s_mov_b32 s74, s73
	s_mov_b32 s73, s71
	s_mov_b32 s71, s41
	s_addc_u32 s41, s11, 0
	s_add_u32 s42, s10, 0x2e4c3900
	s_addc_u32 s43, s11, 0
	s_add_u32 s44, s10, 0x2e4c3a00
	s_addc_u32 s45, s11, 0
	s_add_u32 s46, s10, 0x2e4c3b00
	s_addc_u32 s47, s11, 0
	s_mov_b32 s58, 1
	s_branch .LBB0_1019

.LBB0_870:
	s_mov_b64 s[10:11], s[62:63]
	s_load_dwordx2 s[16:17], s[10:11], 0xc0
	v_mov_b32_e32 v4, v208
	s_and_b32 s10, s21, 0xfffff800
	s_and_b32 s11, s20, 0x7c0
	v_lshlrev_b32_e32 v2, 1, v4
	v_ashrrev_i32_e32 v4, 3, v4
	s_or_b32 s10, s10, s11
	s_and_b32 s12, s5, 0x180
	v_and_b32_e32 v4, -8, v4
	v_and_b32_e32 v6, 0x7e, v2
	s_or_b32 s11, s12, s37
	v_add_u32_e32 v7, s10, v4
	s_add_i32 s10, s12, 0x1500
	s_mov_b64 s[2:3], 0x74c2800
	v_or_b32_e32 v166, s11, v6
	v_ashrrev_i32_e32 v10, 31, v7
	s_lshr_b32 s10, s10, 8
	v_alignbit_b32 v11, v10, v7, 8
	s_addk_i32 s12, 0x1700
	v_mov_b32_e32 v9, v167
	s_mov_b32 s0, 0x7380000
	v_mov_b32_e32 v34, v208
	s_waitcnt lgkmcnt(0)
	v_mov_b32_e32 v0, s16
	v_mov_b32_e32 v1, s17
	v_lshl_add_u64 v[2:3], v[0:1], 0, s[2:3]
	v_lshl_add_u64 v[0:1], v[166:167], 2, v[0:1]
	v_mov_b32_e32 v166, s10
	v_mad_u64_u32 v[4:5], s[10:11], v11, 49, v[166:167]
	s_and_b32 s10, s5, 0x80
	s_nop 0
	v_or_b32_e32 v6, s10, v6
	s_lshr_b32 s10, s12, 8
	v_mov_b32_e32 v8, s10
	v_mad_u32_u24 v5, v10, 49, v5
	v_mad_u64_u32 v[8:9], s[10:11], v11, 49, v[8:9]
	v_lshlrev_b64 v[4:5], 17, v[4:5]
	v_mad_u32_u24 v9, v10, 49, v9
	v_lshl_add_u64 v[4:5], v[2:3], 0, v[4:5]
	v_lshlrev_b32_e32 v166, 1, v6
	v_lshlrev_b32_e32 v6, 9, v7
	v_lshlrev_b64 v[8:9], 17, v[8:9]
	v_lshl_add_u64 v[4:5], v[4:5], 0, v[166:167]
	v_and_b32_e32 v6, 0x1f000, v6
	v_mov_b32_e32 v7, v167
	v_lshl_add_u64 v[2:3], v[2:3], 0, v[8:9]
	v_lshl_add_u64 v[4:5], v[4:5], 0, v[6:7]
	v_lshl_add_u64 v[2:3], v[2:3], 0, v[166:167]
	v_lshl_add_u64 v[2:3], v[2:3], 0, v[6:7]
	global_load_dword v6, v[4:5], off
	global_load_dword v23, v[2:3], off
	global_load_dword v25, v[4:5], off offset:512
	global_load_dword v8, v[2:3], off offset:512
	global_load_dword v22, v[4:5], off offset:1024
	global_load_dword v21, v[2:3], off offset:1024
	global_load_dword v9, v[4:5], off offset:1536
	global_load_dword v18, v[2:3], off offset:1536
	global_load_dword v20, v[4:5], off offset:2048
	global_load_dword v19, v[2:3], off offset:2048
	global_load_dword v17, v[4:5], off offset:2560
	global_load_dword v14, v[2:3], off offset:2560
	global_load_dword v16, v[4:5], off offset:3072
	global_load_dword v15, v[2:3], off offset:3072
	global_load_dword v13, v[4:5], off offset:3584
	global_load_dword v12, v[2:3], off offset:3584
	v_add_co_u32_e32 v0, vcc, s0, v0
	s_mov_b64 s[10:11], s[62:63]
	s_nop 0
	v_addc_co_u32_e32 v1, vcc, 0, v1, vcc
	s_movk_i32 s2, 0x408
	v_readlane_b32 s0, v254, 42
	s_waitcnt vmcnt(15)
	v_lshlrev_b32_e32 v2, 16, v6
	v_mul_f32_e32 v4, 0xbfb8aa3b, v2
	v_mul_f32_e32 v2, 0x3fb8aa3b, v2
	v_exp_f32_e32 v2, v2
	v_and_b32_e32 v3, 0xffff0000, v6
	v_exp_f32_e32 v4, v4
	v_add_f32_e32 v2, 1.0, v2
	v_rcp_f32_e32 v6, v2
	v_mul_f32_e32 v2, 0x3fb8aa3b, v3
	v_exp_f32_e32 v2, v2
	v_add_f32_e32 v4, 1.0, v4
	v_rcp_f32_e32 v26, v4
	v_mul_f32_e32 v4, 0xbfb8aa3b, v3
	v_add_f32_e32 v2, 1.0, v2
	v_rcp_f32_e32 v7, v2
	global_load_dwordx2 v[2:3], v[0:1], off
	v_exp_f32_e32 v4, v4
	global_load_dwordx2 v[32:33], v167, s[10:11] offset:192
	v_add_f32_e32 v4, 1.0, v4
	v_rcp_f32_e32 v27, v4
	v_and_b32_e32 v10, 63, v34
	v_ashrrev_i32_e32 v11, 6, v34
	v_lshlrev_b32_e32 v0, 1, v10
	v_lshl_add_u32 v24, v10, 2, s0
	v_cmp_lt_u32_e64 s[12:13], 15, v10
	s_waitcnt vmcnt(1)
	v_pk_add_f32 v[4:5], v[2:3], 1.0 op_sel_hi:[1,0] neg_lo:[1,0] neg_hi:[1,0]
	s_nop 0
	v_fma_f32 v1, v4, v26, v2
	v_fma_f32 v27, v5, v27, v3
	v_log_f32_e32 v26, v1
	v_log_f32_e32 v27, v27
	v_mad_u64_u32 v[28:29], s[10:11], v11, s2, v[0:1]
	v_lshl_add_u32 v1, v28, 2, 0
	ds_write_b64 v1, v[26:27]
	v_pk_mul_f32 v[6:7], v[4:5], v[6:7]
	v_lshlrev_b32_e32 v26, 16, v25
	ds_write_b64 v1, v[6:7] offset:33024
	v_mul_f32_e32 v1, 0xbfb8aa3b, v26
	v_exp_f32_e32 v1, v1
	s_movk_i32 s2, 0x820
	v_mad_u64_u32 v[6:7], s[10:11], v11, s2, v[24:25]
	v_add_f32_e32 v1, 1.0, v1
	v_rcp_f32_e32 v1, v1
	ds_write_b32 v6, v23
	v_lshl_or_b32 v23, v11, 3, 1
	s_movk_i32 s2, 0x81
	v_fma_f32 v1, v4, v1, v2
	v_and_b32_e32 v25, 0xffff0000, v25
	v_mad_u64_u32 v[6:7], s[10:11], v23, s2, v[0:1]
	v_log_f32_e32 v27, v1
	v_lshl_add_u32 v1, v6, 2, 0
	v_mul_f32_e32 v6, 0xbfb8aa3b, v25
	v_exp_f32_e32 v6, v6
	v_mul_f32_e32 v7, 0x3fb8aa3b, v25
	v_exp_f32_e32 v7, v7
	s_movk_i32 s2, 0x104
	v_add_f32_e32 v6, 1.0, v6
	v_rcp_f32_e32 v6, v6
	v_add_f32_e32 v7, 1.0, v7
	v_rcp_f32_e32 v7, v7
	v_fma_f32 v6, v5, v6, v3
	v_log_f32_e32 v6, v6
	ds_write2_b32 v1, v27, v6 offset1:1
	v_mul_f32_e32 v6, 0x3fb8aa3b, v26
	v_exp_f32_e32 v6, v6
	v_add_u32_e32 v26, 0x8100, v1
	v_add_f32_e32 v6, 1.0, v6
	v_rcp_f32_e32 v6, v6
	s_nop 0
	v_pk_mul_f32 v[6:7], v[4:5], v[6:7]
	ds_write2_b32 v26, v6, v7 offset1:1
	v_mad_u64_u32 v[6:7], s[10:11], v23, s2, v[24:25]
	v_lshlrev_b32_e32 v7, 16, v22
	v_and_b32_e32 v24, 0xffff0000, v22
	v_mul_f32_e32 v22, 0xbfb8aa3b, v7
	v_mul_f32_e32 v23, 0xbfb8aa3b, v24
	v_exp_f32_e32 v22, v22
	v_exp_f32_e32 v23, v23
	v_mul_f32_e32 v7, 0x3fb8aa3b, v7
	v_exp_f32_e32 v7, v7
	v_add_f32_e32 v22, 1.0, v22
	v_add_f32_e32 v23, 1.0, v23
	v_rcp_f32_e32 v22, v22
	v_rcp_f32_e32 v23, v23
	v_add_f32_e32 v7, 1.0, v7
	s_movk_i32 s2, 0x204
	v_fma_f32 v22, v4, v22, v2
	v_fma_f32 v23, v5, v23, v3
	v_log_f32_e32 v22, v22
	v_log_f32_e32 v23, v23
	ds_write_b64 v1, v[22:23] offset:516
	v_rcp_f32_e32 v22, v7
	v_mul_f32_e32 v7, 0x3fb8aa3b, v24
	v_exp_f32_e32 v7, v7
	s_nop 0
	v_add_f32_e32 v7, 1.0, v7
	v_rcp_f32_e32 v23, v7
	v_lshlrev_b32_e32 v7, 16, v9
	v_and_b32_e32 v9, 0xffff0000, v9
	v_pk_mul_f32 v[22:23], v[4:5], v[22:23]
	ds_write_b64 v1, v[22:23] offset:33540
	ds_write2_b32 v6, v8, v21 offset1:65
	v_mul_f32_e32 v8, 0xbfb8aa3b, v7
	v_mul_f32_e32 v22, 0xbfb8aa3b, v9
	v_exp_f32_e32 v8, v8
	v_exp_f32_e32 v22, v22
	v_mul_f32_e32 v7, 0x3fb8aa3b, v7
	v_mul_f32_e32 v9, 0x3fb8aa3b, v9
	v_add_f32_e32 v8, 1.0, v8
	v_add_f32_e32 v22, 1.0, v22
	v_rcp_f32_e32 v8, v8
	v_rcp_f32_e32 v22, v22
	v_exp_f32_e32 v7, v7
	v_exp_f32_e32 v9, v9
	v_fma_f32 v8, v4, v8, v2
	v_fma_f32 v22, v5, v22, v3
	v_log_f32_e32 v8, v8
	v_log_f32_e32 v22, v22
	v_add_u32_e32 v21, 0x408, v1
	v_add_f32_e32 v7, 1.0, v7
	v_add_f32_e32 v9, 1.0, v9
	ds_write2_b32 v21, v8, v22 offset1:1
	v_rcp_f32_e32 v8, v7
	v_rcp_f32_e32 v9, v9
	v_add_u32_e32 v7, 0x8508, v1
	v_pk_mul_f32 v[8:9], v[4:5], v[8:9]
	ds_write2_b32 v7, v8, v9 offset1:1
	v_lshlrev_b32_e32 v7, 16, v20
	v_and_b32_e32 v20, 0xffff0000, v20
	v_mul_f32_e32 v8, 0xbfb8aa3b, v7
	v_mul_f32_e32 v9, 0xbfb8aa3b, v20
	v_exp_f32_e32 v8, v8
	v_exp_f32_e32 v9, v9
	v_mul_f32_e32 v7, 0x3fb8aa3b, v7
	v_exp_f32_e32 v7, v7
	v_add_f32_e32 v8, 1.0, v8
	v_add_f32_e32 v9, 1.0, v9
	v_rcp_f32_e32 v8, v8
	v_rcp_f32_e32 v9, v9
	v_add_f32_e32 v7, 1.0, v7
	v_fma_f32 v8, v4, v8, v2
	v_fma_f32 v9, v5, v9, v3
	v_log_f32_e32 v8, v8
	v_log_f32_e32 v9, v9
	ds_write_b64 v1, v[8:9] offset:1548
	v_rcp_f32_e32 v8, v7
	v_mul_f32_e32 v7, 0x3fb8aa3b, v20
	v_exp_f32_e32 v7, v7
	s_nop 0
	v_add_f32_e32 v7, 1.0, v7
	v_rcp_f32_e32 v9, v7
	v_lshlrev_b32_e32 v7, 16, v17
	v_pk_mul_f32 v[8:9], v[4:5], v[8:9]
	ds_write_b64 v1, v[8:9] offset:34572
	ds_write2_b32 v6, v18, v19 offset0:130 offset1:195
	v_and_b32_e32 v9, 0xffff0000, v17
	v_mul_f32_e32 v8, 0xbfb8aa3b, v7
	v_mul_f32_e32 v18, 0xbfb8aa3b, v9
	v_exp_f32_e32 v8, v8
	v_exp_f32_e32 v18, v18
	v_mul_f32_e32 v7, 0x3fb8aa3b, v7
	v_mul_f32_e32 v9, 0x3fb8aa3b, v9
	v_add_f32_e32 v8, 1.0, v8
	v_add_f32_e32 v18, 1.0, v18
	v_rcp_f32_e32 v8, v8
	v_rcp_f32_e32 v18, v18
	v_exp_f32_e32 v7, v7
	v_exp_f32_e32 v9, v9
	v_fma_f32 v8, v4, v8, v2
	v_fma_f32 v18, v5, v18, v3
	v_log_f32_e32 v8, v8
	v_log_f32_e32 v18, v18
	v_add_u32_e32 v17, 0x810, v1
	v_add_f32_e32 v7, 1.0, v7
	v_add_f32_e32 v9, 1.0, v9
	ds_write2_b32 v17, v8, v18 offset1:1
	v_rcp_f32_e32 v8, v7
	v_rcp_f32_e32 v9, v9
	v_add_u32_e32 v7, 0x8910, v1
	v_pk_mul_f32 v[8:9], v[4:5], v[8:9]
	ds_write2_b32 v7, v8, v9 offset1:1
	v_lshlrev_b32_e32 v7, 16, v16
	v_and_b32_e32 v16, 0xffff0000, v16
	v_mul_f32_e32 v8, 0xbfb8aa3b, v7
	v_mul_f32_e32 v9, 0xbfb8aa3b, v16
	v_exp_f32_e32 v8, v8
	v_exp_f32_e32 v9, v9
	v_mul_f32_e32 v7, 0x3fb8aa3b, v7
	v_exp_f32_e32 v7, v7
	v_add_f32_e32 v8, 1.0, v8
	v_add_f32_e32 v9, 1.0, v9
	v_rcp_f32_e32 v8, v8
	v_rcp_f32_e32 v9, v9
	v_add_f32_e32 v7, 1.0, v7
	v_fma_f32 v8, v4, v8, v2
	v_fma_f32 v9, v5, v9, v3
	v_log_f32_e32 v8, v8
	v_log_f32_e32 v9, v9
	ds_write_b64 v1, v[8:9] offset:2580
	v_rcp_f32_e32 v8, v7
	v_mul_f32_e32 v7, 0x3fb8aa3b, v16
	v_exp_f32_e32 v7, v7
	s_nop 0
	v_add_f32_e32 v7, 1.0, v7
	v_rcp_f32_e32 v9, v7
	v_add_u32_e32 v7, 0x400, v6
	ds_write2_b32 v7, v14, v15 offset0:4 offset1:69
	v_lshlrev_b32_e32 v7, 16, v13
	v_pk_mul_f32 v[8:9], v[4:5], v[8:9]
	ds_write_b64 v1, v[8:9] offset:35604
	v_and_b32_e32 v8, 0xffff0000, v13
	v_mul_f32_e32 v9, 0xbfb8aa3b, v7
	v_mul_f32_e32 v13, 0xbfb8aa3b, v8
	v_exp_f32_e32 v9, v9
	v_exp_f32_e32 v13, v13
	v_add_f32_e32 v9, 1.0, v9
	v_add_f32_e32 v13, 1.0, v13
	v_rcp_f32_e32 v9, v9
	v_rcp_f32_e32 v13, v13
	v_fma_f32 v2, v4, v9, v2
	v_fmac_f32_e32 v3, v5, v13
	v_log_f32_e32 v2, v2
	v_log_f32_e32 v3, v3
	v_add_u32_e32 v9, 0xc18, v1
	v_add_u32_e32 v1, 0x8d18, v1
	ds_write2_b32 v9, v2, v3 offset1:1
	v_mul_f32_e32 v2, 0x3fb8aa3b, v7
	v_mul_f32_e32 v3, 0x3fb8aa3b, v8
	v_exp_f32_e32 v2, v2
	v_exp_f32_e32 v3, v3
	v_add_f32_e32 v2, 1.0, v2
	v_add_f32_e32 v3, 1.0, v3
	v_rcp_f32_e32 v2, v2
	v_rcp_f32_e32 v3, v3
	s_nop 0
	v_pk_mul_f32 v[2:3], v[4:5], v[2:3]
	ds_write2_b32 v1, v2, v3 offset1:1
	ds_write_b32 v6, v12 offset:1560
	v_and_b32_e32 v1, 0x7f, v34
	v_ashrrev_i32_e32 v3, 3, v34
	v_and_b32_e32 v4, 0x3ffffff0, v3
	v_lshl_add_u32 v2, v1, 2, 0
	v_mad_u64_u32 v[4:5], s[10:11], v4, s2, v[2:3]
	s_waitcnt lgkmcnt(0)
	s_barrier
	ds_read2_b32 v[6:7], v4 offset1:129
	v_or_b32_e32 v3, 15, v3
	v_mad_u64_u32 v[2:3], s[10:11], v3, s2, v[2:3]
	s_movk_i32 s2, 0x900
	s_waitcnt lgkmcnt(0)
	v_add_f32_e32 v1, 0, v6
	v_add_f32_e32 v5, v1, v7
	ds_write2_b32 v4, v1, v5 offset1:129
	v_add_u32_e32 v1, 0x400, v4
	ds_read2_b32 v[6:7], v1 offset0:2 offset1:131
	s_waitcnt lgkmcnt(0)
	v_add_f32_e32 v5, v5, v6
	v_add_f32_e32 v8, v5, v7
	ds_write2_b32 v1, v5, v8 offset0:2 offset1:131
	v_add_u32_e32 v1, 0x800, v4
	ds_read2_b32 v[6:7], v1 offset0:4 offset1:133
	s_waitcnt lgkmcnt(0)
	v_add_f32_e32 v5, v8, v6
	v_add_f32_e32 v8, v5, v7
	ds_write2_b32 v1, v5, v8 offset0:4 offset1:133
	v_add_u32_e32 v1, 0xc00, v4
	ds_read2_b32 v[6:7], v1 offset0:6 offset1:135
	s_waitcnt lgkmcnt(0)
	v_add_f32_e32 v5, v8, v6
	v_add_f32_e32 v8, v5, v7
	ds_write2_b32 v1, v5, v8 offset0:6 offset1:135
	v_add_u32_e32 v1, 0x1000, v4
	ds_read2_b32 v[6:7], v1 offset0:8 offset1:137
	s_waitcnt lgkmcnt(0)
	v_add_f32_e32 v5, v8, v6
	v_add_f32_e32 v8, v5, v7
	ds_write2_b32 v1, v5, v8 offset0:8 offset1:137
	v_add_u32_e32 v1, 0x1400, v4
	ds_read2_b32 v[6:7], v1 offset0:10 offset1:139
	s_waitcnt lgkmcnt(0)
	v_add_f32_e32 v5, v8, v6
	v_add_f32_e32 v8, v5, v7
	ds_write2_b32 v1, v5, v8 offset0:10 offset1:139
	v_add_u32_e32 v1, 0x1800, v4
	ds_read2_b32 v[6:7], v1 offset0:12 offset1:141
	s_waitcnt lgkmcnt(0)
	v_add_f32_e32 v5, v8, v6
	v_add_f32_e32 v6, v5, v7
	ds_write2_b32 v1, v5, v6 offset0:12 offset1:141
	ds_read_b32 v1, v4 offset:7224
	s_waitcnt lgkmcnt(0)
	v_add_f32_e32 v1, v6, v1
	ds_write_b32 v4, v1 offset:7224
	ds_read_b32 v3, v2
	v_lshl_add_u32 v4, v34, 2, s51
	s_waitcnt lgkmcnt(0)
	v_add_f32_e32 v1, v1, v3
	ds_write_b32 v2, v1
	ds_write_b32 v4, v1
	v_ashrrev_i32_e32 v1, 31, v34
	v_lshrrev_b32_e32 v1, 26, v1
	v_add_u32_e32 v1, v34, v1
	v_ashrrev_i32_e32 v1, 6, v1
	v_mul_u32_u24_e32 v2, 0x41, v10
	v_lshlrev_b32_e32 v5, 5, v1
	v_lshlrev_b32_e32 v6, 2, v2
	v_add3_u32 v2, s0, v5, v6
	ds_read2_b32 v[2:3], v2 offset1:1
	v_mul_lo_u32 v7, v1, s2
	v_add3_u32 v8, s24, v7, v0
	v_lshl_or_b32 v1, v1, 3, 1
	s_movk_i32 s2, 0x120
	s_waitcnt lgkmcnt(0)
	ds_write_b16 v8, v2
	v_add_u32_e32 v8, s24, v0
	v_add_u32_e32 v7, v8, v7
	v_mul_lo_u32 v1, v1, s2
	ds_write_b16_d16_hi v7, v2 offset:144
	v_add3_u32 v2, s24, v1, v0
	v_add_u32_e32 v7, v8, v1
	ds_write_b16 v2, v3
	ds_write_b16_d16_hi v7, v3 offset:144
	v_add3_u32 v3, s0, v6, v5
	ds_read2_b32 v[0:1], v3 offset0:2 offset1:3
	s_waitcnt lgkmcnt(0)
	ds_write_b16 v2, v0 offset:288
	ds_write_b16_d16_hi v7, v0 offset:432
	ds_write_b16 v2, v1 offset:576
	ds_write_b16_d16_hi v7, v1 offset:720
	ds_read2_b32 v[0:1], v3 offset0:4 offset1:5
	s_waitcnt lgkmcnt(0)
	ds_write_b16 v2, v0 offset:864
	ds_write_b16_d16_hi v7, v0 offset:1008
	ds_write_b16 v2, v1 offset:1152
	ds_write_b16_d16_hi v7, v1 offset:1296
	ds_read2_b32 v[0:1], v3 offset0:6 offset1:7
	s_waitcnt lgkmcnt(0)
	ds_write_b16 v2, v0 offset:1440
	ds_write_b16_d16_hi v7, v0 offset:1584
	ds_write_b16 v2, v1 offset:1728
	ds_write_b16_d16_hi v7, v1 offset:1872
	v_bfe_u32 v0, v34, 4, 2
	v_lshl_add_u32 v5, v11, 2, s51
	s_waitcnt lgkmcnt(0)
	s_barrier
	v_cmp_ne_u32_e64 s[10:11], 1, v0
	v_cmp_eq_u32_e32 vcc, 2, v0
	ds_read2st64_b32 v[0:1], v5 offset0:2 offset1:4
	ds_read_b32 v3, v5 offset:1536
	s_and_saveexec_b64 s[16:17], s[12:13]
	s_xor_b64 s[16:17], exec, s[16:17]
	s_mov_b32 s2, s24
	s_cbranch_execz .LBB0_876
	s_and_saveexec_b64 s[18:19], s[10:11]
	s_xor_b64 s[18:19], exec, s[18:19]
	s_cbranch_execz .LBB0_873
	s_waitcnt lgkmcnt(0)
	v_add_f32_e32 v0, v1, v3
	v_cndmask_b32_e32 v2, v3, v0, vcc

.LBB0_1067:
	s_or_b64 exec, exec, s[6:7]
	s_mov_b64 s[6:7], s[62:63]
	s_waitcnt lgkmcnt(0)
	s_barrier
	s_load_dwordx2 s[10:11], s[6:7], 0xc0
	v_mov_b32_e32 v6, v208
	s_mov_b64 s[6:7], 0x73c2000
	v_add_u32_e32 v8, s61, v6
	v_cmp_gt_i32_e32 vcc, s84, v8
	s_waitcnt lgkmcnt(0)
	v_mov_b32_e32 v2, s10
	v_mov_b32_e32 v3, s11
	v_lshl_add_u64 v[0:1], v[2:3], 0, s[6:7]
	s_and_saveexec_b64 s[6:7], vcc
	s_mov_b32 s5, 0x30000
	s_mov_b32 s12, 0x38000
	s_mov_b32 s13, 0x40000
	s_mov_b32 s14, 0x1ffff
	s_cbranch_execz .LBB0_1070
	s_mov_b64 s[10:11], 0x244c2800
	v_lshl_add_u64 v[4:5], v[2:3], 0, s[10:11]
	s_mov_b64 s[10:11], 0
	v_mov_b32_e32 v7, v8

.LBB0_1073:
	s_or_b64 exec, exec, s[6:7]
	s_mov_b64 s[10:11], s[62:63]
	v_mov_b32_e32 v0, v208
	s_nop 0
	v_add_u32_e32 v144, s61, v0
	v_cmp_gt_i32_e32 vcc, s84, v144
	s_and_saveexec_b64 s[6:7], vcc
	s_cbranch_execz .LBB0_1078
	s_load_dwordx2 s[14:15], s[10:11], 0xc0
	s_mov_b64 s[10:11], 0x73c2800
	s_mov_b64 s[12:13], 0
	s_waitcnt lgkmcnt(0)
	v_mov_b32_e32 v0, s14
	v_mov_b32_e32 v1, s15
	v_lshl_add_u64 v[64:65], v[0:1], 0, s[10:11]
	s_mov_b64 s[10:11], 0x264c2800
	v_lshl_add_u64 v[66:67], v[0:1], 0, s[10:11]

.LBB0_1078:
	s_or_b64 exec, exec, s[6:7]
	s_mov_b64 s[10:11], s[62:63]
	v_mov_b32_e32 v0, v208
	s_nop 0
	v_add_u32_e32 v6, s61, v0
	v_cmp_gt_i32_e32 vcc, s91, v6
	s_and_saveexec_b64 s[6:7], vcc
	s_cbranch_execz .LBB0_1081
	s_load_dwordx2 s[12:13], s[10:11], 0xc0
	v_and_b32_e32 v7, 0x1ff, v0
	v_lshlrev_b32_e32 v166, 2, v7
	s_mov_b64 s[2:3], 0x7442800
	s_mov_b64 s[10:11], 0
	s_waitcnt lgkmcnt(0)
	v_mov_b32_e32 v2, s12
	v_mov_b32_e32 v3, s13
	v_lshl_add_u64 v[0:1], v[2:3], 0, s[2:3]
	v_lshl_add_u64 v[2:3], v[2:3], 0, v[166:167]
	s_mov_b64 s[2:3], 0x2a4c2800
	v_lshl_add_u64 v[2:3], v[2:3], 0, s[2:3]

.LBB0_1081:
	s_or_b64 exec, exec, s[6:7]
	s_mov_b64 s[10:11], s[62:63]
	s_getreg_b32 s5, hwreg(HW_REG_XCC_ID, 0, 4)
	s_waitcnt vmcnt(0)
	v_readlane_b32 s2, v253, 0
	v_readlane_b32 s3, v253, 1
	s_barrier
	s_and_saveexec_b64 s[6:7], s[2:3]
	s_cbranch_execz .LBB0_1134
	s_load_dwordx2 s[10:11], s[10:11], 0xc0
	v_readlane_b32 s0, v254, 38
	s_waitcnt expcnt(0) lgkmcnt(0)
	v_mov_b32_e32 v4, s10
	v_mov_b32_e32 v5, s11
	s_and_b32 s5, s5, 15
	v_mov_b32_e32 v0, s0
	ds_read_b32 v2, v0
	v_readlane_b32 s0, v254, 39
	s_waitcnt lgkmcnt(0)
	v_cmp_ne_u32_e32 vcc, 0, v2
	v_mov_b32_e32 v0, s0
	ds_read_b32 v0, v0
	v_readfirstlane_b32 s10, v4
	v_readfirstlane_b32 s11, v5
	s_cbranch_vccnz .LBB0_1098
	s_add_u32 s12, s10, 0x2e4c2a00
	s_addc_u32 s13, s11, 0
	s_add_u32 s14, s10, 0x2e4c2c00
	s_addc_u32 s15, s11, 0
	s_add_u32 s16, s10, 0x2e4c2d00
	s_addc_u32 s17, s11, 0
	s_add_u32 s18, s10, 0x2e4c2e00
	s_addc_u32 s19, s11, 0
	s_add_u32 s20, s10, 0x2e4c2f00
	s_addc_u32 s21, s11, 0
	s_add_u32 s22, s10, 0x2e4c3000
	s_addc_u32 s23, s11, 0
	s_add_u32 s24, s10, 0x2e4c3100
	s_addc_u32 s25, s11, 0
	s_add_u32 s26, s10, 0x2e4c3200
	s_addc_u32 s27, s11, 0
	s_add_u32 s28, s10, 0x2e4c3300
	s_addc_u32 s29, s11, 0
	s_add_u32 s30, s10, 0x2e4c3400
	s_addc_u32 s31, s11, 0
	s_add_u32 s34, s10, 0x2e4c3500
	s_addc_u32 s35, s11, 0
	s_mov_b32 s0, s36
	s_add_u32 s36, s10, 0x2e4c3600
	s_addc_u32 s37, s11, 0
	s_mov_b32 s2, s38
	s_add_u32 s38, s10, 0x2e4c3700
	s_mov_b32 s3, s39
	s_addc_u32 s39, s11, 0
	s_mov_b32 s54, s76
	s_mov_b32 s76, s59
	s_mov_b32 s59, s72
	s_mov_b32 s72, s85
	s_mov_b32 s85, s79
	s_mov_b32 s82, s78
	s_mov_b64 s[78:79], s[8:9]
	s_mov_b32 s8, s40
	s_add_u32 s40, s10, 0x2e4c3800
	s_mov_b32 s9, s41
	s_addc_u32 s41, s11, 0
	s_add_u32 s42, s10, 0x2e4c3900
	s_addc_u32 s43, s11, 0
	s_add_u32 s44, s10, 0x2e4c3a00
	s_addc_u32 s45, s11, 0
	s_add_u32 s46, s10, 0x2e4c3b00
	s_addc_u32 s47, s11, 0
	s_mov_b32 s58, 1
	s_branch .LBB0_1086

.LBB0_1138:
	s_and_b64 vcc, exec, s[6:7]
	s_cbranch_vccz .LBB0_1652
	s_mov_b64 s[6:7], s[62:63]
	s_load_dwordx2 s[6:7], s[6:7], 0xc0
	v_mov_b32_e32 v2, v208
	s_mov_b64 s[2:3], 0x74c2800
	v_lshlrev_b32_e32 v3, 1, v2
	v_and_b32_e32 v3, 0x7e, v3
	v_or_b32_e32 v166, s41, v3
	v_readlane_b32 s0, v253, 16
	v_readlane_b32 s12, v253, 62
	v_readlane_b32 s13, v253, 63
	s_mov_b32 s24, s60
	v_readlane_b32 s25, v253, 57
	s_mov_b32 s26, s64
	s_waitcnt lgkmcnt(0)
	v_mov_b32_e32 v0, s6
	v_mov_b32_e32 v1, s7
	v_lshl_add_u64 v[4:5], v[0:1], 0, s[2:3]
	v_lshl_add_u64 v[0:1], v[166:167], 2, v[0:1]
	v_add_co_u32_e32 v0, vcc, 0x7380000, v0
	v_readlane_b32 s2, v254, 4
	s_nop 0
	v_addc_co_u32_e32 v1, vcc, 0, v1, vcc
	global_load_dwordx2 v[72:73], v[0:1], off
	v_ashrrev_i32_e32 v0, 3, v2
	v_and_b32_e32 v0, -8, v0
	v_add_u32_e32 v2, s0, v0
	v_ashrrev_i32_e32 v12, 31, v2
	v_alignbit_b32 v10, v12, v2, 8
	v_readlane_b32 s3, v254, 5
	v_readlane_b32 s0, v253, 18
	v_lshlrev_b32_e32 v2, 9, v2
	v_mad_u64_u32 v[0:1], s[6:7], v10, 49, s[2:3]
	v_readlane_b32 s2, v254, 20
	v_readlane_b32 s3, v254, 21
	v_mad_u32_u24 v1, v12, 49, v1
	v_or_b32_e32 v3, s0, v3
	v_mad_u64_u32 v[6:7], s[6:7], v10, 49, s[2:3]
	v_readlane_b32 s2, v254, 22
	v_readlane_b32 s3, v254, 23
	v_lshlrev_b64 v[0:1], 17, v[0:1]
	v_mad_u32_u24 v7, v12, 49, v7
	v_mad_u64_u32 v[8:9], s[6:7], v10, 49, s[2:3]
	v_readlane_b32 s2, v254, 6
	v_readlane_b32 s3, v254, 7
	v_mad_u32_u24 v9, v12, 49, v9
	v_lshl_add_u64 v[0:1], v[4:5], 0, v[0:1]
	v_mad_u64_u32 v[10:11], s[6:7], v10, 49, s[2:3]
	v_mad_u32_u24 v11, v12, 49, v11
	v_lshlrev_b32_e32 v166, 1, v3
	v_lshlrev_b64 v[6:7], 17, v[6:7]
	v_lshlrev_b64 v[8:9], 17, v[8:9]
	v_lshlrev_b64 v[10:11], 17, v[10:11]
	v_lshl_add_u64 v[0:1], v[0:1], 0, v[166:167]
	v_and_b32_e32 v2, 0x1f000, v2
	v_mov_b32_e32 v3, v167
	v_lshl_add_u64 v[6:7], v[4:5], 0, v[6:7]
	v_lshl_add_u64 v[8:9], v[4:5], 0, v[8:9]
	v_lshl_add_u64 v[4:5], v[4:5], 0, v[10:11]
	v_lshl_add_u64 v[0:1], v[0:1], 0, v[2:3]
	v_lshl_add_u64 v[6:7], v[6:7], 0, v[166:167]
	v_lshl_add_u64 v[8:9], v[8:9], 0, v[166:167]
	v_lshl_add_u64 v[4:5], v[4:5], 0, v[166:167]
	v_lshl_add_u64 v[6:7], v[6:7], 0, v[2:3]
	v_lshl_add_u64 v[8:9], v[8:9], 0, v[2:3]
	v_lshl_add_u64 v[2:3], v[4:5], 0, v[2:3]
	global_load_dword v160, v[0:1], off
	global_load_dword v144, v[6:7], off
	global_load_dword v136, v[8:9], off
	global_load_dword v158, v[2:3], off
	global_load_dword v159, v[0:1], off offset:512
	global_load_dword v143, v[6:7], off offset:512
	global_load_dword v135, v[8:9], off offset:512
	global_load_dword v151, v[2:3], off offset:512
	global_load_dword v157, v[0:1], off offset:1024
	global_load_dword v142, v[6:7], off offset:1024
	global_load_dword v134, v[8:9], off offset:1024
	global_load_dword v154, v[2:3], off offset:1024
	global_load_dword v156, v[0:1], off offset:1536
	global_load_dword v141, v[6:7], off offset:1536
	global_load_dword v133, v[8:9], off offset:1536
	global_load_dword v147, v[2:3], off offset:1536
	global_load_dword v155, v[0:1], off offset:2048
	global_load_dword v140, v[6:7], off offset:2048
	global_load_dword v132, v[8:9], off offset:2048
	global_load_dword v148, v[2:3], off offset:2048
	global_load_dword v152, v[0:1], off offset:2560
	global_load_dword v139, v[6:7], off offset:2560
	global_load_dword v131, v[8:9], off offset:2560
	global_load_dword v145, v[2:3], off offset:2560
	global_load_dword v150, v[0:1], off offset:3072
	global_load_dword v138, v[6:7], off offset:3072
	global_load_dword v130, v[8:9], off offset:3072
	global_load_dword v146, v[2:3], off offset:3072
	global_load_dword v149, v[0:1], off offset:3584
	global_load_dword v137, v[6:7], off offset:3584
	global_load_dword v85, v[8:9], off offset:3584
	global_load_dword v153, v[2:3], off offset:3584
	s_and_b64 vcc, exec, s[8:9]
	s_cbranch_vccz .LBB0_1307

.LBB0_1238:
	s_mov_b64 s[10:11], s[62:63]
	s_load_dwordx2 s[24:25], s[10:11], 0xc0
	v_mov_b32_e32 v2, v208
	s_and_b32 s10, s27, 0xfffff800
	s_and_b32 s11, s26, 0x7c0
	v_lshlrev_b32_e32 v6, 1, v2
	v_ashrrev_i32_e32 v2, 3, v2
	s_and_b32 s30, s5, 0x180
	s_or_b32 s29, s10, s11
	v_and_b32_e32 v2, -8, v2
	s_add_i32 s10, s30, 0x1500
	s_add_i32 s11, s30, 0x1700
	v_add_u32_e32 v2, s29, v2
	s_and_b32 s12, s5, 0x80
	s_or_b32 s31, s30, s37
	s_lshr_b32 s13, s10, 8
	s_lshr_b32 s10, s11, 8
	v_and_b32_e32 v6, 0x7e, v6
	v_ashrrev_i32_e32 v14, 31, v2
	v_mov_b32_e32 v5, v167
	v_mov_b32_e32 v4, s10
	v_or_b32_e32 v166, s31, v6
	v_or_b32_e32 v10, s12, v6
	v_lshlrev_b32_e32 v6, 9, v2
	v_alignbit_b32 v15, v14, v2, 8
	s_mov_b64 s[2:3], 0x74c2800
	v_and_b32_e32 v2, 0x1f000, v6
	v_mad_u64_u32 v[4:5], s[10:11], v15, 49, v[4:5]
	v_mad_u32_u24 v5, v14, 49, v5
	v_lshlrev_b64 v[4:5], 17, v[4:5]
	s_mov_b32 s0, 0x7380000
	v_mov_b32_e32 v3, v167
	s_add_i32 s12, s30, 0x1300
	s_lshr_b32 s12, s12, 8
	v_mov_b32_e32 v13, v167
	v_mov_b32_e32 v39, v208
	s_waitcnt lgkmcnt(0)
	v_mov_b32_e32 v0, s24
	v_mov_b32_e32 v1, s25
	v_lshl_add_u64 v[6:7], v[0:1], 0, s[2:3]
	v_lshl_add_u64 v[0:1], v[166:167], 2, v[0:1]
	v_mov_b32_e32 v166, s13
	v_mad_u64_u32 v[8:9], s[10:11], v15, 49, v[166:167]
	v_mad_u32_u24 v9, v14, 49, v9
	v_lshlrev_b32_e32 v166, 1, v10
	v_lshl_add_u64 v[4:5], v[6:7], 0, v[4:5]
	v_lshlrev_b64 v[8:9], 17, v[8:9]
	v_add_co_u32_e32 v0, vcc, s0, v0
	v_lshl_add_u64 v[4:5], v[4:5], 0, v[166:167]
	v_lshl_add_u64 v[8:9], v[6:7], 0, v[8:9]
	v_addc_co_u32_e32 v1, vcc, 0, v1, vcc
	v_lshl_add_u64 v[4:5], v[4:5], 0, v[2:3]
	v_lshl_add_u64 v[8:9], v[8:9], 0, v[166:167]
	global_load_dwordx2 v[0:1], v[0:1], off
	v_lshl_add_u64 v[10:11], v[8:9], 0, v[2:3]
	global_load_dword v20, v[4:5], off
	global_load_dword v27, v[10:11], off
	global_load_dword v30, v[10:11], off offset:512
	global_load_dword v31, v[10:11], off offset:1024
	global_load_dword v32, v[10:11], off offset:1536
	s_add_i32 s13, s30, 0x1900
	v_mov_b32_e32 v9, v167
	s_lshr_b32 s13, s13, 8
	v_mov_b32_e32 v8, s12
	v_mov_b32_e32 v12, s13
	v_mad_u64_u32 v[8:9], s[12:13], v15, 49, v[8:9]
	v_mad_u64_u32 v[12:13], s[12:13], v15, 49, v[12:13]
	v_mad_u32_u24 v9, v14, 49, v9
	v_mad_u32_u24 v13, v14, 49, v13
	v_lshlrev_b64 v[8:9], 17, v[8:9]
	v_lshlrev_b64 v[12:13], 17, v[12:13]
	v_lshl_add_u64 v[8:9], v[6:7], 0, v[8:9]
	v_lshl_add_u64 v[6:7], v[6:7], 0, v[12:13]
	v_lshl_add_u64 v[8:9], v[8:9], 0, v[166:167]
	v_lshl_add_u64 v[6:7], v[6:7], 0, v[166:167]
	v_lshl_add_u64 v[12:13], v[8:9], 0, v[2:3]
	v_lshl_add_u64 v[2:3], v[6:7], 0, v[2:3]
	global_load_dword v8, v[12:13], off
	global_load_dword v69, v[12:13], off offset:512
	global_load_dword v9, v[12:13], off offset:1024
	global_load_dword v60, v[12:13], off offset:1536
	global_load_dword v56, v[12:13], off offset:2048
	global_load_dword v51, v[12:13], off offset:2560
	global_load_dword v42, v[12:13], off offset:3072
	global_load_dword v41, v[12:13], off offset:3584
	global_load_dword v37, v[2:3], off
	global_load_dword v34, v[2:3], off offset:512
	global_load_dword v26, v[2:3], off offset:1024
	global_load_dword v25, v[2:3], off offset:1536
	global_load_dword v24, v[2:3], off offset:2048
	global_load_dword v23, v[2:3], off offset:2560
	global_load_dword v22, v[2:3], off offset:3072
	global_load_dword v21, v[2:3], off offset:3584
	global_load_dword v33, v[4:5], off offset:512
	global_load_dword v43, v[4:5], off offset:1024
	global_load_dword v44, v[4:5], off offset:1536
	global_load_dword v45, v[4:5], off offset:2048
	global_load_dword v46, v[4:5], off offset:2560
	global_load_dword v47, v[4:5], off offset:3072
	global_load_dword v48, v[4:5], off offset:3584
	global_load_dword v49, v[10:11], off offset:2048
	global_load_dword v50, v[10:11], off offset:2560
	global_load_dword v52, v[10:11], off offset:3072
	global_load_dword v73, v[10:11], off offset:3584
	s_mov_b64 s[10:11], s[62:63]
	global_load_dwordx2 v[18:19], v167, s[10:11] offset:136
	global_load_dwordx2 v[16:17], v167, s[10:11] offset:192
	s_movk_i32 s0, 0x820
	v_and_b32_e32 v40, 63, v39
	v_ashrrev_i32_e32 v35, 6, v39
	v_lshlrev_b32_e32 v75, 2, v40
	v_lshlrev_b32_e32 v38, 3, v35
	v_add_u32_e32 v2, s14, v75
	v_or_b32_e32 v29, 1, v38
	v_mad_u64_u32 v[6:7], s[10:11], v35, s0, v[2:3]
	s_movk_i32 s0, 0x104
	v_or_b32_e32 v28, 2, v38
	v_mad_u64_u32 v[2:3], s[10:11], v29, s0, v[2:3]
	v_lshl_add_u32 v74, v40, 3, 0
	v_lshlrev_b32_e32 v3, 9, v28
	v_add_u32_e32 v66, v74, v3
	v_lshlrev_b32_e32 v4, 9, v29
	v_add_u32_e32 v70, v74, v4
	v_lshl_add_u32 v76, v35, 12, v74
	s_movk_i32 s0, 0x900
	v_lshlrev_b32_e32 v36, 1, v40
	v_cmp_gt_u32_e64 s[12:13], s83, v39
	s_waitcnt vmcnt(34)
	v_pk_add_f32 v[4:5], v[0:1], 1.0 op_sel_hi:[1,0] neg_lo:[1,0] neg_hi:[1,0]
	s_waitcnt vmcnt(33)
	ds_write_b32 v6, v20
	s_waitcnt vmcnt(32)
	v_lshlrev_b32_e32 v3, 16, v27
	v_and_b32_e32 v6, 0xffff0000, v27
	s_waitcnt vmcnt(31)
	v_lshlrev_b32_e32 v72, 16, v30
	v_and_b32_e32 v71, 0xffff0000, v30
	v_mul_f32_e32 v7, 0xbfb8aa3b, v3
	v_mul_f32_e32 v10, 0xbfb8aa3b, v6
	s_waitcnt vmcnt(30)
	v_lshlrev_b32_e32 v68, 16, v31
	v_and_b32_e32 v67, 0xffff0000, v31
	v_mul_f32_e32 v3, 0x3fb8aa3b, v3
	v_mul_f32_e32 v11, 0xbfb8aa3b, v72
	v_mul_f32_e32 v12, 0xbfb8aa3b, v71
	v_exp_f32_e32 v7, v7
	v_exp_f32_e32 v10, v10
	v_mul_f32_e32 v6, 0x3fb8aa3b, v6
	v_mul_f32_e32 v13, 0xbfb8aa3b, v68
	v_mul_f32_e32 v14, 0xbfb8aa3b, v67
	v_exp_f32_e32 v3, v3
	v_exp_f32_e32 v11, v11
	v_exp_f32_e32 v12, v12
	v_exp_f32_e32 v6, v6
	v_exp_f32_e32 v13, v13
	v_exp_f32_e32 v14, v14
	v_add_f32_e32 v7, 1.0, v7
	v_add_f32_e32 v10, 1.0, v10
	v_add_f32_e32 v3, 1.0, v3
	v_add_f32_e32 v11, 1.0, v11
	v_add_f32_e32 v12, 1.0, v12
	v_rcp_f32_e32 v20, v7
	v_rcp_f32_e32 v10, v10
	v_add_f32_e32 v15, 1.0, v6
	v_add_f32_e32 v13, 1.0, v13
	v_add_f32_e32 v14, 1.0, v14
	v_rcp_f32_e32 v6, v3
	v_rcp_f32_e32 v3, v11
	v_rcp_f32_e32 v11, v12
	v_rcp_f32_e32 v12, v13
	v_rcp_f32_e32 v13, v14
	v_rcp_f32_e32 v7, v15
	v_fma_f32 v14, v4, v20, v0
	v_fma_f32 v15, v5, v10, v1
	v_fma_f32 v3, v4, v3, v0
	v_fma_f32 v20, v5, v11, v1
	v_log_f32_e32 v10, v14
	v_log_f32_e32 v11, v15
	v_fma_f32 v27, v4, v12, v0
	v_fma_f32 v30, v5, v13, v1
	v_log_f32_e32 v12, v3
	v_log_f32_e32 v13, v20
	s_waitcnt vmcnt(29)
	v_lshlrev_b32_e32 v64, 16, v32
	v_and_b32_e32 v65, 0xffff0000, v32
	v_mul_f32_e32 v3, 0xbfb8aa3b, v64
	ds_write_b64 v76, v[10:11]
	ds_write_b64 v70, v[12:13]
	v_exp_f32_e32 v3, v3
	v_mul_f32_e32 v10, 0xbfb8aa3b, v65
	v_exp_f32_e32 v10, v10
	s_waitcnt vmcnt(11)
	ds_write2_b32 v2, v33, v43 offset1:65
	v_add_f32_e32 v3, 1.0, v3
	v_rcp_f32_e32 v3, v3
	v_add_f32_e32 v10, 1.0, v10
	v_rcp_f32_e32 v11, v10
	v_or_b32_e32 v33, 3, v38
	v_fma_f32 v3, v4, v3, v0
	v_log_f32_e32 v10, v3
	v_fma_f32 v3, v5, v11, v1
	v_log_f32_e32 v11, v3
	v_lshlrev_b32_e32 v3, 9, v33
	v_add_u32_e32 v63, v74, v3
	s_waitcnt vmcnt(5)
	v_lshlrev_b32_e32 v62, 16, v49
	v_and_b32_e32 v61, 0xffff0000, v49
	ds_write_b64 v63, v[10:11]
	v_mul_f32_e32 v3, 0xbfb8aa3b, v62
	v_mul_f32_e32 v10, 0xbfb8aa3b, v61
	v_exp_f32_e32 v3, v3
	v_exp_f32_e32 v10, v10
	v_or_b32_e32 v32, 4, v38
	s_waitcnt vmcnt(4)
	v_lshlrev_b32_e32 v58, 16, v50
	v_add_f32_e32 v3, 1.0, v3
	v_add_f32_e32 v10, 1.0, v10
	v_rcp_f32_e32 v3, v3
	v_rcp_f32_e32 v11, v10
	v_mul_f32_e32 v12, 0xbfb8aa3b, v58
	v_exp_f32_e32 v12, v12
	v_fma_f32 v3, v4, v3, v0
	v_fma_f32 v11, v5, v11, v1
	v_log_f32_e32 v10, v3
	v_log_f32_e32 v11, v11
	v_lshlrev_b32_e32 v3, 9, v32
	v_add_u32_e32 v59, v74, v3
	v_and_b32_e32 v57, 0xffff0000, v50
	ds_write_b64 v59, v[10:11]
	v_mul_f32_e32 v10, 0xbfb8aa3b, v57
	v_exp_f32_e32 v10, v10
	v_add_f32_e32 v3, 1.0, v12
	v_rcp_f32_e32 v3, v3
	v_log_f32_e32 v15, v30
	v_add_f32_e32 v10, 1.0, v10
	v_rcp_f32_e32 v11, v10
	v_or_b32_e32 v30, 5, v38
	v_fma_f32 v3, v4, v3, v0
	v_log_f32_e32 v10, v3
	v_lshlrev_b32_e32 v3, 9, v30
	s_waitcnt vmcnt(3)
	v_lshlrev_b32_e32 v54, 16, v52
	v_add_u32_e32 v55, v74, v3
	v_fma_f32 v3, v5, v11, v1
	v_and_b32_e32 v53, 0xffff0000, v52
	v_mul_f32_e32 v11, 0xbfb8aa3b, v54
	v_exp_f32_e32 v12, v11
	v_mul_f32_e32 v11, 0xbfb8aa3b, v53
	v_exp_f32_e32 v13, v11
	v_log_f32_e32 v11, v3
	v_add_f32_e32 v3, 1.0, v12
	v_rcp_f32_e32 v3, v3
	v_add_f32_e32 v12, 1.0, v13
	v_rcp_f32_e32 v12, v12
	ds_write_b64 v55, v[10:11]
	v_fma_f32 v3, v4, v3, v0
	v_log_f32_e32 v10, v3
	v_fma_f32 v3, v5, v12, v1
	v_log_f32_e32 v11, v3
	v_or_b32_e32 v31, 6, v38
	v_lshlrev_b32_e32 v3, 9, v31
	ds_write2_b32 v2, v44, v45 offset0:130 offset1:195
	v_add_u32_e32 v52, v74, v3
	s_waitcnt vmcnt(2)
	v_lshlrev_b32_e32 v45, 16, v73
	v_and_b32_e32 v44, 0xffff0000, v73
	ds_write_b64 v52, v[10:11]
	v_mul_f32_e32 v3, 0xbfb8aa3b, v45
	v_mul_f32_e32 v10, 0xbfb8aa3b, v44
	v_exp_f32_e32 v3, v3
	v_exp_f32_e32 v10, v10
	v_log_f32_e32 v14, v27
	v_or_b32_e32 v27, 7, v38
	v_add_f32_e32 v3, 1.0, v3
	v_add_f32_e32 v10, 1.0, v10
	v_rcp_f32_e32 v3, v3
	v_rcp_f32_e32 v10, v10
	v_add_u32_e32 v11, 0x400, v2
	ds_write_b64 v66, v[14:15]
	v_fma_f32 v0, v4, v3, v0
	v_fmac_f32_e32 v1, v5, v10
	v_log_f32_e32 v0, v0
	v_log_f32_e32 v1, v1
	v_lshlrev_b32_e32 v3, 9, v27
	v_add_u32_e32 v43, v74, v3
	ds_write2_b32 v11, v46, v47 offset0:4 offset1:69
	ds_write_b64 v43, v[0:1]
	ds_write_b32 v2, v48 offset:1560
	v_ashrrev_i32_e32 v0, 31, v39
	v_lshrrev_b32_e32 v0, 26, v0
	v_add_u32_e32 v0, v39, v0
	v_ashrrev_i32_e32 v14, 6, v0
	v_mul_u32_u24_e32 v0, 0x41, v40
	v_lshlrev_b32_e32 v2, 5, v14
	v_lshlrev_b32_e32 v3, 2, v0
	v_add3_u32 v0, s14, v2, v3
	s_waitcnt lgkmcnt(0)
	s_barrier
	ds_read2_b32 v[0:1], v0 offset1:1
	v_mul_lo_u32 v15, v14, s0
	v_add_u32_e32 v47, s14, v3
	v_add3_u32 v20, s34, v15, v36
	v_add_u32_e32 v12, v47, v2
	ds_read2_b32 v[2:3], v12 offset0:2 offset1:3
	ds_read2_b32 v[10:11], v12 offset0:4 offset1:5
	ds_read2_b32 v[12:13], v12 offset0:6 offset1:7
	s_waitcnt lgkmcnt(3)
	ds_write_b16 v20, v0
	v_add_u32_e32 v20, s34, v36
	v_add_u32_e32 v15, v20, v15
	ds_write_b16_d16_hi v15, v0 offset:144
	v_lshl_or_b32 v0, v14, 3, 1
	s_movk_i32 s0, 0x120
	v_mul_lo_u32 v0, v0, s0
	v_add3_u32 v14, s34, v0, v36
	v_add_u32_e32 v15, v20, v0
	ds_write_b16 v14, v1
	ds_write_b16_d16_hi v15, v1 offset:144
	s_waitcnt lgkmcnt(6)
	ds_write_b16 v14, v2 offset:288
	ds_write_b16_d16_hi v15, v2 offset:432
	ds_write_b16 v14, v3 offset:576
	ds_write_b16_d16_hi v15, v3 offset:720
	s_waitcnt lgkmcnt(9)
	ds_write_b16 v14, v10 offset:864
	ds_write_b16_d16_hi v15, v10 offset:1008
	ds_write_b16 v14, v11 offset:1152
	ds_write_b16_d16_hi v15, v11 offset:1296
	s_waitcnt lgkmcnt(12)
	ds_write_b16 v14, v12 offset:1440
	v_and_b32_e32 v0, 0x7f, v39
	v_lshlrev_b32_e32 v1, 6, v39
	v_lshlrev_b32_e32 v0, 2, v0
	v_and_b32_e32 v1, 0xffffe000, v1
	v_add3_u32 v10, 0, v0, v1
	ds_read2st64_b32 v[0:1], v10 offset1:2
	ds_write_b16_d16_hi v15, v12 offset:1584
	ds_write_b16 v14, v13 offset:1728
	ds_write_b16_d16_hi v15, v13 offset:1872
	ds_read2st64_b32 v[2:3], v10 offset0:4 offset1:6
	v_lshlrev_b32_e32 v48, 16, v8
	v_and_b32_e32 v49, 0xffff0000, v8
	s_waitcnt lgkmcnt(4)
	v_add_f32_e32 v0, 0, v0
	v_add_f32_e32 v11, v0, v1
	ds_write2st64_b32 v10, v0, v11 offset1:2
	ds_read2st64_b32 v[0:1], v10 offset0:8 offset1:10
	s_waitcnt lgkmcnt(2)
	v_add_f32_e32 v2, v11, v2
	v_add_f32_e32 v11, v2, v3
	ds_write2st64_b32 v10, v2, v11 offset0:4 offset1:6
	ds_read2st64_b32 v[2:3], v10 offset0:12 offset1:14
	s_waitcnt lgkmcnt(2)
	v_add_f32_e32 v0, v11, v0
	v_add_f32_e32 v11, v0, v1
	ds_write2st64_b32 v10, v0, v11 offset0:8 offset1:10
	ds_read2st64_b32 v[0:1], v10 offset0:16 offset1:18
	s_waitcnt lgkmcnt(2)
	v_add_f32_e32 v2, v11, v2
	v_add_f32_e32 v11, v2, v3
	ds_write2st64_b32 v10, v2, v11 offset0:12 offset1:14
	ds_read2st64_b32 v[2:3], v10 offset0:20 offset1:22
	s_waitcnt lgkmcnt(2)
	v_add_f32_e32 v0, v11, v0
	v_add_f32_e32 v11, v0, v1
	ds_write2st64_b32 v10, v0, v11 offset0:16 offset1:18
	ds_read2st64_b32 v[0:1], v10 offset0:24 offset1:26
	s_waitcnt lgkmcnt(2)
	v_add_f32_e32 v11, v11, v2
	v_add_f32_e32 v12, v11, v3
	ds_read2st64_b32 v[2:3], v10 offset0:28 offset1:30
	ds_write2st64_b32 v10, v11, v12 offset0:20 offset1:22
	s_waitcnt lgkmcnt(2)
	v_add_f32_e32 v0, v12, v0
	v_add_f32_e32 v1, v0, v1
	ds_write2st64_b32 v10, v0, v1 offset0:24 offset1:26
	s_waitcnt lgkmcnt(2)
	v_add_f32_e32 v0, v1, v2
	v_add_f32_e32 v1, v0, v3
	ds_write2st64_b32 v10, v0, v1 offset0:28 offset1:30
	v_lshl_add_u32 v0, v39, 2, 0
	v_mul_f32_e32 v12, 0xbfb8aa3b, v48
	ds_write_b32 v0, v1 offset:32768
	s_waitcnt lgkmcnt(0)
	s_barrier
	ds_read2st64_b64 v[0:3], v74 offset0:64 offset1:65
	ds_read_b64 v[10:11], v74 offset:33792
	v_exp_f32_e32 v50, v12
	v_mul_f32_e32 v12, 0xbfb8aa3b, v49
	v_exp_f32_e32 v73, v12
	ds_read_b64 v[12:13], v76
	v_ashrrev_i32_e32 v20, 7, v39
	s_waitcnt lgkmcnt(2)
	v_pk_add_f32 v[14:15], v[0:1], v[2:3]
	v_add_f32_e32 v50, 1.0, v50
	s_waitcnt lgkmcnt(1)
	v_pk_add_f32 v[10:11], v[14:15], v[10:11]
	v_cmp_eq_u32_e32 vcc, 2, v20
	v_sub_u32_e32 v8, v74, v75
	v_rcp_f32_e32 v74, v50
	v_add_f32_e32 v50, 1.0, v73
	v_cndmask_b32_e32 v2, v10, v14, vcc
	v_cmp_eq_u32_e64 s[10:11], 1, v20
	v_rcp_f32_e32 v75, v50
	s_waitcnt lgkmcnt(0)
	v_exp_f32_e32 v76, v12
	v_cndmask_b32_e64 v2, v2, v0, s[10:11]
	v_cndmask_b32_e64 v3, v2, 0, s[12:13]
	v_cndmask_b32_e32 v2, v11, v15, vcc
	v_exp_f32_e32 v77, v13
	v_cndmask_b32_e64 v2, v2, v1, s[10:11]
	v_cndmask_b32_e64 v46, v2, 0, s[12:13]
	v_lshlrev_b32_e32 v2, 8, v40
	v_pk_mul_f32 v[48:49], v[74:75], v[48:49]
	s_mov_b32 s0, 0x3db504f3
	v_sub_u32_e32 v2, v47, v2
	v_pk_mul_f32 v[48:49], v[48:49], s[0:1] op_sel_hi:[1,0]
	v_add_f32_e32 v47, v12, v3
	v_pk_mul_f32 v[74:75], v[48:49], v[76:77]
	v_exp_f32_e32 v76, v47
	v_add_f32_e32 v47, v13, v46
	v_exp_f32_e32 v77, v47
	v_pk_mul_f32 v[6:7], v[4:5], v[6:7]
	v_cvt_pk_bf16_f32 v47, v74, v75
	v_mad_u64_u32 v[74:75], s[10:11], v35, s52, v[8:9]
	v_pk_mul_f32 v[48:49], v[48:49], v[76:77]
	v_cmp_gt_i32_e32 vcc, 1, v20
	v_cvt_pk_bf16_f32 v48, v48, v49
	ds_write2st64_b32 v74, v47, v48 offset0:136 offset1:204
	s_and_saveexec_b64 s[10:11], vcc
	s_mov_b32 s2, s14
	s_cbranch_execz .LBB0_1240
	v_sub_f32_e64 v47, -v3, v12
	v_min_f32_e32 v47, 0x42c80000, v47
	v_exp_f32_e32 v48, v47
	v_sub_f32_e64 v47, -v46, v13
	v_min_f32_e32 v47, 0x42c80000, v47
	v_exp_f32_e32 v49, v47
	s_nop 0
	v_pk_mul_f32 v[48:49], v[6:7], v[48:49]
	s_nop 0
	v_cvt_pk_bf16_f32 v47, v48, v49
	v_mad_u64_u32 v[48:49], s[12:13], v35, s52, v[2:3]
	ds_write_b32 v48, v47

.LBB0_1447:
	s_or_b64 exec, exec, s[6:7]
	v_or_b32_e32 v5, v5, v7
	v_cmp_gt_i32_e64 s[8:9], v5, v47
	s_or_b64 s[6:7], vcc, s[8:9]
	s_nop 3
	v_cvt_pk_bf16_f32 v0, v0, s0
	v_lshlrev_b32_e32 v6, 1, v5
	v_readlane_b32 s0, v254, 47
	v_cndmask_b32_e64 v0, v0, 0, s[6:7]
	v_cmp_gt_i32_e64 s[8:9], v5, v45
	v_add3_u32 v7, s0, v15, v6
	ds_write_b16 v7, v0
	s_or_b64 s[6:7], vcc, s[8:9]
	v_cvt_pk_bf16_f32 v0, v1, s0
	v_cndmask_b32_e64 v0, v0, 0, s[6:7]
	v_add3_u32 v1, s0, v13, v6
	v_cmp_gt_i32_e64 s[8:9], v5, v14
	ds_write_b16 v1, v0
	s_or_b64 s[6:7], vcc, s[8:9]
	v_cvt_pk_bf16_f32 v0, v2, s0
	v_cndmask_b32_e64 v0, v0, 0, s[6:7]
	v_add3_u32 v1, s0, v11, v6
	v_cmp_gt_i32_e64 s[8:9], v5, v12
	ds_write_b16 v1, v0
	s_or_b64 s[6:7], vcc, s[8:9]
	v_cvt_pk_bf16_f32 v0, v3, s0
	v_cndmask_b32_e64 v0, v0, 0, s[6:7]
	v_add3_u32 v1, s0, v4, v6
	v_and_b32_e32 v51, 31, v43
	ds_write_b16 v1, v0
	v_lshlrev_b32_e32 v0, 5, v40
	v_and_b32_e32 v45, 32, v0
	v_mov_b32_e32 v0, s0
	s_movk_i32 s0, 0x1200
	v_mul_u32_u24_e32 v2, 0x48, v51
	v_lshrrev_b32_e32 v3, 1, v43
	v_mad_u32_u24 v0, v45, s94, v0
	v_mul_lo_u32 v1, v22, s0
	v_readlane_b32 s10, v254, 46
	v_lshlrev_b32_e32 v2, 1, v2
	v_and_b32_e32 v47, 16, v3
	v_add_u32_e32 v1, s10, v1
	v_add3_u32 v53, v0, v2, v47
	s_waitcnt lgkmcnt(0)
	s_barrier
	v_add3_u32 v66, v1, v2, v47
	ds_read_b128 v[0:3], v53
	ds_read_b128 v[56:59], v53 offset:32
	ds_read_b128 v[4:7], v66
	ds_read_b128 v[60:63], v66 offset:32
	s_waitcnt lgkmcnt(1)
	v_mfma_f32_32x32x16_bf16 v[0:15], v[0:3], v[4:7], 0
	s_movk_i32 s0, 0x2200
	v_mul_lo_u32 v22, v22, s0
	v_add_u32_e32 v22, 0, v22
	v_lshrrev_b32_e32 v49, 3, v43
	v_readlane_b32 s0, v253, 36
	s_lshl_b32 s96, s0, 1
	s_movk_i32 s0, 0x1080
	s_waitcnt lgkmcnt(0)
	v_mfma_f32_32x32x16_bf16 v[0:15], v[56:59], v[60:63], v[0:15]
	ds_read_b128 v[56:59], v53 offset:64
	ds_read_b128 v[60:63], v66 offset:64
	v_or_b32_e32 v166, s41, v42
	v_lshlrev_b32_e32 v111, 16, v90
	v_and_b32_e32 v110, 0xffff0000, v90
	v_lshlrev_b32_e32 v108, 16, v89
	v_and_b32_e32 v107, 0xffff0000, v89
	v_lshlrev_b32_e32 v102, 16, v79
	s_waitcnt lgkmcnt(0)
	v_mfma_f32_32x32x16_bf16 v[0:15], v[56:59], v[60:63], v[0:15]
	ds_read_b128 v[56:59], v53 offset:96
	ds_read_b128 v[60:63], v66 offset:96
	v_mad_u32_u24 v53, v45, s50, 0
	v_and_or_b32 v45, v49, 4, v45
	v_mul_u32_u24_e32 v45, 0x210, v45
	v_and_b32_e32 v101, 0xffff0000, v79
	v_lshlrev_b32_e32 v99, 16, v76
	v_and_b32_e32 v98, 0xffff0000, v76
	s_waitcnt lgkmcnt(0)
	v_mfma_f32_32x32x16_bf16 v[0:15], v[56:59], v[60:63], v[0:15]
	v_mul_u32_u24_e32 v56, 0x88, v51
	v_lshlrev_b32_e32 v56, 1, v56
	v_add3_u32 v53, v53, v56, v47
	v_add3_u32 v22, v22, v56, v47
	ds_read_b128 v[56:59], v53 offset:52224
	ds_read_b128 v[60:63], v53 offset:52256
	ds_read_b128 v[70:73], v22
	ds_read_b128 v[94:97], v22 offset:32
	v_and_b32_e32 v90, 0xffff0000, v68
	s_waitcnt lgkmcnt(1)
	v_mfma_f32_32x32x16_bf16 v[0:15], v[56:59], v[70:73], v[0:15]
	s_waitcnt lgkmcnt(0)
	v_mfma_f32_32x32x16_bf16 v[0:15], v[60:63], v[94:97], v[0:15]
	ds_read_b128 v[56:59], v53 offset:52288
	ds_read_b128 v[60:63], v22 offset:64
	v_mov_b32_e32 v97, v208
	s_waitcnt lgkmcnt(0)
	v_mfma_f32_32x32x16_bf16 v[0:15], v[56:59], v[60:63], v[0:15]
	ds_read_b128 v[56:59], v53 offset:52320
	ds_read_b128 v[60:63], v22 offset:96
	s_waitcnt lgkmcnt(0)
	v_mfma_f32_32x32x16_bf16 v[0:15], v[56:59], v[60:63], v[0:15]
	ds_read_b128 v[56:59], v53 offset:52352
	ds_read_b128 v[60:63], v22 offset:128
	s_waitcnt lgkmcnt(0)
	v_mfma_f32_32x32x16_bf16 v[0:15], v[56:59], v[60:63], v[0:15]
	ds_read_b128 v[56:59], v53 offset:52384
	ds_read_b128 v[60:63], v22 offset:160
	s_waitcnt lgkmcnt(0)
	v_mfma_f32_32x32x16_bf16 v[0:15], v[56:59], v[60:63], v[0:15]
	ds_read_b128 v[56:59], v53 offset:52416
	ds_read_b128 v[60:63], v22 offset:192
	s_waitcnt lgkmcnt(0)
	v_mfma_f32_32x32x16_bf16 v[0:15], v[56:59], v[60:63], v[0:15]
	ds_read_b128 v[56:59], v53 offset:52448
	ds_read_b128 v[60:63], v22 offset:224
	v_and_b32_e32 v22, 0xffffff80, v43
	v_add_u32_e32 v22, s2, v22
	v_lshlrev_b32_e32 v43, 2, v51
	v_add3_u32 v22, v22, v43, v45
	s_waitcnt lgkmcnt(0)
	v_mfma_f32_32x32x16_bf16 v[0:15], v[56:59], v[60:63], v[0:15]
	s_nop 11
	ds_write2_b32 v22, v0, v1 offset1:132
	v_add_u32_e32 v0, 0x400, v22
	ds_write2_b32 v0, v2, v3 offset0:8 offset1:140
	v_add_u32_e32 v0, 0x1000, v22
	ds_write2_b32 v0, v4, v5 offset0:32 offset1:164
	v_add_u32_e32 v0, 0x1400, v22
	ds_write2_b32 v0, v6, v7 offset0:40 offset1:172
	v_add_u32_e32 v0, 0x2000, v22
	ds_write2_b32 v0, v8, v9 offset0:64 offset1:196
	v_add_u32_e32 v0, 0x2400, v22
	ds_write2_b32 v0, v10, v11 offset0:72 offset1:204
	v_add_u32_e32 v0, 0x3000, v22
	v_lshl_add_u32 v2, v42, 2, s2
	ds_write2_b32 v0, v12, v13 offset0:96 offset1:228
	v_add_u32_e32 v0, 0x3400, v22
	v_mad_u64_u32 v[6:7], s[6:7], v40, s0, v[2:3]
	ds_write2_b32 v0, v14, v15 offset0:104 offset1:236
	s_waitcnt lgkmcnt(0)
	s_barrier
	ds_read_b64 v[10:11], v6
	v_lshl_add_u64 v[0:1], v[166:167], 2, v[20:21]
	v_lshlrev_b32_e32 v14, 16, v136
	v_and_b32_e32 v15, 0xffff0000, v136
	v_lshl_add_u64 v[4:5], v[16:17], 0, s[96:97]
	s_waitcnt lgkmcnt(0)
	v_pk_mul_f32 v[6:7], v[10:11], v[10:11]
	v_lshlrev_b32_e32 v166, 1, v42
	v_add_f32_e32 v3, v6, v7
	v_readlane_b32 s0, v253, 16
	v_lshl_add_u64 v[4:5], v[4:5], 0, v[166:167]
	v_add_f32_dpp v3, v3, v3 row_ror:8 row_mask:0xf bank_mask:0xf bound_ctrl:1
	s_mov_b64 s[2:3], 0x22cc2800
	v_add_u32_e32 v12, s0, v33
	v_add_f32_dpp v3, v3, v3 row_ror:4 row_mask:0xf bank_mask:0xf bound_ctrl:1
	v_lshl_add_u64 v[4:5], v[4:5], 0, s[2:3]
	v_ashrrev_i32_e32 v13, 31, v12
	v_add_f32_dpp v3, v3, v3 row_ror:2 row_mask:0xf bank_mask:0xf bound_ctrl:1
	s_movk_i32 s2, 0x210
	s_nop 0
	v_add_f32_dpp v3, v3, v3 row_ror:1 row_mask:0xf bank_mask:0xf bound_ctrl:1
	s_nop 0
	v_readlane_b32 s5, v3, 16
	v_readlane_b32 s8, v3, 48
	v_readlane_b32 s6, v3, 0
	v_readlane_b32 s7, v3, 32
	v_mov_b32_e32 v6, s5
	v_mov_b32_e32 v7, s8
	v_pk_add_f32 v[8:9], s[6:7], v[6:7]
	global_load_dwordx2 v[6:7], v[0:1], off
	v_mul_f32_e32 v0, 0xbfb8aa3b, v14
	v_mul_f32_e32 v1, 0xbfb8aa3b, v15
	v_exp_f32_e32 v0, v0
	v_exp_f32_e32 v1, v1
	v_mov_b32_e32 v43, v8
	v_add_f32_e32 v0, 1.0, v0
	v_add_f32_e32 v1, 1.0, v1
	v_rcp_f32_e32 v0, v0
	v_rcp_f32_e32 v1, v1
	s_nop 0
	v_pk_mul_f32 v[16:17], v[0:1], v[14:15]
	v_lshlrev_b64 v[0:1], 10, v[12:13]
	v_mad_u64_u32 v[14:15], s[6:7], v32, s2, v[2:3]
	v_lshl_add_u64 v[12:13], v[4:5], 0, v[0:1]
	ds_read2_b64 v[0:3], v14 offset1:66
	s_mov_b32 s2, 0x358637bd
	s_waitcnt lgkmcnt(0)
	v_pk_mul_f32 v[20:21], v[0:1], v[0:1]
	s_nop 0
	v_add_f32_e32 v15, v20, v21
	s_nop 1
	v_add_f32_dpp v15, v15, v15 row_ror:8 row_mask:0xf bank_mask:0xf bound_ctrl:1
	s_nop 1
	v_add_f32_dpp v15, v15, v15 row_ror:4 row_mask:0xf bank_mask:0xf bound_ctrl:1
	s_nop 1
	v_add_f32_dpp v15, v15, v15 row_ror:2 row_mask:0xf bank_mask:0xf bound_ctrl:1
	s_nop 1
	v_add_f32_dpp v15, v15, v15 row_ror:1 row_mask:0xf bank_mask:0xf bound_ctrl:1
	s_nop 0
	v_readlane_b32 s5, v15, 16
	v_readlane_b32 s8, v15, 48
	v_readlane_b32 s6, v15, 0
	v_readlane_b32 s7, v15, 32
	v_mov_b32_e32 v20, s5
	v_mov_b32_e32 v21, s8
	v_pk_add_f32 v[20:21], s[6:7], v[20:21]
	s_nop 0
	v_mov_b32_e32 v42, v20
	v_mov_b32_e32 v8, v21
	v_pk_add_f32 v[20:21], v[42:43], v[8:9]
	v_mov_b64_e32 v[8:9], s[2:3]
	s_brev_b32 s2, 60
	v_pk_fma_f32 v[20:21], v[20:21], s[2:3], v[8:9] op_sel_hi:[1,0,0]
	s_nop 0
	v_mul_f32_e32 v15, 0x4b800000, v21
	v_cmp_gt_f32_e64 s[8:9], s58, v21
	v_cmp_gt_f32_e32 vcc, s58, v20
	s_nop 0
	v_cndmask_b32_e64 v15, v21, v15, s[8:9]
	v_rsq_f32_e32 v15, v15
	s_nop 0
	v_mul_f32_e32 v21, 0x45800000, v15
	v_cndmask_b32_e64 v22, v15, v21, s[8:9]
	v_pk_mul_f32 v[10:11], v[10:11], v[22:23] op_sel_hi:[1,0]
	s_waitcnt vmcnt(0)
	v_pk_mul_f32 v[10:11], v[6:7], v[10:11]
	s_nop 0
	v_pk_mul_f32 v[10:11], v[16:17], v[10:11]
	v_lshlrev_b32_e32 v16, 16, v135
	v_cvt_pk_bf16_f32 v10, v10, v11
	global_store_dword v[12:13], v10, off
	v_mul_f32_e32 v10, 0x4b800000, v20
	v_cndmask_b32_e32 v10, v20, v10, vcc
	v_rsq_f32_e32 v10, v10
	v_and_b32_e32 v17, 0xffff0000, v135
	v_add_u32_e32 v12, s0, v32
	v_ashrrev_i32_e32 v13, 31, v12
	v_mul_f32_e32 v11, 0x45800000, v10
	v_cndmask_b32_e32 v10, v10, v11, vcc
	v_mul_f32_e32 v11, 0xbfb8aa3b, v16
	v_exp_f32_e32 v11, v11
	s_nop 0
	v_add_f32_e32 v11, 1.0, v11
	v_pk_mul_f32 v[0:1], v[0:1], v[10:11] op_sel_hi:[1,0]
	v_mul_f32_e32 v10, 0xbfb8aa3b, v17
	v_exp_f32_e32 v10, v10
	v_rcp_f32_e32 v20, v11
	v_pk_mul_f32 v[0:1], v[6:7], v[0:1]
	v_add_f32_e32 v10, 1.0, v10
	v_rcp_f32_e32 v21, v10
	s_nop 0
	v_pk_mul_f32 v[10:11], v[20:21], v[16:17]
	s_nop 0
	v_pk_mul_f32 v[0:1], v[10:11], v[0:1]
	s_nop 0
	v_cvt_pk_bf16_f32 v10, v0, v1
	v_lshlrev_b64 v[0:1], 10, v[12:13]
	v_lshlrev_b32_e32 v12, 16, v134
	v_mul_f32_e32 v15, 0xbfb8aa3b, v12
	v_exp_f32_e32 v15, v15
	v_and_b32_e32 v13, 0xffff0000, v134
	v_lshl_add_u64 v[0:1], v[4:5], 0, v[0:1]
	global_store_dword v[0:1], v10, off
	v_add_f32_e32 v15, 1.0, v15
	v_rcp_f32_e32 v16, v15
	v_mul_f32_e32 v15, 0xbfb8aa3b, v13
	v_exp_f32_e32 v15, v15
	v_add_u32_e32 v10, s0, v31
	v_ashrrev_i32_e32 v11, 31, v10
	v_lshlrev_b64 v[10:11], 10, v[10:11]
	v_add_f32_e32 v15, 1.0, v15
	v_rcp_f32_e32 v17, v15
	v_lshl_add_u64 v[20:21], v[4:5], 0, v[10:11]
	v_pk_mul_f32 v[0:1], v[2:3], v[2:3]
	v_pk_mul_f32 v[16:17], v[16:17], v[12:13]
	ds_read2_b64 v[10:13], v14 offset0:132 offset1:198
	v_add_f32_e32 v0, v0, v1
	s_waitcnt lgkmcnt(0)
	v_pk_mul_f32 v[32:33], v[10:11], v[10:11]
	v_add_f32_dpp v0, v0, v0 row_ror:8 row_mask:0xf bank_mask:0xf bound_ctrl:1
	v_add_f32_e32 v15, v32, v33
	s_nop 0
	v_add_f32_dpp v0, v0, v0 row_ror:4 row_mask:0xf bank_mask:0xf bound_ctrl:1
	v_add_f32_dpp v15, v15, v15 row_ror:8 row_mask:0xf bank_mask:0xf bound_ctrl:1
	s_nop 0
	v_add_f32_dpp v0, v0, v0 row_ror:2 row_mask:0xf bank_mask:0xf bound_ctrl:1
	v_add_f32_dpp v15, v15, v15 row_ror:4 row_mask:0xf bank_mask:0xf bound_ctrl:1
	s_nop 0
	v_add_f32_dpp v0, v0, v0 row_ror:1 row_mask:0xf bank_mask:0xf bound_ctrl:1
	v_add_f32_dpp v15, v15, v15 row_ror:2 row_mask:0xf bank_mask:0xf bound_ctrl:1
	v_readlane_b32 s5, v0, 16
	v_readlane_b32 s8, v0, 48
	v_add_f32_dpp v15, v15, v15 row_ror:1 row_mask:0xf bank_mask:0xf bound_ctrl:1
	v_readlane_b32 s6, v0, 0
	v_readlane_b32 s7, v0, 32
	v_mov_b32_e32 v0, s5
	v_mov_b32_e32 v1, s8
	v_readlane_b32 s5, v15, 16
	v_readlane_b32 s8, v15, 48
	v_pk_add_f32 v[0:1], s[6:7], v[0:1]
	v_readlane_b32 s6, v15, 0
	v_readlane_b32 s7, v15, 32
	v_mov_b32_e32 v32, s5
	v_mov_b32_e32 v33, s8
	v_pk_add_f32 v[32:33], s[6:7], v[32:33]
	v_mov_b32_e32 v43, v0
	v_mov_b32_e32 v42, v32
	v_mov_b32_e32 v0, v33
	v_pk_add_f32 v[0:1], v[42:43], v[0:1]
	s_nop 0
	v_pk_fma_f32 v[0:1], v[0:1], s[2:3], v[8:9] op_sel_hi:[1,0,0]
	s_nop 0
	v_mul_f32_e32 v15, 0x4b800000, v1
	v_cmp_gt_f32_e64 s[8:9], s58, v1
	v_cmp_gt_f32_e32 vcc, s58, v0
	s_nop 0
	v_cndmask_b32_e64 v1, v1, v15, s[8:9]
	v_rsq_f32_e32 v1, v1
	s_nop 0
	v_mul_f32_e32 v15, 0x45800000, v1
	v_cndmask_b32_e64 v22, v1, v15, s[8:9]
	v_pk_mul_f32 v[2:3], v[2:3], v[22:23] op_sel_hi:[1,0]
	s_nop 0
	v_pk_mul_f32 v[2:3], v[6:7], v[2:3]
	s_nop 0
	v_pk_mul_f32 v[2:3], v[16:17], v[2:3]
	v_lshlrev_b32_e32 v16, 16, v133
	v_cvt_pk_bf16_f32 v1, v2, v3
	global_store_dword v[20:21], v1, off
	v_mul_f32_e32 v1, 0x4b800000, v0
	v_cndmask_b32_e32 v0, v0, v1, vcc
	v_rsq_f32_e32 v0, v0
	v_and_b32_e32 v17, 0xffff0000, v133
	v_add_u32_e32 v2, s0, v30
	v_ashrrev_i32_e32 v3, 31, v2
	v_mul_f32_e32 v1, 0x45800000, v0
	v_cndmask_b32_e32 v0, v0, v1, vcc
	v_mul_f32_e32 v1, 0xbfb8aa3b, v16
	v_exp_f32_e32 v1, v1
	s_nop 0
	v_add_f32_e32 v1, 1.0, v1
	v_rcp_f32_e32 v20, v1
	v_pk_mul_f32 v[0:1], v[10:11], v[0:1] op_sel_hi:[1,0]
	v_mul_f32_e32 v10, 0xbfb8aa3b, v17
	v_exp_f32_e32 v10, v10
	v_pk_mul_f32 v[0:1], v[6:7], v[0:1]
	v_add_f32_e32 v10, 1.0, v10
	v_rcp_f32_e32 v21, v10
	s_nop 0
	v_pk_mul_f32 v[10:11], v[20:21], v[16:17]
	s_nop 0
	v_pk_mul_f32 v[0:1], v[10:11], v[0:1]
	s_nop 0
	v_cvt_pk_bf16_f32 v10, v0, v1
	v_lshlrev_b64 v[0:1], 10, v[2:3]
	v_lshlrev_b32_e32 v2, 16, v132
	v_mul_f32_e32 v15, 0xbfb8aa3b, v2
	v_exp_f32_e32 v15, v15
	v_lshl_add_u64 v[0:1], v[4:5], 0, v[0:1]
	global_store_dword v[0:1], v10, off
	v_pk_mul_f32 v[0:1], v[12:13], v[12:13]
	v_and_b32_e32 v3, 0xffff0000, v132
	v_add_f32_e32 v0, v0, v1
	v_add_f32_e32 v15, 1.0, v15
	v_rcp_f32_e32 v16, v15
	v_add_f32_dpp v0, v0, v0 row_ror:8 row_mask:0xf bank_mask:0xf bound_ctrl:1
	v_mul_f32_e32 v15, 0xbfb8aa3b, v3
	v_exp_f32_e32 v15, v15
	v_add_f32_dpp v0, v0, v0 row_ror:4 row_mask:0xf bank_mask:0xf bound_ctrl:1
	v_add_f32_e32 v15, 1.0, v15
	s_nop 0
	v_add_f32_dpp v0, v0, v0 row_ror:2 row_mask:0xf bank_mask:0xf bound_ctrl:1
	v_rcp_f32_e32 v17, v15
	s_nop 0
	v_add_f32_dpp v0, v0, v0 row_ror:1 row_mask:0xf bank_mask:0xf bound_ctrl:1
	v_pk_mul_f32 v[16:17], v[16:17], v[2:3]
	v_readlane_b32 s5, v0, 16
	v_readlane_b32 s8, v0, 48
	v_readlane_b32 s6, v0, 0
	v_readlane_b32 s7, v0, 32
	v_mov_b32_e32 v0, s5
	v_mov_b32_e32 v1, s8
	v_pk_add_f32 v[10:11], s[6:7], v[0:1]
	v_add_u32_e32 v0, s0, v29
	v_ashrrev_i32_e32 v1, 31, v0
	v_lshlrev_b64 v[0:1], 10, v[0:1]
	v_lshl_add_u64 v[20:21], v[4:5], 0, v[0:1]
	v_add_u32_e32 v0, 0x800, v14
	ds_read2_b64 v[0:3], v0 offset0:8 offset1:74
	v_mov_b32_e32 v33, v10
	s_waitcnt lgkmcnt(0)
	v_pk_mul_f32 v[30:31], v[0:1], v[0:1]
	s_nop 0
	v_add_f32_e32 v15, v30, v31
	s_nop 1
	v_add_f32_dpp v15, v15, v15 row_ror:8 row_mask:0xf bank_mask:0xf bound_ctrl:1
	s_nop 1
	v_add_f32_dpp v15, v15, v15 row_ror:4 row_mask:0xf bank_mask:0xf bound_ctrl:1
	s_nop 1
	v_add_f32_dpp v15, v15, v15 row_ror:2 row_mask:0xf bank_mask:0xf bound_ctrl:1
	s_nop 1
	v_add_f32_dpp v15, v15, v15 row_ror:1 row_mask:0xf bank_mask:0xf bound_ctrl:1
	s_nop 0
	v_readlane_b32 s5, v15, 16
	v_readlane_b32 s8, v15, 48
	v_readlane_b32 s6, v15, 0
	v_readlane_b32 s7, v15, 32
	v_mov_b32_e32 v30, s5
	v_mov_b32_e32 v31, s8
	v_pk_add_f32 v[30:31], s[6:7], v[30:31]
	s_nop 0
	v_mov_b32_e32 v32, v30
	v_mov_b32_e32 v10, v31
	v_pk_add_f32 v[10:11], v[32:33], v[10:11]
	s_nop 0
	v_pk_fma_f32 v[10:11], v[10:11], s[2:3], v[8:9] op_sel_hi:[1,0,0]
	s_nop 0
	v_mul_f32_e32 v15, 0x4b800000, v11
	v_cmp_gt_f32_e64 s[8:9], s58, v11
	v_cmp_gt_f32_e32 vcc, s58, v10
	s_nop 0
	v_cndmask_b32_e64 v11, v11, v15, s[8:9]
	v_rsq_f32_e32 v11, v11
	s_nop 0
	v_mul_f32_e32 v15, 0x45800000, v11
	v_cndmask_b32_e64 v22, v11, v15, s[8:9]
	v_pk_mul_f32 v[12:13], v[12:13], v[22:23] op_sel_hi:[1,0]
	s_nop 0
	v_pk_mul_f32 v[12:13], v[6:7], v[12:13]
	s_nop 0
	v_pk_mul_f32 v[12:13], v[16:17], v[12:13]
	v_lshlrev_b32_e32 v16, 16, v131
	v_cvt_pk_bf16_f32 v11, v12, v13
	global_store_dword v[20:21], v11, off
	v_mul_f32_e32 v11, 0x4b800000, v10
	v_cndmask_b32_e32 v10, v10, v11, vcc
	v_rsq_f32_e32 v10, v10
	v_and_b32_e32 v17, 0xffff0000, v131
	v_add_u32_e32 v12, s0, v26
	v_ashrrev_i32_e32 v13, 31, v12
	v_mul_f32_e32 v11, 0x45800000, v10
	v_cndmask_b32_e32 v10, v10, v11, vcc
	v_mul_f32_e32 v11, 0xbfb8aa3b, v16
	v_exp_f32_e32 v11, v11
	s_nop 0
	v_add_f32_e32 v11, 1.0, v11
	v_pk_mul_f32 v[0:1], v[0:1], v[10:11] op_sel_hi:[1,0]
	v_mul_f32_e32 v10, 0xbfb8aa3b, v17
	v_exp_f32_e32 v10, v10
	v_rcp_f32_e32 v20, v11
	v_pk_mul_f32 v[0:1], v[6:7], v[0:1]
	v_add_f32_e32 v10, 1.0, v10
	v_rcp_f32_e32 v21, v10
	s_nop 0
	v_pk_mul_f32 v[10:11], v[20:21], v[16:17]
	s_nop 0
	v_pk_mul_f32 v[0:1], v[10:11], v[0:1]
	s_nop 0
	v_cvt_pk_bf16_f32 v10, v0, v1
	v_lshlrev_b64 v[0:1], 10, v[12:13]
	v_lshl_add_u64 v[0:1], v[4:5], 0, v[0:1]
	global_store_dword v[0:1], v10, off
	v_pk_mul_f32 v[0:1], v[2:3], v[2:3]
	v_add_u32_e32 v10, s0, v28
	v_add_f32_e32 v0, v0, v1
	v_ashrrev_i32_e32 v11, 31, v10
	v_lshlrev_b64 v[10:11], 10, v[10:11]
	v_add_f32_dpp v0, v0, v0 row_ror:8 row_mask:0xf bank_mask:0xf bound_ctrl:1
	v_lshl_add_u64 v[10:11], v[4:5], 0, v[10:11]
	s_nop 0
	v_add_f32_dpp v0, v0, v0 row_ror:4 row_mask:0xf bank_mask:0xf bound_ctrl:1
	s_nop 1
	v_add_f32_dpp v0, v0, v0 row_ror:2 row_mask:0xf bank_mask:0xf bound_ctrl:1
	s_nop 1
	v_add_f32_dpp v0, v0, v0 row_ror:1 row_mask:0xf bank_mask:0xf bound_ctrl:1
	s_nop 0
	v_readlane_b32 s5, v0, 16
	v_readlane_b32 s8, v0, 48
	v_readlane_b32 s6, v0, 0
	v_readlane_b32 s7, v0, 32
	v_mov_b32_e32 v0, s5
	v_mov_b32_e32 v1, s8
	v_pk_add_f32 v[12:13], s[6:7], v[0:1]
	v_lshlrev_b32_e32 v0, 16, v130
	v_mul_f32_e32 v15, 0xbfb8aa3b, v0
	v_exp_f32_e32 v15, v15
	v_and_b32_e32 v1, 0xffff0000, v130
	v_mov_b32_e32 v21, v12
	v_add_f32_e32 v15, 1.0, v15
	v_rcp_f32_e32 v16, v15
	v_mul_f32_e32 v15, 0xbfb8aa3b, v1
	v_exp_f32_e32 v15, v15
	s_nop 0
	v_add_f32_e32 v15, 1.0, v15
	v_rcp_f32_e32 v17, v15
	ds_read_b64 v[14:15], v14 offset:3168
	v_pk_mul_f32 v[0:1], v[16:17], v[0:1]
	s_waitcnt lgkmcnt(0)
	v_pk_mul_f32 v[16:17], v[14:15], v[14:15]
	s_nop 0
	v_add_f32_e32 v16, v16, v17
	s_nop 1
	v_add_f32_dpp v16, v16, v16 row_ror:8 row_mask:0xf bank_mask:0xf bound_ctrl:1
	s_nop 1
	v_add_f32_dpp v16, v16, v16 row_ror:4 row_mask:0xf bank_mask:0xf bound_ctrl:1
	s_nop 1
	v_add_f32_dpp v16, v16, v16 row_ror:2 row_mask:0xf bank_mask:0xf bound_ctrl:1
	s_nop 1
	v_add_f32_dpp v16, v16, v16 row_ror:1 row_mask:0xf bank_mask:0xf bound_ctrl:1
	s_nop 0
	v_readlane_b32 s5, v16, 16
	v_readlane_b32 s8, v16, 48
	v_readlane_b32 s6, v16, 0
	v_readlane_b32 s7, v16, 32
	v_mov_b32_e32 v16, s5
	v_mov_b32_e32 v17, s8
	v_pk_add_f32 v[16:17], s[6:7], v[16:17]
	s_mov_b64 s[6:7], s[62:63]
	v_mov_b32_e32 v20, v16
	v_mov_b32_e32 v12, v17
	v_pk_add_f32 v[12:13], v[20:21], v[12:13]
	s_nop 0
	v_pk_fma_f32 v[8:9], v[12:13], s[2:3], v[8:9] op_sel_hi:[1,0,0]
	s_mov_b64 s[2:3], 0x74c2800
	v_mul_f32_e32 v12, 0x4b800000, v9
	v_cmp_gt_f32_e64 s[8:9], s58, v9
	v_cmp_gt_f32_e32 vcc, s58, v8
	s_nop 0
	v_cndmask_b32_e64 v9, v9, v12, s[8:9]
	v_rsq_f32_e32 v9, v9
	s_nop 0
	v_mul_f32_e32 v12, 0x45800000, v9
	v_cndmask_b32_e64 v12, v9, v12, s[8:9]
	v_pk_mul_f32 v[2:3], v[2:3], v[12:13] op_sel_hi:[1,0]
	v_and_b32_e32 v9, 0xffff0000, v85
	v_pk_mul_f32 v[2:3], v[6:7], v[2:3]
	s_nop 0
	v_pk_mul_f32 v[0:1], v[0:1], v[2:3]
	v_add_u32_e32 v2, s0, v23
	v_cvt_pk_bf16_f32 v0, v0, v1
	global_store_dword v[10:11], v0, off
	v_mul_f32_e32 v0, 0x4b800000, v8
	v_cndmask_b32_e32 v0, v8, v0, vcc
	v_rsq_f32_e32 v0, v0
	v_lshlrev_b32_e32 v8, 16, v85
	v_ashrrev_i32_e32 v3, 31, v2
	s_mov_b32 s0, 0x7380000
	v_mul_f32_e32 v1, 0x45800000, v0
	v_cndmask_b32_e32 v0, v0, v1, vcc
	v_mul_f32_e32 v1, 0xbfb8aa3b, v8
	v_exp_f32_e32 v1, v1
	s_nop 0
	v_add_f32_e32 v1, 1.0, v1
	v_rcp_f32_e32 v10, v1
	v_pk_mul_f32 v[0:1], v[14:15], v[0:1] op_sel_hi:[1,0]
	s_nop 0
	v_pk_mul_f32 v[0:1], v[6:7], v[0:1]
	v_mul_f32_e32 v6, 0xbfb8aa3b, v9
	v_exp_f32_e32 v6, v6
	s_nop 0
	v_add_f32_e32 v6, 1.0, v6
	v_rcp_f32_e32 v11, v6
	s_nop 0
	v_pk_mul_f32 v[6:7], v[10:11], v[8:9]
	s_nop 0
	v_pk_mul_f32 v[0:1], v[6:7], v[0:1]
	s_nop 0
	v_cvt_pk_bf16_f32 v6, v0, v1
	v_lshlrev_b64 v[0:1], 10, v[2:3]
	v_lshl_add_u64 v[0:1], v[4:5], 0, v[0:1]
	global_store_dword v[0:1], v6, off
	s_barrier
	s_load_dwordx2 s[6:7], s[6:7], 0xc0
	v_mov_b32_e32 v4, v208
	s_nop 0
	v_lshlrev_b32_e32 v2, 1, v4
	v_and_b32_e32 v5, 0x7e, v2
	v_or_b32_e32 v166, s39, v5
	s_waitcnt lgkmcnt(0)
	v_mov_b32_e32 v0, s6
	v_mov_b32_e32 v1, s7
	v_lshl_add_u64 v[2:3], v[0:1], 0, s[2:3]
	v_lshl_add_u64 v[0:1], v[166:167], 2, v[0:1]
	v_add_co_u32_e32 v0, vcc, s0, v0
	v_readlane_b32 s0, v253, 23
	s_nop 0
	v_addc_co_u32_e32 v1, vcc, 0, v1, vcc
	global_load_dwordx2 v[16:17], v[0:1], off
	v_ashrrev_i32_e32 v0, 3, v4
	v_and_b32_e32 v0, -8, v0
	v_add_u32_e32 v4, s0, v0
	v_ashrrev_i32_e32 v12, 31, v4
	v_readlane_b32 s2, v254, 12
	v_alignbit_b32 v10, v12, v4, 8
	v_readlane_b32 s3, v254, 13
	v_readlane_b32 s0, v253, 24
	v_lshlrev_b32_e32 v4, 9, v4
	v_mad_u64_u32 v[0:1], s[6:7], v10, 49, s[2:3]
	v_readlane_b32 s2, v254, 28
	v_readlane_b32 s3, v254, 29
	v_mad_u32_u24 v1, v12, 49, v1
	v_or_b32_e32 v5, s0, v5
	v_mad_u64_u32 v[6:7], s[6:7], v10, 49, s[2:3]
	v_readlane_b32 s2, v254, 30
	v_readlane_b32 s3, v254, 31
	v_mad_u32_u24 v7, v12, 49, v7
	v_lshlrev_b64 v[0:1], 17, v[0:1]
	v_mad_u64_u32 v[8:9], s[6:7], v10, 49, s[2:3]
	v_readlane_b32 s2, v254, 14
	v_readlane_b32 s3, v254, 15
	v_lshlrev_b64 v[6:7], 17, v[6:7]
	v_mad_u32_u24 v9, v12, 49, v9
	v_mad_u64_u32 v[10:11], s[6:7], v10, 49, s[2:3]
	v_mad_u32_u24 v11, v12, 49, v11
	v_lshl_add_u64 v[0:1], v[2:3], 0, v[0:1]
	v_lshlrev_b32_e32 v166, 1, v5
	v_lshl_add_u64 v[6:7], v[2:3], 0, v[6:7]
	v_lshlrev_b64 v[8:9], 17, v[8:9]
	v_lshlrev_b64 v[10:11], 17, v[10:11]
	v_lshl_add_u64 v[0:1], v[0:1], 0, v[166:167]
	v_and_b32_e32 v4, 0x1f000, v4
	v_mov_b32_e32 v5, v167
	v_lshl_add_u64 v[6:7], v[6:7], 0, v[166:167]
	v_lshl_add_u64 v[8:9], v[2:3], 0, v[8:9]
	v_lshl_add_u64 v[2:3], v[2:3], 0, v[10:11]
	v_lshl_add_u64 v[0:1], v[0:1], 0, v[4:5]
	v_lshl_add_u64 v[6:7], v[6:7], 0, v[4:5]
	v_lshl_add_u64 v[8:9], v[8:9], 0, v[166:167]
	v_lshl_add_u64 v[2:3], v[2:3], 0, v[166:167]
	v_lshl_add_u64 v[8:9], v[8:9], 0, v[4:5]
	v_lshl_add_u64 v[2:3], v[2:3], 0, v[4:5]
	global_load_dword v88, v[0:1], off
	global_load_dword v84, v[6:7], off
	global_load_dword v40, v[8:9], off
	global_load_dword v77, v[2:3], off
	global_load_dword v78, v[0:1], off offset:512
	global_load_dword v53, v[6:7], off offset:512
	global_load_dword v33, v[8:9], off offset:512
	global_load_dword v69, v[2:3], off offset:512
	global_load_dword v73, v[0:1], off offset:1024
	global_load_dword v51, v[6:7], off offset:1024
	global_load_dword v32, v[8:9], off offset:1024
	global_load_dword v71, v[2:3], off offset:1024
	global_load_dword v70, v[0:1], off offset:1536
	global_load_dword v49, v[6:7], off offset:1536
	global_load_dword v31, v[8:9], off offset:1536
	global_load_dword v61, v[2:3], off offset:1536
	global_load_dword v66, v[0:1], off offset:2048
	global_load_dword v47, v[6:7], off offset:2048
	global_load_dword v30, v[8:9], off offset:2048
	global_load_dword v63, v[2:3], off offset:2048
	global_load_dword v62, v[0:1], off offset:2560
	global_load_dword v45, v[6:7], off offset:2560
	global_load_dword v29, v[8:9], off offset:2560
	global_load_dword v57, v[2:3], off offset:2560
	global_load_dword v60, v[0:1], off offset:3072
	global_load_dword v43, v[6:7], off offset:3072
	global_load_dword v28, v[8:9], off offset:3072
	global_load_dword v59, v[2:3], off offset:3072
	global_load_dword v58, v[0:1], off offset:3584
	global_load_dword v42, v[6:7], off offset:3584
	global_load_dword v26, v[8:9], off offset:3584
	global_load_dword v56, v[2:3], off offset:3584
	v_lshlrev_b32_e32 v1, 16, v93
	v_and_b32_e32 v6, 0xffff0000, v93
	v_mul_f32_e32 v2, 0xbfb8aa3b, v1
	v_mul_f32_e32 v3, 0xbfb8aa3b, v6
	v_exp_f32_e32 v2, v2
	v_exp_f32_e32 v3, v3
	v_pk_add_f32 v[4:5], v[18:19], 1.0 op_sel_hi:[1,0] neg_lo:[1,0] neg_hi:[1,0]
	v_mul_f32_e32 v1, 0x3fb8aa3b, v1
	v_add_f32_e32 v2, 1.0, v2
	v_add_f32_e32 v3, 1.0, v3
	v_rcp_f32_e32 v2, v2
	v_rcp_f32_e32 v3, v3
	s_mov_b64 s[6:7], s[62:63]
	v_exp_f32_e32 v1, v1
	v_fma_f32 v2, v4, v2, v18
	v_fma_f32 v3, v5, v3, v19
	v_log_f32_e32 v2, v2
	v_log_f32_e32 v3, v3
	global_load_dwordx2 v[22:23], v167, s[6:7] offset:136
	global_load_dwordx2 v[20:21], v167, s[6:7] offset:192
	v_add_f32_e32 v1, 1.0, v1
	v_and_b32_e32 v11, 63, v97
	v_ashrrev_i32_e32 v95, 6, v97
	v_lshl_add_u32 v10, v11, 3, 0
	v_lshl_add_u32 v15, v95, 12, v10
	ds_write_b64 v15, v[2:3]
	v_rcp_f32_e32 v2, v1
	v_mul_f32_e32 v1, 0x3fb8aa3b, v6
	v_exp_f32_e32 v1, v1
	v_readlane_b32 s2, v254, 45
	v_lshlrev_b32_e32 v14, 2, v11
	s_movk_i32 s0, 0x820
	v_add_f32_e32 v1, 1.0, v1
	v_rcp_f32_e32 v3, v1
	v_add_u32_e32 v0, s2, v14
	v_lshlrev_b32_e32 v94, 3, v95
	v_or_b32_e32 v72, 2, v94
	v_pk_mul_f32 v[6:7], v[4:5], v[2:3]
	v_mad_u64_u32 v[2:3], s[6:7], v95, s0, v[0:1]
	v_mul_f32_e32 v1, 0xbfb8aa3b, v111
	v_exp_f32_e32 v1, v1
	ds_write_b32 v2, v91
	v_or_b32_e32 v91, 1, v94
	s_movk_i32 s0, 0x104
	v_add_f32_e32 v1, 1.0, v1
	v_rcp_f32_e32 v1, v1
	v_or_b32_e32 v85, 3, v94
	v_or_b32_e32 v79, 4, v94
	v_lshlrev_b32_e32 v8, 16, v92
	v_fma_f32 v1, v4, v1, v18
	v_log_f32_e32 v2, v1
	v_lshlrev_b32_e32 v1, 9, v91
	v_add_u32_e32 v109, v10, v1
	v_mul_f32_e32 v1, 0xbfb8aa3b, v110
	v_exp_f32_e32 v1, v1
	v_and_b32_e32 v9, 0xffff0000, v92
	v_lshlrev_b32_e32 v92, 16, v68
	v_or_b32_e32 v68, 6, v94
	v_add_f32_e32 v1, 1.0, v1
	v_rcp_f32_e32 v1, v1
	v_lshlrev_b32_e32 v96, 1, v11
	v_cmp_gt_u32_e32 vcc, s83, v97
	v_fma_f32 v1, v5, v1, v19
	v_log_f32_e32 v3, v1
	v_mad_u64_u32 v[0:1], s[6:7], v91, s0, v[0:1]
	v_mul_f32_e32 v1, 0xbfb8aa3b, v108
	v_exp_f32_e32 v1, v1
	ds_write_b64 v109, v[2:3]
	s_movk_i32 s0, 0x900
	v_add_f32_e32 v1, 1.0, v1
	v_rcp_f32_e32 v1, v1
	s_nop 0
	v_fma_f32 v1, v4, v1, v18
	v_log_f32_e32 v2, v1
	v_lshlrev_b32_e32 v1, 9, v72
	v_add_u32_e32 v106, v10, v1
	v_mul_f32_e32 v1, 0xbfb8aa3b, v107
	v_exp_f32_e32 v1, v1
	s_nop 0
	v_add_f32_e32 v1, 1.0, v1
	v_rcp_f32_e32 v1, v1
	s_nop 0
	v_fma_f32 v1, v5, v1, v19
	v_log_f32_e32 v3, v1
	v_mul_f32_e32 v1, 0xbfb8aa3b, v102
	v_exp_f32_e32 v1, v1
	ds_write_b64 v106, v[2:3]
	ds_write2_b32 v0, v86, v87 offset1:65
	v_lshlrev_b32_e32 v87, 16, v67
	v_add_f32_e32 v1, 1.0, v1
	v_rcp_f32_e32 v1, v1
	v_and_b32_e32 v86, 0xffff0000, v67
	v_and_b32_e32 v67, 0xffff0000, v25
	v_fma_f32 v1, v4, v1, v18
	v_log_f32_e32 v2, v1
	v_lshlrev_b32_e32 v1, 9, v85
	v_add_u32_e32 v100, v10, v1
	v_mul_f32_e32 v1, 0xbfb8aa3b, v101
	v_exp_f32_e32 v1, v1
	s_nop 0
	v_add_f32_e32 v1, 1.0, v1
	v_rcp_f32_e32 v1, v1
	s_nop 0
	v_fma_f32 v1, v5, v1, v19
	v_log_f32_e32 v3, v1
	v_mul_f32_e32 v1, 0xbfb8aa3b, v99
	v_exp_f32_e32 v1, v1
	ds_write_b64 v100, v[2:3]
	v_add_f32_e32 v1, 1.0, v1
	v_rcp_f32_e32 v1, v1
	s_nop 0
	v_fma_f32 v1, v4, v1, v18
	v_log_f32_e32 v2, v1
	v_lshlrev_b32_e32 v1, 9, v79
	v_add_u32_e32 v93, v10, v1
	v_mul_f32_e32 v1, 0xbfb8aa3b, v98
	v_exp_f32_e32 v1, v1
	s_nop 0
	v_add_f32_e32 v1, 1.0, v1
	v_rcp_f32_e32 v1, v1
	s_nop 0
	v_fma_f32 v1, v5, v1, v19
	v_log_f32_e32 v3, v1
	v_mul_f32_e32 v1, 0xbfb8aa3b, v92
	v_exp_f32_e32 v1, v1
	ds_write_b64 v93, v[2:3]
	ds_write2_b32 v0, v74, v75 offset0:130 offset1:195
	v_or_b32_e32 v74, 5, v94
	v_add_f32_e32 v1, 1.0, v1
	v_rcp_f32_e32 v1, v1
	v_lshlrev_b32_e32 v75, 16, v25
	v_fma_f32 v1, v4, v1, v18
	v_log_f32_e32 v2, v1
	v_lshlrev_b32_e32 v1, 9, v74
	v_add_u32_e32 v89, v10, v1
	v_mul_f32_e32 v1, 0xbfb8aa3b, v90
	v_exp_f32_e32 v1, v1
	s_nop 0
	v_add_f32_e32 v1, 1.0, v1
	v_rcp_f32_e32 v1, v1
	s_nop 0
	v_fma_f32 v1, v5, v1, v19
	v_log_f32_e32 v3, v1
	v_mul_f32_e32 v1, 0xbfb8aa3b, v87
	v_exp_f32_e32 v1, v1
	ds_write_b64 v89, v[2:3]
	v_add_f32_e32 v1, 1.0, v1
	v_rcp_f32_e32 v1, v1
	s_nop 0
	v_fma_f32 v1, v4, v1, v18
	v_log_f32_e32 v2, v1
	v_lshlrev_b32_e32 v1, 9, v68
	v_add_u32_e32 v76, v10, v1
	v_mul_f32_e32 v1, 0xbfb8aa3b, v86
	v_exp_f32_e32 v1, v1
	s_nop 0
	v_add_f32_e32 v1, 1.0, v1
	v_rcp_f32_e32 v1, v1
	s_nop 0
	v_fma_f32 v1, v5, v1, v19
	v_log_f32_e32 v3, v1
	v_add_u32_e32 v1, 0x400, v0
	ds_write2_b32 v1, v64, v65 offset0:4 offset1:69
	v_mul_f32_e32 v1, 0xbfb8aa3b, v75
	v_exp_f32_e32 v1, v1
	v_or_b32_e32 v64, 7, v94
	ds_write_b64 v76, v[2:3]
	v_add_f32_e32 v1, 1.0, v1
	v_rcp_f32_e32 v1, v1
	s_nop 0
	v_fma_f32 v1, v4, v1, v18
	v_log_f32_e32 v2, v1
	v_lshlrev_b32_e32 v1, 9, v64
	v_add_u32_e32 v65, v10, v1
	v_mul_f32_e32 v1, 0xbfb8aa3b, v67
	v_exp_f32_e32 v1, v1
	s_nop 0
	v_add_f32_e32 v1, 1.0, v1
	v_rcp_f32_e32 v1, v1
	s_nop 0
	v_fmac_f32_e32 v19, v5, v1
	v_log_f32_e32 v3, v19
	ds_write_b64 v65, v[2:3]
	ds_write_b32 v0, v24 offset:1560
	v_ashrrev_i32_e32 v0, 31, v97
	v_lshrrev_b32_e32 v0, 26, v0
	v_add_u32_e32 v0, v97, v0
	v_ashrrev_i32_e32 v2, 6, v0
	v_mul_u32_u24_e32 v0, 0x41, v11
	v_lshlrev_b32_e32 v3, 5, v2
	v_lshlrev_b32_e32 v12, 2, v0
	v_add3_u32 v0, s2, v3, v12
	s_waitcnt lgkmcnt(0)
	s_barrier
	ds_read2_b32 v[0:1], v0 offset1:1
	v_mul_lo_u32 v13, v2, s0
	v_add3_u32 v18, s10, v13, v96
	s_movk_i32 s0, 0x120
	v_add_u32_e32 v103, s2, v12
	s_waitcnt lgkmcnt(0)
	ds_write_b16 v18, v0
	v_add_u32_e32 v18, s10, v96
	v_add_u32_e32 v13, v18, v13
	ds_write_b16_d16_hi v13, v0 offset:144
	v_lshl_or_b32 v0, v2, 3, 1
	v_mul_lo_u32 v0, v0, s0
	v_add3_u32 v2, s10, v0, v96
	v_add_u32_e32 v12, v18, v0
	v_add_u32_e32 v3, v103, v3
	ds_write_b16 v2, v1
	ds_write_b16_d16_hi v12, v1 offset:144
	ds_read2_b32 v[0:1], v3 offset0:2 offset1:3
	s_waitcnt lgkmcnt(0)
	ds_write_b16 v2, v0 offset:288
	ds_write_b16_d16_hi v12, v0 offset:432
	ds_write_b16 v2, v1 offset:576
	ds_write_b16_d16_hi v12, v1 offset:720
	ds_read2_b32 v[0:1], v3 offset0:4 offset1:5
	s_waitcnt lgkmcnt(0)
	ds_write_b16 v2, v0 offset:864
	ds_write_b16_d16_hi v12, v0 offset:1008
	ds_write_b16 v2, v1 offset:1152
	ds_write_b16_d16_hi v12, v1 offset:1296
	ds_read2_b32 v[0:1], v3 offset0:6 offset1:7
	s_waitcnt lgkmcnt(0)
	ds_write_b16 v2, v0 offset:1440
	ds_write_b16_d16_hi v12, v0 offset:1584
	ds_write_b16 v2, v1 offset:1728
	ds_write_b16_d16_hi v12, v1 offset:1872
	v_and_b32_e32 v0, 0x7f, v97
	v_lshlrev_b32_e32 v1, 6, v97
	v_lshlrev_b32_e32 v0, 2, v0
	v_and_b32_e32 v1, 0xffffe000, v1
	v_add3_u32 v2, 0, v0, v1
	ds_read2st64_b32 v[0:1], v2 offset1:2
	v_ashrrev_i32_e32 v18, 7, v97
	v_cmp_eq_u32_e64 s[10:11], 2, v18
	v_cmp_eq_u32_e64 s[8:9], 1, v18
	s_mov_b32 s0, 0x3db504f3
	s_waitcnt lgkmcnt(0)
	v_add_f32_e32 v0, 0, v0
	v_add_f32_e32 v3, v0, v1
	ds_write2st64_b32 v2, v0, v3 offset1:2
	ds_read2st64_b32 v[0:1], v2 offset0:4 offset1:6
	s_waitcnt lgkmcnt(0)
	v_add_f32_e32 v0, v3, v0
	v_add_f32_e32 v3, v0, v1
	ds_write2st64_b32 v2, v0, v3 offset0:4 offset1:6
	ds_read2st64_b32 v[0:1], v2 offset0:8 offset1:10
	s_waitcnt lgkmcnt(0)
	v_add_f32_e32 v0, v3, v0
	v_add_f32_e32 v3, v0, v1
	ds_write2st64_b32 v2, v0, v3 offset0:8 offset1:10
	ds_read2st64_b32 v[0:1], v2 offset0:12 offset1:14
	s_waitcnt lgkmcnt(0)
	v_add_f32_e32 v0, v3, v0
	v_add_f32_e32 v3, v0, v1
	ds_write2st64_b32 v2, v0, v3 offset0:12 offset1:14
	ds_read2st64_b32 v[0:1], v2 offset0:16 offset1:18
	s_waitcnt lgkmcnt(0)
	v_add_f32_e32 v0, v3, v0
	v_add_f32_e32 v3, v0, v1
	ds_write2st64_b32 v2, v0, v3 offset0:16 offset1:18
	ds_read2st64_b32 v[0:1], v2 offset0:20 offset1:22
	s_waitcnt lgkmcnt(0)
	v_add_f32_e32 v0, v3, v0
	v_add_f32_e32 v3, v0, v1
	ds_write2st64_b32 v2, v0, v3 offset0:20 offset1:22
	ds_read2st64_b32 v[0:1], v2 offset0:24 offset1:26
	s_waitcnt lgkmcnt(0)
	v_add_f32_e32 v0, v3, v0
	v_add_f32_e32 v3, v0, v1
	ds_write2st64_b32 v2, v0, v3 offset0:24 offset1:26
	ds_read2st64_b32 v[0:1], v2 offset0:28 offset1:30
	s_waitcnt lgkmcnt(0)
	v_add_f32_e32 v0, v3, v0
	v_add_f32_e32 v1, v0, v1
	ds_write2st64_b32 v2, v0, v1 offset0:28 offset1:30
	v_lshl_add_u32 v0, v97, 2, 0
	ds_write_b32 v0, v1 offset:32768
	s_waitcnt lgkmcnt(0)
	s_barrier
	ds_read2st64_b64 v[0:3], v10 offset0:64 offset1:65
	ds_read_b64 v[12:13], v10 offset:33792
	v_sub_u32_e32 v10, v10, v14
	ds_read_b64 v[14:15], v15
	s_waitcnt lgkmcnt(2)
	v_pk_add_f32 v[24:25], v[0:1], v[2:3]
	s_waitcnt lgkmcnt(1)
	v_pk_add_f32 v[12:13], v[24:25], v[12:13]
	s_waitcnt lgkmcnt(0)
	v_exp_f32_e32 v104, v14
	v_cndmask_b32_e64 v2, v12, v24, s[10:11]
	v_cndmask_b32_e64 v2, v2, v0, s[8:9]
	v_cndmask_b32_e64 v3, v2, 0, vcc
	v_cndmask_b32_e64 v2, v13, v25, s[10:11]
	v_cndmask_b32_e64 v2, v2, v1, s[8:9]
	v_cndmask_b32_e64 v19, v2, 0, vcc
	v_lshlrev_b32_e32 v2, 8, v11
	v_sub_u32_e32 v2, v103, v2
	v_mul_f32_e32 v103, 0xbfb8aa3b, v8
	v_exp_f32_e32 v103, v103
	v_exp_f32_e32 v105, v15
	v_cmp_gt_i32_e32 vcc, 1, v18
	v_add_f32_e32 v103, 1.0, v103
	v_rcp_f32_e32 v112, v103
	v_mul_f32_e32 v103, 0xbfb8aa3b, v9
	v_exp_f32_e32 v103, v103
	s_nop 0
	v_add_f32_e32 v103, 1.0, v103
	v_rcp_f32_e32 v113, v103
	s_nop 0
	v_pk_mul_f32 v[8:9], v[112:113], v[8:9]
	s_nop 0
	v_pk_mul_f32 v[8:9], v[8:9], s[0:1] op_sel_hi:[1,0]
	s_nop 0
	v_pk_mul_f32 v[104:105], v[8:9], v[104:105]
	s_nop 0
	v_cvt_pk_bf16_f32 v103, v104, v105
	v_mad_u64_u32 v[104:105], s[6:7], v95, s52, v[10:11]
	v_add_f32_e32 v105, v14, v3
	v_exp_f32_e32 v112, v105
	v_add_f32_e32 v105, v15, v19
	v_exp_f32_e32 v113, v105
	s_nop 0
	v_pk_mul_f32 v[8:9], v[8:9], v[112:113]
	s_nop 0
	v_cvt_pk_bf16_f32 v8, v8, v9
	ds_write2st64_b32 v104, v103, v8 offset0:136 offset1:204
	s_and_saveexec_b64 s[6:7], vcc
	s_cbranch_execz .LBB0_1449
	v_sub_f32_e64 v8, -v3, v14
	v_sub_f32_e64 v9, -v19, v15
	v_min_f32_e32 v8, 0x42c80000, v8
	v_min_f32_e32 v9, 0x42c80000, v9
	v_exp_f32_e32 v8, v8
	v_exp_f32_e32 v9, v9
	s_nop 0
	v_pk_mul_f32 v[8:9], v[6:7], v[8:9]
	s_nop 0
	v_cvt_pk_bf16_f32 v103, v8, v9
	v_mad_u64_u32 v[8:9], s[8:9], v95, s52, v[2:3]
	ds_write_b32 v8, v103

.LBB0_1515:
	s_or_b64 exec, exec, s[6:7]
	v_or_b32_e32 v5, v5, v7
	v_cmp_gt_i32_e64 s[8:9], v5, v24
	s_or_b64 s[6:7], vcc, s[8:9]
	s_nop 3
	v_cvt_pk_bf16_f32 v0, v0, s0
	v_lshlrev_b32_e32 v6, 1, v5
	v_readlane_b32 s0, v254, 47
	v_cndmask_b32_e64 v0, v0, 0, s[6:7]
	v_cmp_gt_i32_e64 s[8:9], v5, v19
	v_add3_u32 v7, s0, v15, v6
	ds_write_b16 v7, v0
	s_or_b64 s[6:7], vcc, s[8:9]
	v_cvt_pk_bf16_f32 v0, v1, s0
	v_cndmask_b32_e64 v0, v0, 0, s[6:7]
	v_add3_u32 v1, s0, v13, v6
	v_cmp_gt_i32_e64 s[8:9], v5, v14
	ds_write_b16 v1, v0
	s_or_b64 s[6:7], vcc, s[8:9]
	v_cvt_pk_bf16_f32 v0, v2, s0
	v_cndmask_b32_e64 v0, v0, 0, s[6:7]
	v_add3_u32 v1, s0, v11, v6
	v_cmp_gt_i32_e64 s[8:9], v5, v12
	ds_write_b16 v1, v0
	s_or_b64 s[6:7], vcc, s[8:9]
	v_cvt_pk_bf16_f32 v0, v3, s0
	v_cndmask_b32_e64 v0, v0, 0, s[6:7]
	v_add3_u32 v1, s0, v4, v6
	v_and_b32_e32 v44, 31, v97
	ds_write_b16 v1, v0
	v_lshlrev_b32_e32 v0, 5, v95
	v_and_b32_e32 v19, 32, v0
	v_mov_b32_e32 v0, s0
	s_movk_i32 s0, 0x1200
	v_mul_u32_u24_e32 v2, 0x48, v44
	v_lshrrev_b32_e32 v3, 1, v97
	v_mad_u32_u24 v0, v19, s94, v0
	v_mul_lo_u32 v1, v18, s0
	v_readlane_b32 s10, v254, 46
	v_lshlrev_b32_e32 v2, 1, v2
	v_and_b32_e32 v24, 16, v3
	v_add_u32_e32 v1, s10, v1
	v_add3_u32 v46, v0, v2, v24
	s_waitcnt lgkmcnt(0)
	s_barrier
	v_add3_u32 v48, v1, v2, v24
	ds_read_b128 v[0:3], v46
	ds_read_b128 v[98:101], v46 offset:32
	ds_read_b128 v[4:7], v48
	ds_read_b128 v[102:105], v48 offset:32
	s_waitcnt lgkmcnt(1)
	v_mfma_f32_32x32x16_bf16 v[0:15], v[0:3], v[4:7], 0
	s_movk_i32 s0, 0x2200
	v_mul_lo_u32 v18, v18, s0
	v_add_u32_e32 v18, 0, v18
	v_lshrrev_b32_e32 v25, 3, v97
	v_readlane_b32 s0, v253, 37
	s_lshl_b32 s96, s0, 1
	s_movk_i32 s0, 0x1080
	s_waitcnt lgkmcnt(0)
	v_mfma_f32_32x32x16_bf16 v[0:15], v[98:101], v[102:105], v[0:15]
	ds_read_b128 v[98:101], v46 offset:64
	ds_read_b128 v[102:105], v48 offset:64
	v_or_b32_e32 v166, s40, v96
	s_waitcnt lgkmcnt(0)
	v_mfma_f32_32x32x16_bf16 v[0:15], v[98:101], v[102:105], v[0:15]
	ds_read_b128 v[98:101], v46 offset:96
	ds_read_b128 v[102:105], v48 offset:96
	v_mul_u32_u24_e32 v48, 0x88, v44
	v_mad_u32_u24 v46, v19, s50, 0
	v_lshlrev_b32_e32 v48, 1, v48
	v_add3_u32 v46, v46, v48, v24
	v_add3_u32 v18, v18, v48, v24
	v_and_or_b32 v19, v25, 4, v19
	s_waitcnt lgkmcnt(0)
	v_mfma_f32_32x32x16_bf16 v[0:15], v[98:101], v[102:105], v[0:15]
	ds_read_b128 v[98:101], v46 offset:52224
	ds_read_b128 v[102:105], v46 offset:52256
	ds_read_b128 v[106:109], v18
	ds_read_b128 v[110:113], v18 offset:32
	v_lshlrev_b32_e32 v24, 2, v44
	v_mul_u32_u24_e32 v19, 0x210, v19
	s_waitcnt lgkmcnt(1)
	v_mfma_f32_32x32x16_bf16 v[0:15], v[98:101], v[106:109], v[0:15]
	v_lshlrev_b32_e32 v108, 16, v73
	v_and_b32_e32 v107, 0xffff0000, v73
	s_waitcnt lgkmcnt(0)
	v_mfma_f32_32x32x16_bf16 v[0:15], v[102:105], v[110:113], v[0:15]
	ds_read_b128 v[98:101], v46 offset:52288
	ds_read_b128 v[102:105], v18 offset:64
	v_lshlrev_b32_e32 v111, 16, v78
	v_and_b32_e32 v110, 0xffff0000, v78
	v_and_b32_e32 v78, 0xffff0000, v62
	s_waitcnt lgkmcnt(0)
	v_mfma_f32_32x32x16_bf16 v[0:15], v[98:101], v[102:105], v[0:15]
	ds_read_b128 v[98:101], v46 offset:52320
	ds_read_b128 v[102:105], v18 offset:96
	s_waitcnt lgkmcnt(0)
	v_mfma_f32_32x32x16_bf16 v[0:15], v[98:101], v[102:105], v[0:15]
	ds_read_b128 v[98:101], v46 offset:52352
	ds_read_b128 v[102:105], v18 offset:128
	s_waitcnt lgkmcnt(0)
	v_mfma_f32_32x32x16_bf16 v[0:15], v[98:101], v[102:105], v[0:15]
	ds_read_b128 v[98:101], v46 offset:52384
	ds_read_b128 v[102:105], v18 offset:160
	s_waitcnt lgkmcnt(0)
	v_mfma_f32_32x32x16_bf16 v[0:15], v[98:101], v[102:105], v[0:15]
	ds_read_b128 v[98:101], v46 offset:52416
	ds_read_b128 v[102:105], v18 offset:192
	s_waitcnt lgkmcnt(0)
	v_mfma_f32_32x32x16_bf16 v[0:15], v[98:101], v[102:105], v[0:15]
	ds_read_b128 v[98:101], v46 offset:52448
	ds_read_b128 v[102:105], v18 offset:224
	v_and_b32_e32 v18, 0xffffff80, v97
	v_add_u32_e32 v18, s2, v18
	v_add3_u32 v18, v18, v24, v19
	v_mov_b32_e32 v97, v208
	s_waitcnt lgkmcnt(0)
	v_mfma_f32_32x32x16_bf16 v[0:15], v[98:101], v[102:105], v[0:15]
	v_lshlrev_b32_e32 v103, 16, v70
	v_and_b32_e32 v102, 0xffff0000, v70
	v_lshlrev_b32_e32 v100, 16, v66
	v_and_b32_e32 v99, 0xffff0000, v66
	v_and_b32_e32 v66, 0xffff0000, v60
	s_nop 6
	ds_write2_b32 v18, v0, v1 offset1:132
	v_add_u32_e32 v0, 0x400, v18
	ds_write2_b32 v0, v2, v3 offset0:8 offset1:140
	v_add_u32_e32 v0, 0x1000, v18
	ds_write2_b32 v0, v4, v5 offset0:32 offset1:164
	v_add_u32_e32 v0, 0x1400, v18
	ds_write2_b32 v0, v6, v7 offset0:40 offset1:172
	v_add_u32_e32 v0, 0x2000, v18
	ds_write2_b32 v0, v8, v9 offset0:64 offset1:196
	v_add_u32_e32 v0, 0x2400, v18
	ds_write2_b32 v0, v10, v11 offset0:72 offset1:204
	v_add_u32_e32 v0, 0x3000, v18
	v_lshl_add_u32 v2, v96, 2, s2
	ds_write2_b32 v0, v12, v13 offset0:96 offset1:228
	v_add_u32_e32 v0, 0x3400, v18
	v_mad_u64_u32 v[6:7], s[6:7], v95, s0, v[2:3]
	ds_write2_b32 v0, v14, v15 offset0:104 offset1:236
	s_waitcnt lgkmcnt(0)
	s_barrier
	ds_read_b64 v[10:11], v6
	v_lshl_add_u64 v[0:1], v[166:167], 2, v[22:23]
	v_lshlrev_b32_e32 v14, 16, v41
	v_and_b32_e32 v15, 0xffff0000, v41
	v_lshl_add_u64 v[4:5], v[20:21], 0, s[96:97]
	s_waitcnt lgkmcnt(0)
	v_pk_mul_f32 v[6:7], v[10:11], v[10:11]
	v_lshlrev_b32_e32 v166, 1, v96
	v_add_f32_e32 v3, v6, v7
	v_readlane_b32 s0, v253, 19
	v_lshl_add_u64 v[4:5], v[4:5], 0, v[166:167]
	v_add_f32_dpp v3, v3, v3 row_ror:8 row_mask:0xf bank_mask:0xf bound_ctrl:1
	s_mov_b64 s[2:3], 0x22cc2800
	v_add_u32_e32 v12, s0, v94
	v_add_f32_dpp v3, v3, v3 row_ror:4 row_mask:0xf bank_mask:0xf bound_ctrl:1
	v_lshl_add_u64 v[4:5], v[4:5], 0, s[2:3]
	v_ashrrev_i32_e32 v13, 31, v12
	v_add_f32_dpp v3, v3, v3 row_ror:2 row_mask:0xf bank_mask:0xf bound_ctrl:1
	s_movk_i32 s2, 0x210
	s_nop 0
	v_add_f32_dpp v3, v3, v3 row_ror:1 row_mask:0xf bank_mask:0xf bound_ctrl:1
	s_nop 0
	v_readlane_b32 s5, v3, 16
	v_readlane_b32 s8, v3, 48
	v_readlane_b32 s6, v3, 0
	v_readlane_b32 s7, v3, 32
	v_mov_b32_e32 v6, s5
	v_mov_b32_e32 v7, s8
	v_pk_add_f32 v[8:9], s[6:7], v[6:7]
	global_load_dwordx2 v[6:7], v[0:1], off
	v_mul_f32_e32 v0, 0xbfb8aa3b, v14
	v_mul_f32_e32 v1, 0xbfb8aa3b, v15
	v_exp_f32_e32 v0, v0
	v_exp_f32_e32 v1, v1
	v_mov_b32_e32 v23, v8
	v_add_f32_e32 v0, 1.0, v0
	v_add_f32_e32 v1, 1.0, v1
	v_rcp_f32_e32 v0, v0
	v_rcp_f32_e32 v1, v1
	s_nop 0
	v_pk_mul_f32 v[18:19], v[0:1], v[14:15]
	v_lshlrev_b64 v[0:1], 10, v[12:13]
	v_mad_u64_u32 v[14:15], s[6:7], v91, s2, v[2:3]
	v_lshl_add_u64 v[12:13], v[4:5], 0, v[0:1]
	ds_read2_b64 v[0:3], v14 offset1:66
	s_mov_b32 s2, 0x358637bd
	s_waitcnt lgkmcnt(0)
	v_pk_mul_f32 v[20:21], v[0:1], v[0:1]
	s_nop 0
	v_add_f32_e32 v15, v20, v21
	s_nop 1
	v_add_f32_dpp v15, v15, v15 row_ror:8 row_mask:0xf bank_mask:0xf bound_ctrl:1
	s_nop 1
	v_add_f32_dpp v15, v15, v15 row_ror:4 row_mask:0xf bank_mask:0xf bound_ctrl:1
	s_nop 1
	v_add_f32_dpp v15, v15, v15 row_ror:2 row_mask:0xf bank_mask:0xf bound_ctrl:1
	s_nop 1
	v_add_f32_dpp v15, v15, v15 row_ror:1 row_mask:0xf bank_mask:0xf bound_ctrl:1
	s_nop 0
	v_readlane_b32 s5, v15, 16
	v_readlane_b32 s8, v15, 48
	v_readlane_b32 s6, v15, 0
	v_readlane_b32 s7, v15, 32
	v_mov_b32_e32 v20, s5
	v_mov_b32_e32 v21, s8
	v_pk_add_f32 v[20:21], s[6:7], v[20:21]
	s_nop 0
	v_mov_b32_e32 v22, v20
	v_mov_b32_e32 v8, v21
	v_pk_add_f32 v[20:21], v[22:23], v[8:9]
	v_mov_b64_e32 v[8:9], s[2:3]
	s_brev_b32 s2, 60
	v_pk_fma_f32 v[20:21], v[20:21], s[2:3], v[8:9] op_sel_hi:[1,0,0]
	s_nop 0
	v_mul_f32_e32 v15, 0x4b800000, v21
	v_cmp_gt_f32_e64 s[8:9], s58, v21
	v_cmp_gt_f32_e32 vcc, s58, v20
	s_nop 0
	v_cndmask_b32_e64 v15, v21, v15, s[8:9]
	v_rsq_f32_e32 v15, v15
	s_nop 0
	v_mul_f32_e32 v21, 0x45800000, v15
	v_cndmask_b32_e64 v22, v15, v21, s[8:9]
	v_pk_mul_f32 v[10:11], v[10:11], v[22:23] op_sel_hi:[1,0]
	s_waitcnt vmcnt(0)
	v_pk_mul_f32 v[10:11], v[6:7], v[10:11]
	s_nop 0
	v_pk_mul_f32 v[10:11], v[18:19], v[10:11]
	v_lshlrev_b32_e32 v18, 16, v39
	v_cvt_pk_bf16_f32 v10, v10, v11
	global_store_dword v[12:13], v10, off
	v_mul_f32_e32 v10, 0x4b800000, v20
	v_cndmask_b32_e32 v10, v20, v10, vcc
	v_rsq_f32_e32 v10, v10
	v_and_b32_e32 v19, 0xffff0000, v39
	v_add_u32_e32 v12, s0, v91
	v_ashrrev_i32_e32 v13, 31, v12
	v_mul_f32_e32 v11, 0x45800000, v10
	v_cndmask_b32_e32 v10, v10, v11, vcc
	v_mul_f32_e32 v11, 0xbfb8aa3b, v18
	v_exp_f32_e32 v11, v11
	s_nop 0
	v_add_f32_e32 v11, 1.0, v11
	v_pk_mul_f32 v[0:1], v[0:1], v[10:11] op_sel_hi:[1,0]
	v_mul_f32_e32 v10, 0xbfb8aa3b, v19
	v_exp_f32_e32 v10, v10
	v_rcp_f32_e32 v20, v11
	v_pk_mul_f32 v[0:1], v[6:7], v[0:1]
	v_add_f32_e32 v10, 1.0, v10
	v_rcp_f32_e32 v21, v10
	s_nop 0
	v_pk_mul_f32 v[10:11], v[20:21], v[18:19]
	s_nop 0
	v_pk_mul_f32 v[0:1], v[10:11], v[0:1]
	s_nop 0
	v_cvt_pk_bf16_f32 v10, v0, v1
	v_lshlrev_b64 v[0:1], 10, v[12:13]
	v_lshlrev_b32_e32 v12, 16, v38
	v_mul_f32_e32 v15, 0xbfb8aa3b, v12
	v_exp_f32_e32 v15, v15
	v_and_b32_e32 v13, 0xffff0000, v38
	v_lshl_add_u64 v[0:1], v[4:5], 0, v[0:1]
	global_store_dword v[0:1], v10, off
	v_add_f32_e32 v15, 1.0, v15
	v_rcp_f32_e32 v18, v15
	v_mul_f32_e32 v15, 0xbfb8aa3b, v13
	v_exp_f32_e32 v15, v15
	v_add_u32_e32 v10, s0, v72
	v_ashrrev_i32_e32 v11, 31, v10
	v_lshlrev_b64 v[10:11], 10, v[10:11]
	v_add_f32_e32 v15, 1.0, v15
	v_rcp_f32_e32 v19, v15
	v_lshl_add_u64 v[20:21], v[4:5], 0, v[10:11]
	v_pk_mul_f32 v[0:1], v[2:3], v[2:3]
	v_pk_mul_f32 v[18:19], v[18:19], v[12:13]
	ds_read2_b64 v[10:13], v14 offset0:132 offset1:198
	v_add_f32_e32 v0, v0, v1
	s_waitcnt lgkmcnt(0)
	v_pk_mul_f32 v[22:23], v[10:11], v[10:11]
	v_add_f32_dpp v0, v0, v0 row_ror:8 row_mask:0xf bank_mask:0xf bound_ctrl:1
	v_add_f32_e32 v15, v22, v23
	s_nop 0
	v_add_f32_dpp v0, v0, v0 row_ror:4 row_mask:0xf bank_mask:0xf bound_ctrl:1
	v_add_f32_dpp v15, v15, v15 row_ror:8 row_mask:0xf bank_mask:0xf bound_ctrl:1
	s_nop 0
	v_add_f32_dpp v0, v0, v0 row_ror:2 row_mask:0xf bank_mask:0xf bound_ctrl:1
	v_add_f32_dpp v15, v15, v15 row_ror:4 row_mask:0xf bank_mask:0xf bound_ctrl:1
	s_nop 0
	v_add_f32_dpp v0, v0, v0 row_ror:1 row_mask:0xf bank_mask:0xf bound_ctrl:1
	v_add_f32_dpp v15, v15, v15 row_ror:2 row_mask:0xf bank_mask:0xf bound_ctrl:1
	v_readlane_b32 s5, v0, 16
	v_readlane_b32 s8, v0, 48
	v_add_f32_dpp v15, v15, v15 row_ror:1 row_mask:0xf bank_mask:0xf bound_ctrl:1
	v_readlane_b32 s6, v0, 0
	v_readlane_b32 s7, v0, 32
	v_mov_b32_e32 v0, s5
	v_mov_b32_e32 v1, s8
	v_readlane_b32 s5, v15, 16
	v_readlane_b32 s8, v15, 48
	v_pk_add_f32 v[0:1], s[6:7], v[0:1]
	v_readlane_b32 s6, v15, 0
	v_readlane_b32 s7, v15, 32
	v_mov_b32_e32 v22, s5
	v_mov_b32_e32 v23, s8
	v_pk_add_f32 v[22:23], s[6:7], v[22:23]
	v_mov_b32_e32 v25, v0
	v_mov_b32_e32 v24, v22
	v_mov_b32_e32 v0, v23
	v_pk_add_f32 v[0:1], v[24:25], v[0:1]
	s_nop 0
	v_pk_fma_f32 v[0:1], v[0:1], s[2:3], v[8:9] op_sel_hi:[1,0,0]
	s_nop 0
	v_mul_f32_e32 v15, 0x4b800000, v1
	v_cmp_gt_f32_e64 s[8:9], s58, v1
	v_cmp_gt_f32_e32 vcc, s58, v0
	s_nop 0
	v_cndmask_b32_e64 v1, v1, v15, s[8:9]
	v_rsq_f32_e32 v1, v1
	s_nop 0
	v_mul_f32_e32 v15, 0x45800000, v1
	v_cndmask_b32_e64 v22, v1, v15, s[8:9]
	v_pk_mul_f32 v[2:3], v[2:3], v[22:23] op_sel_hi:[1,0]
	s_nop 0
	v_pk_mul_f32 v[2:3], v[6:7], v[2:3]
	s_nop 0
	v_pk_mul_f32 v[2:3], v[18:19], v[2:3]
	v_lshlrev_b32_e32 v18, 16, v37
	v_cvt_pk_bf16_f32 v1, v2, v3
	global_store_dword v[20:21], v1, off
	v_mul_f32_e32 v1, 0x4b800000, v0
	v_cndmask_b32_e32 v0, v0, v1, vcc
	v_rsq_f32_e32 v0, v0
	v_and_b32_e32 v19, 0xffff0000, v37
	v_add_u32_e32 v2, s0, v85
	v_ashrrev_i32_e32 v3, 31, v2
	v_mul_f32_e32 v1, 0x45800000, v0
	v_cndmask_b32_e32 v0, v0, v1, vcc
	v_mul_f32_e32 v1, 0xbfb8aa3b, v18
	v_exp_f32_e32 v1, v1
	s_nop 0
	v_add_f32_e32 v1, 1.0, v1
	v_rcp_f32_e32 v20, v1
	v_pk_mul_f32 v[0:1], v[10:11], v[0:1] op_sel_hi:[1,0]
	v_mul_f32_e32 v10, 0xbfb8aa3b, v19
	v_exp_f32_e32 v10, v10
	v_pk_mul_f32 v[0:1], v[6:7], v[0:1]
	v_add_f32_e32 v10, 1.0, v10
	v_rcp_f32_e32 v21, v10
	s_nop 0
	v_pk_mul_f32 v[10:11], v[20:21], v[18:19]
	s_nop 0
	v_pk_mul_f32 v[0:1], v[10:11], v[0:1]
	s_nop 0
	v_cvt_pk_bf16_f32 v10, v0, v1
	v_lshlrev_b64 v[0:1], 10, v[2:3]
	v_lshlrev_b32_e32 v2, 16, v36
	v_mul_f32_e32 v15, 0xbfb8aa3b, v2
	v_exp_f32_e32 v15, v15
	v_lshl_add_u64 v[0:1], v[4:5], 0, v[0:1]
	global_store_dword v[0:1], v10, off
	v_pk_mul_f32 v[0:1], v[12:13], v[12:13]
	v_and_b32_e32 v3, 0xffff0000, v36
	v_add_f32_e32 v0, v0, v1
	v_add_f32_e32 v15, 1.0, v15
	v_rcp_f32_e32 v18, v15
	v_add_f32_dpp v0, v0, v0 row_ror:8 row_mask:0xf bank_mask:0xf bound_ctrl:1
	v_mul_f32_e32 v15, 0xbfb8aa3b, v3
	v_exp_f32_e32 v15, v15
	v_add_f32_dpp v0, v0, v0 row_ror:4 row_mask:0xf bank_mask:0xf bound_ctrl:1
	v_add_f32_e32 v15, 1.0, v15
	s_nop 0
	v_add_f32_dpp v0, v0, v0 row_ror:2 row_mask:0xf bank_mask:0xf bound_ctrl:1
	v_rcp_f32_e32 v19, v15
	s_nop 0
	v_add_f32_dpp v0, v0, v0 row_ror:1 row_mask:0xf bank_mask:0xf bound_ctrl:1
	v_pk_mul_f32 v[18:19], v[18:19], v[2:3]
	v_readlane_b32 s5, v0, 16
	v_readlane_b32 s8, v0, 48
	v_readlane_b32 s6, v0, 0
	v_readlane_b32 s7, v0, 32
	v_mov_b32_e32 v0, s5
	v_mov_b32_e32 v1, s8
	v_pk_add_f32 v[10:11], s[6:7], v[0:1]
	v_add_u32_e32 v0, s0, v79
	v_ashrrev_i32_e32 v1, 31, v0
	v_lshlrev_b64 v[0:1], 10, v[0:1]
	v_lshl_add_u64 v[20:21], v[4:5], 0, v[0:1]
	v_add_u32_e32 v0, 0x800, v14
	ds_read2_b64 v[0:3], v0 offset0:8 offset1:74
	v_mov_b32_e32 v25, v10
	s_waitcnt lgkmcnt(0)
	v_pk_mul_f32 v[22:23], v[0:1], v[0:1]
	s_nop 0
	v_add_f32_e32 v15, v22, v23
	s_nop 1
	v_add_f32_dpp v15, v15, v15 row_ror:8 row_mask:0xf bank_mask:0xf bound_ctrl:1
	s_nop 1
	v_add_f32_dpp v15, v15, v15 row_ror:4 row_mask:0xf bank_mask:0xf bound_ctrl:1
	s_nop 1
	v_add_f32_dpp v15, v15, v15 row_ror:2 row_mask:0xf bank_mask:0xf bound_ctrl:1
	s_nop 1
	v_add_f32_dpp v15, v15, v15 row_ror:1 row_mask:0xf bank_mask:0xf bound_ctrl:1
	s_nop 0
	v_readlane_b32 s5, v15, 16
	v_readlane_b32 s8, v15, 48
	v_readlane_b32 s6, v15, 0
	v_readlane_b32 s7, v15, 32
	v_mov_b32_e32 v22, s5
	v_mov_b32_e32 v23, s8
	v_pk_add_f32 v[22:23], s[6:7], v[22:23]
	s_nop 0
	v_mov_b32_e32 v24, v22
	v_mov_b32_e32 v10, v23
	v_pk_add_f32 v[10:11], v[24:25], v[10:11]
	s_nop 0
	v_pk_fma_f32 v[10:11], v[10:11], s[2:3], v[8:9] op_sel_hi:[1,0,0]
	s_nop 0
	v_mul_f32_e32 v15, 0x4b800000, v11
	v_cmp_gt_f32_e64 s[8:9], s58, v11
	v_cmp_gt_f32_e32 vcc, s58, v10
	s_nop 0
	v_cndmask_b32_e64 v11, v11, v15, s[8:9]
	v_rsq_f32_e32 v11, v11
	s_nop 0
	v_mul_f32_e32 v15, 0x45800000, v11
	v_cndmask_b32_e64 v22, v11, v15, s[8:9]
	v_pk_mul_f32 v[12:13], v[12:13], v[22:23] op_sel_hi:[1,0]
	s_nop 0
	v_pk_mul_f32 v[12:13], v[6:7], v[12:13]
	s_nop 0
	v_pk_mul_f32 v[12:13], v[18:19], v[12:13]
	v_lshlrev_b32_e32 v18, 16, v35
	v_cvt_pk_bf16_f32 v11, v12, v13
	global_store_dword v[20:21], v11, off
	v_mul_f32_e32 v11, 0x4b800000, v10
	v_cndmask_b32_e32 v10, v10, v11, vcc
	v_rsq_f32_e32 v10, v10
	v_and_b32_e32 v19, 0xffff0000, v35
	v_add_u32_e32 v12, s0, v74
	v_ashrrev_i32_e32 v13, 31, v12
	v_mul_f32_e32 v11, 0x45800000, v10
	v_cndmask_b32_e32 v10, v10, v11, vcc
	v_mul_f32_e32 v11, 0xbfb8aa3b, v18
	v_exp_f32_e32 v11, v11
	s_nop 0
	v_add_f32_e32 v11, 1.0, v11
	v_pk_mul_f32 v[0:1], v[0:1], v[10:11] op_sel_hi:[1,0]
	v_mul_f32_e32 v10, 0xbfb8aa3b, v19
	v_exp_f32_e32 v10, v10
	v_rcp_f32_e32 v20, v11
	v_pk_mul_f32 v[0:1], v[6:7], v[0:1]
	v_add_f32_e32 v10, 1.0, v10
	v_rcp_f32_e32 v21, v10
	s_nop 0
	v_pk_mul_f32 v[10:11], v[20:21], v[18:19]
	s_nop 0
	v_pk_mul_f32 v[0:1], v[10:11], v[0:1]
	s_nop 0
	v_cvt_pk_bf16_f32 v10, v0, v1
	v_lshlrev_b64 v[0:1], 10, v[12:13]
	v_lshl_add_u64 v[0:1], v[4:5], 0, v[0:1]
	global_store_dword v[0:1], v10, off
	v_pk_mul_f32 v[0:1], v[2:3], v[2:3]
	v_add_u32_e32 v10, s0, v68
	v_add_f32_e32 v0, v0, v1
	v_ashrrev_i32_e32 v11, 31, v10
	v_lshlrev_b64 v[10:11], 10, v[10:11]
	v_add_f32_dpp v0, v0, v0 row_ror:8 row_mask:0xf bank_mask:0xf bound_ctrl:1
	v_lshl_add_u64 v[10:11], v[4:5], 0, v[10:11]
	s_nop 0
	v_add_f32_dpp v0, v0, v0 row_ror:4 row_mask:0xf bank_mask:0xf bound_ctrl:1
	s_nop 1
	v_add_f32_dpp v0, v0, v0 row_ror:2 row_mask:0xf bank_mask:0xf bound_ctrl:1
	s_nop 1
	v_add_f32_dpp v0, v0, v0 row_ror:1 row_mask:0xf bank_mask:0xf bound_ctrl:1
	s_nop 0
	v_readlane_b32 s5, v0, 16
	v_readlane_b32 s8, v0, 48
	v_readlane_b32 s6, v0, 0
	v_readlane_b32 s7, v0, 32
	v_mov_b32_e32 v0, s5
	v_mov_b32_e32 v1, s8
	v_pk_add_f32 v[12:13], s[6:7], v[0:1]
	v_lshlrev_b32_e32 v0, 16, v34
	v_mul_f32_e32 v15, 0xbfb8aa3b, v0
	v_exp_f32_e32 v15, v15
	v_and_b32_e32 v1, 0xffff0000, v34
	v_mov_b32_e32 v21, v12
	v_add_f32_e32 v15, 1.0, v15
	v_rcp_f32_e32 v18, v15
	v_mul_f32_e32 v15, 0xbfb8aa3b, v1
	v_exp_f32_e32 v15, v15
	s_nop 0
	v_add_f32_e32 v15, 1.0, v15
	v_rcp_f32_e32 v19, v15
	ds_read_b64 v[14:15], v14 offset:3168
	v_pk_mul_f32 v[0:1], v[18:19], v[0:1]
	s_waitcnt lgkmcnt(0)
	v_pk_mul_f32 v[18:19], v[14:15], v[14:15]
	s_nop 0
	v_add_f32_e32 v18, v18, v19
	s_nop 1
	v_add_f32_dpp v18, v18, v18 row_ror:8 row_mask:0xf bank_mask:0xf bound_ctrl:1
	s_nop 1
	v_add_f32_dpp v18, v18, v18 row_ror:4 row_mask:0xf bank_mask:0xf bound_ctrl:1
	s_nop 1
	v_add_f32_dpp v18, v18, v18 row_ror:2 row_mask:0xf bank_mask:0xf bound_ctrl:1
	s_nop 1
	v_add_f32_dpp v18, v18, v18 row_ror:1 row_mask:0xf bank_mask:0xf bound_ctrl:1
	s_nop 0
	v_readlane_b32 s5, v18, 16
	v_readlane_b32 s8, v18, 48
	v_readlane_b32 s6, v18, 0
	v_readlane_b32 s7, v18, 32
	v_mov_b32_e32 v18, s5
	v_mov_b32_e32 v19, s8
	v_pk_add_f32 v[18:19], s[6:7], v[18:19]
	s_mov_b64 s[6:7], s[62:63]
	v_mov_b32_e32 v20, v18
	v_mov_b32_e32 v12, v19
	v_pk_add_f32 v[12:13], v[20:21], v[12:13]
	s_nop 0
	v_pk_fma_f32 v[8:9], v[12:13], s[2:3], v[8:9] op_sel_hi:[1,0,0]
	s_mov_b64 s[2:3], 0x74c2800
	v_mul_f32_e32 v12, 0x4b800000, v9
	v_cmp_gt_f32_e64 s[8:9], s58, v9
	v_cmp_gt_f32_e32 vcc, s58, v8
	s_nop 0
	v_cndmask_b32_e64 v9, v9, v12, s[8:9]
	v_rsq_f32_e32 v9, v9
	s_nop 0
	v_mul_f32_e32 v12, 0x45800000, v9
	v_cndmask_b32_e64 v12, v9, v12, s[8:9]
	v_pk_mul_f32 v[2:3], v[2:3], v[12:13] op_sel_hi:[1,0]
	v_and_b32_e32 v9, 0xffff0000, v27
	v_pk_mul_f32 v[2:3], v[6:7], v[2:3]
	s_nop 0
	v_pk_mul_f32 v[0:1], v[0:1], v[2:3]
	v_add_u32_e32 v2, s0, v64
	v_cvt_pk_bf16_f32 v0, v0, v1
	global_store_dword v[10:11], v0, off
	v_mul_f32_e32 v0, 0x4b800000, v8
	v_cndmask_b32_e32 v0, v8, v0, vcc
	v_rsq_f32_e32 v0, v0
	v_lshlrev_b32_e32 v8, 16, v27
	v_ashrrev_i32_e32 v3, 31, v2
	s_mov_b32 s0, 0x7380000
	v_mul_f32_e32 v1, 0x45800000, v0
	v_cndmask_b32_e32 v0, v0, v1, vcc
	v_mul_f32_e32 v1, 0xbfb8aa3b, v8
	v_exp_f32_e32 v1, v1
	s_nop 0
	v_add_f32_e32 v1, 1.0, v1
	v_rcp_f32_e32 v10, v1
	v_pk_mul_f32 v[0:1], v[14:15], v[0:1] op_sel_hi:[1,0]
	s_nop 0
	v_pk_mul_f32 v[0:1], v[6:7], v[0:1]
	v_mul_f32_e32 v6, 0xbfb8aa3b, v9
	v_exp_f32_e32 v6, v6
	s_nop 0
	v_add_f32_e32 v6, 1.0, v6
	v_rcp_f32_e32 v11, v6
	s_nop 0
	v_pk_mul_f32 v[6:7], v[10:11], v[8:9]
	s_nop 0
	v_pk_mul_f32 v[0:1], v[6:7], v[0:1]
	s_nop 0
	v_cvt_pk_bf16_f32 v6, v0, v1
	v_lshlrev_b64 v[0:1], 10, v[2:3]
	v_lshl_add_u64 v[0:1], v[4:5], 0, v[0:1]
	global_store_dword v[0:1], v6, off
	s_barrier
	s_load_dwordx2 s[6:7], s[6:7], 0xc0
	v_mov_b32_e32 v4, v208
	s_nop 0
	v_lshlrev_b32_e32 v2, 1, v4
	v_and_b32_e32 v5, 0x7e, v2
	v_or_b32_e32 v166, s38, v5
	s_waitcnt lgkmcnt(0)
	v_mov_b32_e32 v0, s6
	v_mov_b32_e32 v1, s7
	v_lshl_add_u64 v[2:3], v[0:1], 0, s[2:3]
	v_lshl_add_u64 v[0:1], v[166:167], 2, v[0:1]
	v_add_co_u32_e32 v0, vcc, s0, v0
	v_readlane_b32 s0, v253, 28
	s_nop 0
	v_addc_co_u32_e32 v1, vcc, 0, v1, vcc
	global_load_dwordx2 v[18:19], v[0:1], off
	v_ashrrev_i32_e32 v0, 3, v4
	v_and_b32_e32 v0, -8, v0
	v_add_u32_e32 v4, s0, v0
	v_ashrrev_i32_e32 v12, 31, v4
	v_readlane_b32 s2, v254, 16
	v_alignbit_b32 v10, v12, v4, 8
	v_readlane_b32 s3, v254, 17
	v_readlane_b32 s0, v253, 29
	v_lshlrev_b32_e32 v4, 9, v4
	v_mad_u64_u32 v[0:1], s[6:7], v10, 49, s[2:3]
	v_readlane_b32 s2, v254, 32
	v_readlane_b32 s3, v254, 33
	v_mad_u32_u24 v1, v12, 49, v1
	v_or_b32_e32 v5, s0, v5
	v_mad_u64_u32 v[6:7], s[6:7], v10, 49, s[2:3]
	v_readlane_b32 s2, v254, 34
	v_readlane_b32 s3, v254, 35
	v_mad_u32_u24 v7, v12, 49, v7
	v_lshlrev_b64 v[0:1], 17, v[0:1]
	v_mad_u64_u32 v[8:9], s[6:7], v10, 49, s[2:3]
	v_readlane_b32 s2, v254, 18
	v_readlane_b32 s3, v254, 19
	v_lshlrev_b64 v[6:7], 17, v[6:7]
	v_mad_u32_u24 v9, v12, 49, v9
	v_mad_u64_u32 v[10:11], s[6:7], v10, 49, s[2:3]
	v_mad_u32_u24 v11, v12, 49, v11
	v_lshl_add_u64 v[0:1], v[2:3], 0, v[0:1]
	v_lshlrev_b32_e32 v166, 1, v5
	v_lshl_add_u64 v[6:7], v[2:3], 0, v[6:7]
	v_lshlrev_b64 v[8:9], 17, v[8:9]
	v_lshlrev_b64 v[10:11], 17, v[10:11]
	v_lshl_add_u64 v[0:1], v[0:1], 0, v[166:167]
	v_and_b32_e32 v4, 0x1f000, v4
	v_mov_b32_e32 v5, v167
	v_lshl_add_u64 v[6:7], v[6:7], 0, v[166:167]
	v_lshl_add_u64 v[8:9], v[2:3], 0, v[8:9]
	v_lshl_add_u64 v[2:3], v[2:3], 0, v[10:11]
	v_lshl_add_u64 v[0:1], v[0:1], 0, v[4:5]
	v_lshl_add_u64 v[6:7], v[6:7], 0, v[4:5]
	v_lshl_add_u64 v[8:9], v[8:9], 0, v[166:167]
	v_lshl_add_u64 v[2:3], v[2:3], 0, v[166:167]
	v_lshl_add_u64 v[8:9], v[8:9], 0, v[4:5]
	v_lshl_add_u64 v[2:3], v[2:3], 0, v[4:5]
	global_load_dword v93, v[0:1], off
	global_load_dword v92, v[6:7], off
	global_load_dword v41, v[8:9], off
	global_load_dword v90, v[2:3], off
	global_load_dword v91, v[0:1], off offset:512
	global_load_dword v55, v[6:7], off offset:512
	global_load_dword v39, v[8:9], off offset:512
	global_load_dword v85, v[2:3], off offset:512
	global_load_dword v89, v[0:1], off offset:1024
	global_load_dword v54, v[6:7], off offset:1024
	global_load_dword v38, v[8:9], off offset:1024
	global_load_dword v87, v[2:3], off offset:1024
	global_load_dword v86, v[0:1], off offset:1536
	global_load_dword v52, v[6:7], off offset:1536
	global_load_dword v37, v[8:9], off offset:1536
	global_load_dword v74, v[2:3], off offset:1536
	global_load_dword v79, v[0:1], off offset:2048
	global_load_dword v50, v[6:7], off offset:2048
	global_load_dword v36, v[8:9], off offset:2048
	global_load_dword v76, v[2:3], off offset:2048
	global_load_dword v75, v[0:1], off offset:2560
	global_load_dword v48, v[6:7], off offset:2560
	global_load_dword v35, v[8:9], off offset:2560
	global_load_dword v65, v[2:3], off offset:2560
	global_load_dword v72, v[0:1], off offset:3072
	global_load_dword v46, v[6:7], off offset:3072
	global_load_dword v34, v[8:9], off offset:3072
	global_load_dword v68, v[2:3], off offset:3072
	global_load_dword v67, v[0:1], off offset:3584
	global_load_dword v44, v[6:7], off offset:3584
	global_load_dword v27, v[8:9], off offset:3584
	global_load_dword v64, v[2:3], off offset:3584
	v_lshlrev_b32_e32 v1, 16, v88
	v_and_b32_e32 v6, 0xffff0000, v88
	v_mul_f32_e32 v2, 0xbfb8aa3b, v1
	v_mul_f32_e32 v3, 0xbfb8aa3b, v6
	v_exp_f32_e32 v2, v2
	v_exp_f32_e32 v3, v3
	v_pk_add_f32 v[4:5], v[16:17], 1.0 op_sel_hi:[1,0] neg_lo:[1,0] neg_hi:[1,0]
	v_mul_f32_e32 v1, 0x3fb8aa3b, v1
	v_add_f32_e32 v2, 1.0, v2
	v_add_f32_e32 v3, 1.0, v3
	v_rcp_f32_e32 v2, v2
	v_rcp_f32_e32 v3, v3
	s_mov_b64 s[6:7], s[62:63]
	v_exp_f32_e32 v1, v1
	v_fma_f32 v2, v4, v2, v16
	v_fma_f32 v3, v5, v3, v17
	v_log_f32_e32 v2, v2
	v_log_f32_e32 v3, v3
	global_load_dwordx2 v[22:23], v167, s[6:7] offset:136
	global_load_dwordx2 v[20:21], v167, s[6:7] offset:192
	v_add_f32_e32 v1, 1.0, v1
	v_and_b32_e32 v11, 63, v97
	v_ashrrev_i32_e32 v95, 6, v97
	v_lshl_add_u32 v10, v11, 3, 0
	v_lshl_add_u32 v15, v95, 12, v10
	ds_write_b64 v15, v[2:3]
	v_rcp_f32_e32 v2, v1
	v_mul_f32_e32 v1, 0x3fb8aa3b, v6
	v_exp_f32_e32 v1, v1
	v_readlane_b32 s2, v254, 45
	v_lshlrev_b32_e32 v14, 2, v11
	s_movk_i32 s0, 0x820
	v_add_f32_e32 v1, 1.0, v1
	v_rcp_f32_e32 v3, v1
	v_add_u32_e32 v0, s2, v14
	v_lshlrev_b32_e32 v94, 3, v95
	v_lshlrev_b32_e32 v8, 16, v84
	v_pk_mul_f32 v[6:7], v[4:5], v[2:3]
	v_mad_u64_u32 v[2:3], s[6:7], v95, s0, v[0:1]
	v_mul_f32_e32 v1, 0xbfb8aa3b, v111
	v_exp_f32_e32 v1, v1
	v_and_b32_e32 v9, 0xffff0000, v84
	v_or_b32_e32 v84, 1, v94
	ds_write_b32 v2, v77
	v_add_f32_e32 v1, 1.0, v1
	v_rcp_f32_e32 v1, v1
	s_movk_i32 s0, 0x104
	v_or_b32_e32 v77, 2, v94
	v_or_b32_e32 v70, 4, v94
	v_fma_f32 v1, v4, v1, v16
	v_log_f32_e32 v2, v1
	v_lshlrev_b32_e32 v1, 9, v84
	v_add_u32_e32 v109, v10, v1
	v_mul_f32_e32 v1, 0xbfb8aa3b, v110
	v_exp_f32_e32 v1, v1
	v_lshlrev_b32_e32 v88, 16, v62
	v_or_b32_e32 v62, 6, v94
	v_lshlrev_b32_e32 v96, 1, v11
	v_add_f32_e32 v1, 1.0, v1
	v_rcp_f32_e32 v1, v1
	v_cmp_gt_u32_e32 vcc, s83, v97
	v_fma_f32 v1, v5, v1, v17
	v_log_f32_e32 v3, v1
	v_mad_u64_u32 v[0:1], s[6:7], v84, s0, v[0:1]
	v_mul_f32_e32 v1, 0xbfb8aa3b, v108
	v_exp_f32_e32 v1, v1
	ds_write_b64 v109, v[2:3]
	s_movk_i32 s0, 0x900
	v_add_f32_e32 v1, 1.0, v1
	v_rcp_f32_e32 v1, v1
	s_nop 0
	v_fma_f32 v1, v4, v1, v16
	v_log_f32_e32 v2, v1
	v_lshlrev_b32_e32 v1, 9, v77
	v_add_u32_e32 v106, v10, v1
	v_mul_f32_e32 v1, 0xbfb8aa3b, v107
	v_exp_f32_e32 v1, v1
	s_nop 0
	v_add_f32_e32 v1, 1.0, v1
	v_rcp_f32_e32 v1, v1
	s_nop 0
	v_fma_f32 v1, v5, v1, v17
	v_log_f32_e32 v3, v1
	v_mul_f32_e32 v1, 0xbfb8aa3b, v103
	v_exp_f32_e32 v1, v1
	ds_write_b64 v106, v[2:3]
	ds_write2_b32 v0, v69, v71 offset1:65
	v_or_b32_e32 v69, 3, v94
	v_add_f32_e32 v1, 1.0, v1
	v_rcp_f32_e32 v1, v1
	v_lshlrev_b32_e32 v71, 16, v60
	v_lshlrev_b32_e32 v60, 16, v58
	v_fma_f32 v1, v4, v1, v16
	v_log_f32_e32 v2, v1
	v_lshlrev_b32_e32 v1, 9, v69
	v_add_u32_e32 v101, v10, v1
	v_mul_f32_e32 v1, 0xbfb8aa3b, v102
	v_exp_f32_e32 v1, v1
	s_nop 0
	v_add_f32_e32 v1, 1.0, v1
	v_rcp_f32_e32 v1, v1
	s_nop 0
	v_fma_f32 v1, v5, v1, v17
	v_log_f32_e32 v3, v1
	v_mul_f32_e32 v1, 0xbfb8aa3b, v100
	v_exp_f32_e32 v1, v1
	ds_write_b64 v101, v[2:3]
	v_add_f32_e32 v1, 1.0, v1
	v_rcp_f32_e32 v1, v1
	s_nop 0
	v_fma_f32 v1, v4, v1, v16
	v_log_f32_e32 v2, v1
	v_lshlrev_b32_e32 v1, 9, v70
	v_add_u32_e32 v98, v10, v1
	v_mul_f32_e32 v1, 0xbfb8aa3b, v99
	v_exp_f32_e32 v1, v1
	s_nop 0
	v_add_f32_e32 v1, 1.0, v1
	v_rcp_f32_e32 v1, v1
	s_nop 0
	v_fma_f32 v1, v5, v1, v17
	v_log_f32_e32 v3, v1
	v_mul_f32_e32 v1, 0xbfb8aa3b, v88
	v_exp_f32_e32 v1, v1
	ds_write_b64 v98, v[2:3]
	ds_write2_b32 v0, v61, v63 offset0:130 offset1:195
	v_or_b32_e32 v61, 5, v94
	v_add_f32_e32 v1, 1.0, v1
	v_rcp_f32_e32 v1, v1
	s_nop 0
	v_fma_f32 v1, v4, v1, v16
	v_log_f32_e32 v2, v1
	v_lshlrev_b32_e32 v1, 9, v61
	v_add_u32_e32 v73, v10, v1
	v_mul_f32_e32 v1, 0xbfb8aa3b, v78
	v_exp_f32_e32 v1, v1
	s_nop 0
	v_add_f32_e32 v1, 1.0, v1
	v_rcp_f32_e32 v1, v1
	s_nop 0
	v_fma_f32 v1, v5, v1, v17
	v_log_f32_e32 v3, v1
	v_mul_f32_e32 v1, 0xbfb8aa3b, v71
	v_exp_f32_e32 v1, v1
	ds_write_b64 v73, v[2:3]
	v_add_f32_e32 v1, 1.0, v1
	v_rcp_f32_e32 v1, v1
	s_nop 0
	v_fma_f32 v1, v4, v1, v16
	v_log_f32_e32 v2, v1
	v_lshlrev_b32_e32 v1, 9, v62
	v_add_u32_e32 v63, v10, v1
	v_mul_f32_e32 v1, 0xbfb8aa3b, v66
	v_exp_f32_e32 v1, v1
	s_nop 0
	v_add_f32_e32 v1, 1.0, v1
	v_rcp_f32_e32 v1, v1
	s_nop 0
	v_fma_f32 v1, v5, v1, v17
	v_log_f32_e32 v3, v1
	v_add_u32_e32 v1, 0x400, v0
	ds_write2_b32 v1, v57, v59 offset0:4 offset1:69
	v_mul_f32_e32 v1, 0xbfb8aa3b, v60
	v_exp_f32_e32 v1, v1
	v_or_b32_e32 v57, 7, v94
	ds_write_b64 v63, v[2:3]
	v_and_b32_e32 v59, 0xffff0000, v58
	v_add_f32_e32 v1, 1.0, v1
	v_rcp_f32_e32 v1, v1
	s_nop 0
	v_fma_f32 v1, v4, v1, v16
	v_log_f32_e32 v2, v1
	v_lshlrev_b32_e32 v1, 9, v57
	v_add_u32_e32 v58, v10, v1
	v_mul_f32_e32 v1, 0xbfb8aa3b, v59
	v_exp_f32_e32 v1, v1
	s_nop 0
	v_add_f32_e32 v1, 1.0, v1
	v_rcp_f32_e32 v1, v1
	s_nop 0
	v_fmac_f32_e32 v17, v5, v1
	v_log_f32_e32 v3, v17
	ds_write_b64 v58, v[2:3]
	ds_write_b32 v0, v56 offset:1560
	v_ashrrev_i32_e32 v0, 31, v97
	v_lshrrev_b32_e32 v0, 26, v0
	v_add_u32_e32 v0, v97, v0
	v_ashrrev_i32_e32 v2, 6, v0
	v_mul_u32_u24_e32 v0, 0x41, v11
	v_lshlrev_b32_e32 v3, 5, v2
	v_lshlrev_b32_e32 v12, 2, v0
	v_add3_u32 v0, s2, v3, v12
	s_waitcnt lgkmcnt(0)
	s_barrier
	ds_read2_b32 v[0:1], v0 offset1:1
	v_mul_lo_u32 v13, v2, s0
	v_add3_u32 v16, s10, v13, v96
	s_movk_i32 s0, 0x120
	v_add_u32_e32 v56, s2, v12
	s_waitcnt lgkmcnt(0)
	ds_write_b16 v16, v0
	v_add_u32_e32 v16, s10, v96
	v_add_u32_e32 v13, v16, v13
	ds_write_b16_d16_hi v13, v0 offset:144
	v_lshl_or_b32 v0, v2, 3, 1
	v_mul_lo_u32 v0, v0, s0
	v_add3_u32 v2, s10, v0, v96
	v_add_u32_e32 v12, v16, v0
	v_add_u32_e32 v3, v56, v3
	ds_write_b16 v2, v1
	ds_write_b16_d16_hi v12, v1 offset:144
	ds_read2_b32 v[0:1], v3 offset0:2 offset1:3
	s_waitcnt lgkmcnt(0)
	ds_write_b16 v2, v0 offset:288
	ds_write_b16_d16_hi v12, v0 offset:432
	ds_write_b16 v2, v1 offset:576
	ds_write_b16_d16_hi v12, v1 offset:720
	ds_read2_b32 v[0:1], v3 offset0:4 offset1:5
	s_waitcnt lgkmcnt(0)
	ds_write_b16 v2, v0 offset:864
	ds_write_b16_d16_hi v12, v0 offset:1008
	ds_write_b16 v2, v1 offset:1152
	ds_write_b16_d16_hi v12, v1 offset:1296
	ds_read2_b32 v[0:1], v3 offset0:6 offset1:7
	s_waitcnt lgkmcnt(0)
	ds_write_b16 v2, v0 offset:1440
	ds_write_b16_d16_hi v12, v0 offset:1584
	ds_write_b16 v2, v1 offset:1728
	ds_write_b16_d16_hi v12, v1 offset:1872
	v_and_b32_e32 v0, 0x7f, v97
	v_lshlrev_b32_e32 v1, 6, v97
	v_lshlrev_b32_e32 v0, 2, v0
	v_and_b32_e32 v1, 0xffffe000, v1
	v_add3_u32 v2, 0, v0, v1
	ds_read2st64_b32 v[0:1], v2 offset1:2
	v_ashrrev_i32_e32 v16, 7, v97
	v_cmp_eq_u32_e64 s[10:11], 2, v16
	v_cmp_eq_u32_e64 s[8:9], 1, v16
	s_mov_b32 s0, 0x3db504f3
	s_waitcnt lgkmcnt(0)
	v_add_f32_e32 v0, 0, v0
	v_add_f32_e32 v3, v0, v1
	ds_write2st64_b32 v2, v0, v3 offset1:2
	ds_read2st64_b32 v[0:1], v2 offset0:4 offset1:6
	s_waitcnt lgkmcnt(0)
	v_add_f32_e32 v0, v3, v0
	v_add_f32_e32 v3, v0, v1
	ds_write2st64_b32 v2, v0, v3 offset0:4 offset1:6
	ds_read2st64_b32 v[0:1], v2 offset0:8 offset1:10
	s_waitcnt lgkmcnt(0)
	v_add_f32_e32 v0, v3, v0
	v_add_f32_e32 v3, v0, v1
	ds_write2st64_b32 v2, v0, v3 offset0:8 offset1:10
	ds_read2st64_b32 v[0:1], v2 offset0:12 offset1:14
	s_waitcnt lgkmcnt(0)
	v_add_f32_e32 v0, v3, v0
	v_add_f32_e32 v3, v0, v1
	ds_write2st64_b32 v2, v0, v3 offset0:12 offset1:14
	ds_read2st64_b32 v[0:1], v2 offset0:16 offset1:18
	s_waitcnt lgkmcnt(0)
	v_add_f32_e32 v0, v3, v0
	v_add_f32_e32 v3, v0, v1
	ds_write2st64_b32 v2, v0, v3 offset0:16 offset1:18
	ds_read2st64_b32 v[0:1], v2 offset0:20 offset1:22
	s_waitcnt lgkmcnt(0)
	v_add_f32_e32 v0, v3, v0
	v_add_f32_e32 v3, v0, v1
	ds_write2st64_b32 v2, v0, v3 offset0:20 offset1:22
	ds_read2st64_b32 v[0:1], v2 offset0:24 offset1:26
	s_waitcnt lgkmcnt(0)
	v_add_f32_e32 v0, v3, v0
	v_add_f32_e32 v3, v0, v1
	ds_write2st64_b32 v2, v0, v3 offset0:24 offset1:26
	ds_read2st64_b32 v[0:1], v2 offset0:28 offset1:30
	s_waitcnt lgkmcnt(0)
	v_add_f32_e32 v0, v3, v0
	v_add_f32_e32 v1, v0, v1
	ds_write2st64_b32 v2, v0, v1 offset0:28 offset1:30
	v_lshl_add_u32 v0, v97, 2, 0
	ds_write_b32 v0, v1 offset:32768
	s_waitcnt lgkmcnt(0)
	s_barrier
	ds_read2st64_b64 v[0:3], v10 offset0:64 offset1:65
	ds_read_b64 v[12:13], v10 offset:33792
	v_sub_u32_e32 v10, v10, v14
	ds_read_b64 v[14:15], v15
	s_waitcnt lgkmcnt(2)
	v_pk_add_f32 v[24:25], v[0:1], v[2:3]
	s_waitcnt lgkmcnt(1)
	v_pk_add_f32 v[12:13], v[24:25], v[12:13]
	s_waitcnt lgkmcnt(0)
	v_exp_f32_e32 v104, v14
	v_cndmask_b32_e64 v2, v12, v24, s[10:11]
	v_cndmask_b32_e64 v2, v2, v0, s[8:9]
	v_cndmask_b32_e64 v3, v2, 0, vcc
	v_cndmask_b32_e64 v2, v13, v25, s[10:11]
	v_cndmask_b32_e64 v2, v2, v1, s[8:9]
	v_cndmask_b32_e64 v17, v2, 0, vcc
	v_lshlrev_b32_e32 v2, 8, v11
	v_sub_u32_e32 v2, v56, v2
	v_mul_f32_e32 v56, 0xbfb8aa3b, v8
	v_exp_f32_e32 v56, v56
	v_exp_f32_e32 v105, v15
	v_cmp_gt_i32_e32 vcc, 1, v16
	v_add_f32_e32 v56, 1.0, v56
	v_rcp_f32_e32 v112, v56
	v_mul_f32_e32 v56, 0xbfb8aa3b, v9
	v_exp_f32_e32 v56, v56
	s_nop 0
	v_add_f32_e32 v56, 1.0, v56
	v_rcp_f32_e32 v113, v56
	s_nop 0
	v_pk_mul_f32 v[8:9], v[112:113], v[8:9]
	s_nop 0
	v_pk_mul_f32 v[8:9], v[8:9], s[0:1] op_sel_hi:[1,0]
	s_nop 0
	v_pk_mul_f32 v[104:105], v[8:9], v[104:105]
	s_nop 0
	v_cvt_pk_bf16_f32 v56, v104, v105
	v_mad_u64_u32 v[104:105], s[6:7], v95, s52, v[10:11]
	v_add_f32_e32 v105, v14, v3
	v_exp_f32_e32 v112, v105
	v_add_f32_e32 v105, v15, v17
	v_exp_f32_e32 v113, v105
	s_nop 0
	v_pk_mul_f32 v[8:9], v[8:9], v[112:113]
	s_nop 0
	v_cvt_pk_bf16_f32 v8, v8, v9
	ds_write2st64_b32 v104, v56, v8 offset0:136 offset1:204
	s_and_saveexec_b64 s[6:7], vcc
	s_cbranch_execz .LBB0_1517
	v_sub_f32_e64 v8, -v3, v14
	v_sub_f32_e64 v9, -v17, v15
	v_min_f32_e32 v8, 0x42c80000, v8
	v_min_f32_e32 v9, 0x42c80000, v9
	v_exp_f32_e32 v8, v8
	v_exp_f32_e32 v9, v9
	s_nop 0
	v_pk_mul_f32 v[8:9], v[6:7], v[8:9]
	s_nop 0
	v_cvt_pk_bf16_f32 v56, v8, v9
	v_mad_u64_u32 v[8:9], s[8:9], v95, s52, v[2:3]
	ds_write_b32 v8, v56

.LBB0_1683:
	s_or_b64 exec, exec, s[6:7]
	s_mov_b64 s[8:9], s[62:63]
	s_getreg_b32 s5, hwreg(HW_REG_XCC_ID, 0, 4)
	s_waitcnt vmcnt(0)
	v_readlane_b32 s2, v253, 0
	v_readlane_b32 s3, v253, 1
	s_barrier
	s_and_saveexec_b64 s[6:7], s[2:3]
	s_xor_b64 s[6:7], exec, s[6:7]
	s_cbranch_execz .LBB0_1737
	s_load_dwordx2 s[8:9], s[8:9], 0xc0
	v_readlane_b32 s0, v254, 38
	s_waitcnt expcnt(0) lgkmcnt(0)
	v_mov_b32_e32 v4, s8
	v_mov_b32_e32 v5, s9
	s_and_b32 s5, s5, 15
	v_mov_b32_e32 v0, s0
	ds_read_b32 v2, v0
	v_readlane_b32 s0, v254, 39
	s_waitcnt lgkmcnt(0)
	v_cmp_ne_u32_e32 vcc, 0, v2
	v_mov_b32_e32 v0, s0
	ds_read_b32 v0, v0
	v_readfirstlane_b32 s8, v4
	v_readfirstlane_b32 s9, v5
	s_cbranch_vccnz .LBB0_1700
	s_add_u32 s10, s8, 0x2e4c2a00
	s_addc_u32 s11, s9, 0
	s_add_u32 s12, s8, 0x2e4c2c00
	s_addc_u32 s13, s9, 0
	s_add_u32 s14, s8, 0x2e4c2d00
	s_addc_u32 s15, s9, 0
	s_add_u32 s16, s8, 0x2e4c2e00
	s_addc_u32 s17, s9, 0
	s_add_u32 s18, s8, 0x2e4c2f00
	s_addc_u32 s19, s9, 0
	s_add_u32 s20, s8, 0x2e4c3000
	s_addc_u32 s21, s9, 0
	s_add_u32 s22, s8, 0x2e4c3100
	s_addc_u32 s23, s9, 0
	s_add_u32 s24, s8, 0x2e4c3200
	s_addc_u32 s25, s9, 0
	s_add_u32 s26, s8, 0x2e4c3300
	s_addc_u32 s27, s9, 0
	s_add_u32 s28, s8, 0x2e4c3400
	s_addc_u32 s29, s9, 0
	s_add_u32 s30, s8, 0x2e4c3500
	s_addc_u32 s31, s9, 0
	s_add_u32 s34, s8, 0x2e4c3600
	s_addc_u32 s35, s9, 0
	s_add_u32 s36, s8, 0x2e4c3700
	s_addc_u32 s37, s9, 0
	s_add_u32 s38, s8, 0x2e4c3800
	s_addc_u32 s39, s9, 0
	s_add_u32 s40, s8, 0x2e4c3900
	s_addc_u32 s41, s9, 0
	s_add_u32 s42, s8, 0x2e4c3a00
	s_addc_u32 s43, s9, 0
	s_add_u32 s44, s8, 0x2e4c3b00
	s_addc_u32 s45, s9, 0
	s_mov_b32 s52, 1
	s_branch .LBB0_1688

.LBB0_1737:
	s_or_b64 exec, exec, s[6:7]
	s_mov_b64 s[6:7], s[62:63]
	s_waitcnt lgkmcnt(0)
	s_barrier
	s_load_dwordx2 s[14:15], s[6:7], 0xc0
	s_mov_b64 s[6:7], s[62:63]
	s_mov_b64 s[2:3], 0x244c2800
	s_mul_i32 s96, s83, 0x240000
	s_mov_b64 s[8:9], 0x3100000
	s_mov_b64 s[10:11], s[62:63]
	s_mov_b64 s[12:13], s[62:63]
	v_mov_b32_e32 v16, v208
	s_waitcnt lgkmcnt(0)
	v_mov_b32_e32 v0, s14
	v_mov_b32_e32 v1, s15
	v_lshl_add_u64 v[176:177], v[0:1], 0, s[2:3]
	global_load_dwordx2 v[0:1], v167, s[6:7] offset:192
	s_mov_b64 s[6:7], s[62:63]
	global_load_dwordx2 v[2:3], v167, s[6:7] offset:192
	s_mov_b64 s[2:3], 0x1fcc2800
	s_lshl_b64 s[6:7], s[96:97], 1
	s_waitcnt vmcnt(1)
	v_lshl_add_u64 v[0:1], v[0:1], 0, s[2:3]
	v_readlane_b32 s2, v253, 7
	v_readlane_b32 s3, v253, 8
	s_waitcnt vmcnt(0)
	v_lshl_add_u64 v[2:3], v[2:3], 0, s[6:7]
	v_lshl_add_u64 v[2:3], v[2:3], 0, s[8:9]
	v_readfirstlane_b32 s5, v1
	v_readfirstlane_b32 s28, v0
	v_readfirstlane_b32 s29, v16
	s_movk_i32 s8, 0x200
	v_readfirstlane_b32 s30, v3
	v_readfirstlane_b32 s31, v2
	s_and_b64 vcc, exec, s[2:3]
	s_cbranch_vccz .LBB0_1793
	v_lshlrev_b32_e32 v4, 4, v16
	v_add_u32_e32 v5, 0x2000, v4
	v_ashrrev_i32_e32 v6, 31, v5
	v_lshrrev_b32_e32 v6, 22, v6
	v_add_u32_e32 v6, v5, v6
	v_ashrrev_i32_e32 v6, 10, v6
	v_mul_i32_i24_e32 v7, 0x400, v6
	v_sub_u32_e32 v5, v5, v7
	v_lshrrev_b32_e32 v7, 4, v5
	v_bitop3_b32 v5, v7, v5, 32 bitop3:0x6c
	v_ashrrev_i32_e32 v7, 31, v5
	v_lshrrev_b32_e32 v7, 26, v7
	v_add_u32_e32 v7, v5, v7
	v_lshlrev_b32_e32 v9, 3, v6
	v_ashrrev_i32_e32 v8, 6, v7
	v_and_b32_e32 v9, -16, v9
	v_add_u32_e32 v9, v8, v9
	v_and_b32_e32 v8, 3, v8
	s_mov_b32 s0, 0x7fffffe0
	v_lshrrev_b32_e32 v10, 2, v9
	v_lshlrev_b32_e32 v11, 1, v9
	v_lshlrev_b32_e32 v6, 5, v6
	v_and_or_b32 v8, v9, s0, v8
	v_and_b32_e32 v10, 4, v10
	v_and_b32_e32 v11, 24, v11
	v_and_b32_e32 v17, 32, v6
	v_and_b32_e32 v6, 0xc0, v7
	v_or3_b32 v8, v8, v10, v11
	v_sub_u32_e32 v5, v5, v6
	v_mov_b32_e32 v11, 1
	v_ashrrev_i16_sdwa v5, v11, sext(v5) dst_sel:DWORD dst_unused:UNUSED_PAD src0_sel:DWORD src1_sel:BYTE_0
	v_bfe_i32 v18, v5, 0, 16
	v_mul_lo_u32 v8, v8, s8
	v_add_u32_e32 v5, v17, v18
	v_mul_lo_u32 v19, v9, s8
	v_add_lshl_u32 v178, v8, v5, 1
	v_add_lshl_u32 v180, v5, v19, 1
	v_bfe_i32 v5, v16, 27, 1
	v_lshrrev_b32_e32 v5, 22, v5
	v_add_u32_e32 v5, v4, v5
	v_and_b32_e32 v5, 0xfffffc00, v5
	v_sub_u32_e32 v4, v4, v5
	v_ashrrev_i32_e32 v6, 31, v16
	v_lshrrev_b32_e32 v5, 4, v4
	v_lshrrev_b32_e32 v6, 26, v6
	v_bitop3_b32 v5, v5, v4, 32 bitop3:0x6c
	v_ashrrev_i32_e32 v4, 31, v4
	v_add_u32_e32 v6, v16, v6
	v_lshrrev_b32_e32 v4, 26, v4
	v_ashrrev_i32_e32 v6, 6, v6
	v_add_u32_e32 v4, v5, v4
	v_lshlrev_b32_e32 v7, 3, v6
	v_ashrrev_i32_e32 v4, 6, v4
	v_and_b32_e32 v7, -16, v7
	s_ashr_i32 s9, s8, 31
	v_add_u32_e32 v7, v4, v7
	v_and_b32_e32 v8, 3, v4
	global_load_dwordx2 v[0:1], v167, s[10:11] offset:192
	global_load_dwordx2 v[2:3], v167, s[12:13] offset:192
	s_lshl_b64 s[12:13], s[8:9], 9
	v_and_or_b32 v8, v7, s0, v8
	v_readlane_b32 s0, v253, 46
	v_readlane_b32 s2, v253, 47
	s_mul_i32 s16, s12, s0
	s_mul_hi_u32 s17, s12, s70
	v_readlane_b32 s3, v253, 48
	v_mul_i32_i24_e32 v4, 64, v4
	s_add_i32 s18, s17, s16
	s_lshr_b64 s[16:17], s[8:9], 23
	s_mul_i32 s19, s12, s3
	s_mul_hi_u32 s20, s12, s2
	s_ashr_i32 s14, s29, 6
	v_lshrrev_b32_e32 v9, 2, v7
	v_lshlrev_b32_e32 v10, 1, v7
	v_sub_u32_e32 v4, v5, v4
	s_mul_i32 s17, s16, s70
	s_add_i32 s19, s20, s19
	s_mul_i32 s16, s16, s2
	s_ashr_i32 s15, s29, 8
	s_lshl_b64 s[10:11], s[8:9], 8
	s_lshl_b32 s34, s14, 10
	v_and_b32_e32 v9, 4, v9
	v_and_b32_e32 v10, 24, v10
	v_lshlrev_b32_e32 v6, 5, v6
	v_ashrrev_i16_sdwa v4, v11, sext(v4) dst_sel:DWORD dst_unused:UNUSED_PAD src0_sel:DWORD src1_sel:BYTE_0
	s_add_i32 s18, s18, s17
	s_add_i32 s19, s19, s16
	s_mul_i32 s16, s12, s2
	v_or3_b32 v8, v8, v9, v10
	v_and_b32_e32 v20, 32, v6
	v_bfe_i32 v21, v4, 0, 16
	s_add_u32 s24, s31, s16
	v_mul_lo_u32 v8, v8, s8
	v_add_u32_e32 v4, v20, v21
	s_addc_u32 s25, s30, s19
	s_add_i32 s35, s34, 0
	v_add_lshl_u32 v182, v8, v4, 1
	s_add_i32 m0, s35, 0x10000
	s_mul_i32 s17, s12, s70
	global_load_lds_dwordx4 v182, s[24:25]
	s_add_i32 m0, s35, 0x12000
	v_mul_lo_u32 v22, v7, s8
	s_add_u32 s26, s28, s17
	v_add_lshl_u32 v184, v4, v22, 1
	global_load_lds_dwordx4 v178, s[24:25]
	s_addc_u32 s27, s5, s18
	s_mov_b32 m0, s35
	s_add_i32 s36, s35, 0x2000
	global_load_lds_dwordx4 v184, s[26:27]
	s_mov_b32 m0, s36
	s_add_u32 s16, s24, s10
	global_load_lds_dwordx4 v180, s[26:27]
	s_addc_u32 s17, s25, s11
	s_add_i32 m0, s35, 0x14000
	v_mov_b32_e32 v183, v167
	v_mov_b32_e32 v179, v167
	global_load_lds_dwordx4 v182, s[16:17]
	s_add_i32 m0, s35, 0x16000
	v_lshl_add_u64 v[12:13], s[16:17], 0, v[182:183]
	v_lshl_add_u64 v[14:15], s[16:17], 0, v[178:179]
	global_load_lds_dwordx4 v178, s[16:17]
	s_add_u32 s16, s26, s10
	s_addc_u32 s17, s27, s11
	s_add_i32 s37, s35, 0x4000
	s_mov_b32 m0, s37
	s_add_i32 s38, s35, 0x6000
	global_load_lds_dwordx4 v184, s[16:17]
	s_mov_b32 m0, s38
	v_mov_b32_e32 v185, v167
	global_load_lds_dwordx4 v180, s[16:17]
	v_mov_b32_e32 v181, v167
	v_lshl_add_u64 v[4:5], s[24:25], 0, v[182:183]
	v_lshl_add_u64 v[6:7], s[24:25], 0, v[178:179]
	v_lshl_add_u64 v[8:9], s[26:27], 0, v[184:185]
	v_lshl_add_u64 v[10:11], s[26:27], 0, v[180:181]
	s_cmp_lg_u32 s15, 1
	s_cbranch_scc1 .LBB0_1740
	s_barrier

.LBB0_1815:
	s_mov_b64 s[8:9], s[62:63]
	s_getreg_b32 s5, hwreg(HW_REG_XCC_ID, 0, 4)
	s_waitcnt vmcnt(0)
	v_readlane_b32 s2, v253, 0
	v_readlane_b32 s3, v253, 1
	s_waitcnt lgkmcnt(0)
	s_barrier
	s_and_saveexec_b64 s[6:7], s[2:3]
	s_xor_b64 s[6:7], exec, s[6:7]
	s_cbranch_execz .LBB0_1869
	s_load_dwordx2 s[8:9], s[8:9], 0xc0
	v_readlane_b32 s0, v254, 38
	s_waitcnt expcnt(0) lgkmcnt(0)
	v_mov_b32_e32 v4, s8
	v_mov_b32_e32 v5, s9
	s_and_b32 s5, s5, 15
	v_mov_b32_e32 v0, s0
	ds_read_b32 v2, v0
	v_readlane_b32 s0, v254, 39
	s_waitcnt lgkmcnt(0)
	v_cmp_ne_u32_e32 vcc, 0, v2
	v_mov_b32_e32 v0, s0
	ds_read_b32 v0, v0
	v_readfirstlane_b32 s8, v4
	v_readfirstlane_b32 s9, v5
	s_cbranch_vccnz .LBB0_1832
	s_add_u32 s10, s8, 0x2e4c2a00
	s_addc_u32 s11, s9, 0
	s_add_u32 s12, s8, 0x2e4c2c00
	s_addc_u32 s13, s9, 0
	s_add_u32 s14, s8, 0x2e4c2d00
	s_addc_u32 s15, s9, 0
	s_add_u32 s16, s8, 0x2e4c2e00
	s_addc_u32 s17, s9, 0
	s_add_u32 s18, s8, 0x2e4c2f00
	s_addc_u32 s19, s9, 0
	s_add_u32 s20, s8, 0x2e4c3000
	s_addc_u32 s21, s9, 0
	s_add_u32 s22, s8, 0x2e4c3100
	s_addc_u32 s23, s9, 0
	s_add_u32 s24, s8, 0x2e4c3200
	s_addc_u32 s25, s9, 0
	s_add_u32 s26, s8, 0x2e4c3300
	s_addc_u32 s27, s9, 0
	s_add_u32 s28, s8, 0x2e4c3400
	s_addc_u32 s29, s9, 0
	s_add_u32 s30, s8, 0x2e4c3500
	s_addc_u32 s31, s9, 0
	s_add_u32 s34, s8, 0x2e4c3600
	s_addc_u32 s35, s9, 0
	s_add_u32 s36, s8, 0x2e4c3700
	s_addc_u32 s37, s9, 0
	s_add_u32 s38, s8, 0x2e4c3800
	s_addc_u32 s39, s9, 0
	s_add_u32 s40, s8, 0x2e4c3900
	s_addc_u32 s41, s9, 0
	s_add_u32 s42, s8, 0x2e4c3a00
	s_addc_u32 s43, s9, 0
	s_add_u32 s44, s8, 0x2e4c3b00
	s_addc_u32 s45, s9, 0
	s_mov_b32 s52, 1
	s_branch .LBB0_1820

.LBB0_1892:
	s_load_dwordx2 s[8:9], s[8:9], 0xc0
	v_readlane_b32 s0, v254, 38
	s_waitcnt expcnt(0) lgkmcnt(0)
	v_mov_b32_e32 v4, s8
	v_mov_b32_e32 v5, s9
	s_and_b32 s5, s5, 15
	v_mov_b32_e32 v0, s0
	ds_read_b32 v2, v0
	v_readlane_b32 s0, v254, 39
	s_waitcnt lgkmcnt(0)
	v_cmp_ne_u32_e32 vcc, 0, v2
	v_mov_b32_e32 v0, s0
	ds_read_b32 v0, v0
	v_readfirstlane_b32 s8, v4
	v_readfirstlane_b32 s9, v5
	s_cbranch_vccnz .LBB0_1908
	s_add_u32 s10, s8, 0x2e4c2a00
	s_addc_u32 s11, s9, 0
	s_add_u32 s12, s8, 0x2e4c2c00
	s_addc_u32 s13, s9, 0
	s_add_u32 s14, s8, 0x2e4c2d00
	s_addc_u32 s15, s9, 0
	s_add_u32 s16, s8, 0x2e4c2e00
	s_addc_u32 s17, s9, 0
	s_add_u32 s18, s8, 0x2e4c2f00
	s_addc_u32 s19, s9, 0
	s_add_u32 s20, s8, 0x2e4c3000
	s_addc_u32 s21, s9, 0
	s_add_u32 s22, s8, 0x2e4c3100
	s_addc_u32 s23, s9, 0
	s_add_u32 s24, s8, 0x2e4c3200
	s_addc_u32 s25, s9, 0
	s_add_u32 s26, s8, 0x2e4c3300
	s_addc_u32 s27, s9, 0
	s_add_u32 s28, s8, 0x2e4c3400
	s_addc_u32 s29, s9, 0
	s_add_u32 s30, s8, 0x2e4c3500
	s_addc_u32 s31, s9, 0
	s_add_u32 s34, s8, 0x2e4c3600
	s_addc_u32 s35, s9, 0
	s_add_u32 s36, s8, 0x2e4c3700
	s_addc_u32 s37, s9, 0
	s_add_u32 s38, s8, 0x2e4c3800
	s_addc_u32 s39, s9, 0
	s_add_u32 s40, s8, 0x2e4c3900
	s_addc_u32 s41, s9, 0
	s_add_u32 s42, s8, 0x2e4c3a00
	s_addc_u32 s43, s9, 0
	s_add_u32 s44, s8, 0x2e4c3b00
	s_addc_u32 s45, s9, 0
	s_mov_b32 s52, 1
	s_branch .LBB0_1896
